# s_setprio 0 hoisted above the last MFMA of each block so the post-MMA s_barrier directly follows the MFMA
# speedup vs baseline: 1.0016x; 1.0016x over previous
; #define PG8_STAGE(bufoff, gbase, voff) do { _Pragma("unroll") for (int _i = 0; _i < 2; ++_i) \
;         __builtin_amdgcn_global_load_lds((const unsigned*)((const char*)(gbase) + (voff)[_i]), (PG8_LAS unsigned*)(lds + (bufoff) + ldsw + _i * 8192), 16, 0, 0); } while (0)
; #define PG8_LDA(dst, b, h) do { _Pragma("unroll") for (int m = 0; m < 4; ++m) _Pragma("unroll") for (int k = 0; k < 2; ++k) dst[m][k] = *(const PG8_LAS bf16x8*)(lds + PG8_SA(b, h) + aoff + m * 2048 + k * 1024); } while (0)
; #define PG8_LDB(dst, b, h) do { _Pragma("unroll") for (int n = 0; n < 2; ++n) _Pragma("unroll") for (int k = 0; k < 2; ++k) dst[n][k] = *(const PG8_LAS bf16x8*)(lds + PG8_SB(b, h) + boff + n * 2048 + k * 1024); } while (0)
; #define PG8_MMA(ai, bj, At, Bt) do { __builtin_amdgcn_s_setprio(1); _Pragma("unroll") for (int m = 0; m < 4; ++m) _Pragma("unroll") for (int n = 0; n < 2; ++n) _Pragma("unroll") for (int k = 0; k < 2; ++k) \
;         acc[ai][bj][m][n] = __builtin_amdgcn_mfma_f32_16x16x32_bf16(Bt[n][k], At[m][k], acc[ai][bj][m][n], 0, 0, 0); __builtin_amdgcn_s_setprio(0); } while (0)
; #define PG8_WAIT_L(n) asm volatile("s_waitcnt lgkmcnt(" #n ")" ::: "memory")
; #define PG8_BAR __builtin_amdgcn_s_barrier()
; #define PG8_SCHED __builtin_amdgcn_sched_barrier(0)
; template <class Epi, class Sched, bool ALIGN_EPI = false, bool SP2 = false>
; __device__ __forceinline__ void gemm_phase(PG8_LAS unsigned char* lds, const Gemm g, const Sched& S, const Epi& E) {
;     ...
;             PG8_LDB(B0, 0, 0); PG8_LDB(B1, 0, 1); PG8_SCHED; PG8_LDA(At, 0, 0); PG8_STAGE(PG8_SA(1, 1), a1 + hstep, voffA);
;             asm volatile("s_cmp_lg_u32 %0, 0\n\ts_cbranch_scc1 .Lrelax%=\n\ts_waitcnt vmcnt(8)\n.Lrelax%=:\n\ts_waitcnt vmcnt(%1)" :: "s"(relax), "n"(8 + Epi::NST) : "memory", "scc");
;             PG8_WAIT_L(0); PG8_BAR; PG8_MMA(0, 0, At, B0); PG8_MMA(0, 1, At, B1); PG8_BAR; PG8_SCHED;
;             PG8_LDA(At, 0, 1); PG8_STAGE(PG8_SB(0, 0), b2, voffB); PG8_STAGE(PG8_SB(0, 1), b2 + hstep, voffB); PG8_STAGE(PG8_SA(0, 0), a2, voffA);
;             asm volatile("s_cmp_lg_u32 %0, 0\n\ts_cbranch_scc1 .Lrelax%=\n\ts_waitcnt vmcnt(8)\n.Lrelax%=:\n\ts_waitcnt vmcnt(%1)" :: "s"(relax), "n"(8 + Epi::NST) : "memory", "scc");
;             PG8_WAIT_L(0); PG8_BAR; PG8_MMA(1, 0, At, B0); PG8_MMA(1, 1, At, B1); PG8_BAR; PG8_SCHED;
.Lmy_qkvp_rx1:
	s_waitcnt vmcnt(24)
	s_waitcnt lgkmcnt(0)
	s_setprio 1
	s_barrier
	v_mfma_f32_16x16x32_bf16 v[124:127], v[132:135], v[198:201], 0
	v_mfma_f32_16x16x32_bf16 v[120:123], v[164:167], v[198:201], 0
	v_mfma_f32_16x16x32_bf16 v[112:115], v[132:135], v[206:209], 0
	v_mfma_f32_16x16x32_bf16 v[104:107], v[164:167], v[206:209], 0
	v_mfma_f32_16x16x32_bf16 v[96:99], v[132:135], v[214:217], 0
	v_mfma_f32_16x16x32_bf16 v[88:91], v[164:167], v[214:217], 0
	v_mfma_f32_16x16x32_bf16 v[80:83], v[132:135], v[238:241], 0
	v_mfma_f32_16x16x32_bf16 v[72:75], v[164:167], v[238:241], 0
	v_mfma_f32_16x16x32_bf16 v[124:127], v[150:153], v[202:205], v[124:127]
	v_mfma_f32_16x16x32_bf16 v[120:123], v[168:171], v[202:205], v[120:123]
	v_mfma_f32_16x16x32_bf16 v[112:115], v[150:153], v[210:213], v[112:115]
	v_mfma_f32_16x16x32_bf16 v[104:107], v[168:171], v[210:213], v[104:107]
	v_mfma_f32_16x16x32_bf16 v[96:99], v[150:153], v[234:237], v[96:99]
	v_mfma_f32_16x16x32_bf16 v[88:91], v[168:171], v[234:237], v[88:91]
	v_mfma_f32_16x16x32_bf16 v[80:83], v[150:153], v[242:245], v[80:83]
	v_mfma_f32_16x16x32_bf16 v[72:75], v[168:171], v[242:245], v[72:75]
	s_setprio 0
	s_setprio 1
	v_mfma_f32_16x16x32_bf16 v[116:119], v[172:175], v[198:201], 0
	v_mfma_f32_16x16x32_bf16 v[108:111], v[190:193], v[198:201], 0
	v_mfma_f32_16x16x32_bf16 v[100:103], v[172:175], v[206:209], 0
	v_mfma_f32_16x16x32_bf16 v[92:95], v[190:193], v[206:209], 0
	v_mfma_f32_16x16x32_bf16 v[84:87], v[172:175], v[214:217], 0
	v_mfma_f32_16x16x32_bf16 v[76:79], v[190:193], v[214:217], 0
	v_mfma_f32_16x16x32_bf16 v[68:71], v[172:175], v[238:241], 0
	v_mfma_f32_16x16x32_bf16 v[64:67], v[190:193], v[238:241], 0
	v_mfma_f32_16x16x32_bf16 v[116:119], v[186:189], v[202:205], v[116:119]
	v_mfma_f32_16x16x32_bf16 v[108:111], v[194:197], v[202:205], v[108:111]
	v_mfma_f32_16x16x32_bf16 v[100:103], v[186:189], v[210:213], v[100:103]
	v_mfma_f32_16x16x32_bf16 v[92:95], v[194:197], v[210:213], v[92:95]
	v_mfma_f32_16x16x32_bf16 v[84:87], v[186:189], v[234:237], v[84:87]
	v_mfma_f32_16x16x32_bf16 v[76:79], v[194:197], v[234:237], v[76:79]
	v_mfma_f32_16x16x32_bf16 v[68:71], v[186:189], v[242:245], v[68:71]
	s_setprio 0
	v_mfma_f32_16x16x32_bf16 v[64:67], v[194:197], v[242:245], v[64:67]
	s_barrier
	s_add_i32 m0, s2, 0x10000
	ds_read_b128 v[198:201], v163 offset:16384
	ds_read_b128 v[202:205], v163 offset:17408
	ds_read_b128 v[206:209], v163 offset:18432
	ds_read_b128 v[210:213], v163 offset:19456
	ds_read_b128 v[214:217], v163 offset:20480
	ds_read_b128 v[234:237], v163 offset:21504
	ds_read_b128 v[238:241], v163 offset:22528
	ds_read_b128 v[242:245], v163 offset:23552
	global_load_lds_dwordx4 v138, s[4:5]
	s_add_i32 m0, s2, 0x12000
	s_add_u32 s72, s4, 0x40000
	s_addc_u32 s73, s5, 0
	global_load_lds_dwordx4 v142, s[4:5]
	s_add_i32 m0, s2, 0x14000
	s_nop 0
	global_load_lds_dwordx4 v138, s[72:73]
	s_add_i32 m0, s2, 0x16000
	s_nop 0
	global_load_lds_dwordx4 v142, s[72:73]
	s_mov_b32 m0, s37
	s_nop 0
	global_load_lds_dwordx4 v136, s[34:35]
	s_mov_b32 m0, s57
	s_nop 0
	global_load_lds_dwordx4 v140, s[34:35]
	s_cmp_lg_u32 s30, 0
	s_cbranch_scc1 .Lmy_qkvp_rx2
	s_waitcnt vmcnt(8)
.Lmy_qkvp_rx2:
	s_waitcnt vmcnt(24)
	s_waitcnt lgkmcnt(0)
	s_setprio 1
	s_barrier
	v_mfma_f32_16x16x32_bf16 v[60:63], v[132:135], v[198:201], 0
	v_mfma_f32_16x16x32_bf16 v[56:59], v[164:167], v[198:201], 0
	v_mfma_f32_16x16x32_bf16 v[48:51], v[132:135], v[206:209], 0
	v_mfma_f32_16x16x32_bf16 v[40:43], v[164:167], v[206:209], 0
	v_mfma_f32_16x16x32_bf16 v[32:35], v[132:135], v[214:217], 0
	v_mfma_f32_16x16x32_bf16 v[24:27], v[164:167], v[214:217], 0
	v_mfma_f32_16x16x32_bf16 v[16:19], v[132:135], v[238:241], 0
	v_mfma_f32_16x16x32_bf16 v[8:11], v[164:167], v[238:241], 0
	v_mfma_f32_16x16x32_bf16 v[60:63], v[150:153], v[202:205], v[60:63]
	v_mfma_f32_16x16x32_bf16 v[56:59], v[168:171], v[202:205], v[56:59]
	v_mfma_f32_16x16x32_bf16 v[48:51], v[150:153], v[210:213], v[48:51]
	v_mfma_f32_16x16x32_bf16 v[40:43], v[168:171], v[210:213], v[40:43]
	v_mfma_f32_16x16x32_bf16 v[32:35], v[150:153], v[234:237], v[32:35]
	v_mfma_f32_16x16x32_bf16 v[24:27], v[168:171], v[234:237], v[24:27]
	v_mfma_f32_16x16x32_bf16 v[16:19], v[150:153], v[242:245], v[16:19]
	v_mfma_f32_16x16x32_bf16 v[8:11], v[168:171], v[242:245], v[8:11]
	s_setprio 0
	s_setprio 1
	v_mfma_f32_16x16x32_bf16 v[52:55], v[172:175], v[198:201], 0
	v_mfma_f32_16x16x32_bf16 v[44:47], v[190:193], v[198:201], 0
	v_mfma_f32_16x16x32_bf16 v[36:39], v[172:175], v[206:209], 0
	v_mfma_f32_16x16x32_bf16 v[28:31], v[190:193], v[206:209], 0
	v_mfma_f32_16x16x32_bf16 v[20:23], v[172:175], v[214:217], 0
	v_mfma_f32_16x16x32_bf16 v[12:15], v[190:193], v[214:217], 0
	v_mfma_f32_16x16x32_bf16 v[4:7], v[172:175], v[238:241], 0
	v_mfma_f32_16x16x32_bf16 v[0:3], v[190:193], v[238:241], 0
	v_mfma_f32_16x16x32_bf16 v[52:55], v[186:189], v[202:205], v[52:55]
	v_mfma_f32_16x16x32_bf16 v[44:47], v[194:197], v[202:205], v[44:47]
	v_mfma_f32_16x16x32_bf16 v[36:39], v[186:189], v[210:213], v[36:39]
	v_mfma_f32_16x16x32_bf16 v[28:31], v[194:197], v[210:213], v[28:31]
	v_mfma_f32_16x16x32_bf16 v[20:23], v[186:189], v[234:237], v[20:23]
	v_mfma_f32_16x16x32_bf16 v[12:15], v[194:197], v[234:237], v[12:15]
	v_mfma_f32_16x16x32_bf16 v[4:7], v[186:189], v[242:245], v[4:7]
	s_setprio 0
	v_mfma_f32_16x16x32_bf16 v[0:3], v[194:197], v[242:245], v[0:3]
	s_barrier
; #define PG8_STAGE(bufoff, gbase, voff) do { _Pragma("unroll") for (int _i = 0; _i < 2; ++_i) \
;         __builtin_amdgcn_global_load_lds((const unsigned*)((const char*)(gbase) + (voff)[_i]), (PG8_LAS unsigned*)(lds + (bufoff) + ldsw + _i * 8192), 16, 0, 0); } while (0)
; #define PG8_LDA(dst, b, h) do { _Pragma("unroll") for (int m = 0; m < 4; ++m) _Pragma("unroll") for (int k = 0; k < 2; ++k) dst[m][k] = *(const PG8_LAS bf16x8*)(lds + PG8_SA(b, h) + aoff + m * 2048 + k * 1024); } while (0)
; #define PG8_LDB(dst, b, h) do { _Pragma("unroll") for (int n = 0; n < 2; ++n) _Pragma("unroll") for (int k = 0; k < 2; ++k) dst[n][k] = *(const PG8_LAS bf16x8*)(lds + PG8_SB(b, h) + boff + n * 2048 + k * 1024); } while (0)
; #define PG8_MMA(ai, bj, At, Bt) do { __builtin_amdgcn_s_setprio(1); _Pragma("unroll") for (int m = 0; m < 4; ++m) _Pragma("unroll") for (int n = 0; n < 2; ++n) _Pragma("unroll") for (int k = 0; k < 2; ++k) \
;         acc[ai][bj][m][n] = __builtin_amdgcn_mfma_f32_16x16x32_bf16(Bt[n][k], At[m][k], acc[ai][bj][m][n], 0, 0, 0); __builtin_amdgcn_s_setprio(0); } while (0)
; #define PG8_WAIT_V(n) asm volatile("s_waitcnt vmcnt(" #n ")" ::: "memory")
; #define PG8_WAIT_L(n) asm volatile("s_waitcnt lgkmcnt(" #n ")" ::: "memory")
; #define PG8_BAR __builtin_amdgcn_s_barrier()
; #define PG8_SCHED __builtin_amdgcn_sched_barrier(0)
; template <class Epi, class Sched, bool ALIGN_EPI = false, bool SP2 = false>
; __device__ __forceinline__ void gemm_phase(PG8_LAS unsigned char* lds, const Gemm g, const Sched& S, const Epi& E) {
;     ...
;             PG8_LDB(B0, 1, 0); PG8_LDB(B1, 1, 1); PG8_SCHED; PG8_LDA(At, 1, 0); PG8_STAGE(PG8_SA(0, 1), a2 + hstep, voffA);
;             PG8_WAIT_V(8); PG8_WAIT_L(0); PG8_BAR; PG8_MMA(0, 0, At, B0); PG8_MMA(0, 1, At, B1); PG8_BAR; PG8_SCHED;
;             PG8_LDA(At, 1, 1); PG8_STAGE(PG8_SB(1, 0), b3, voffB); PG8_STAGE(PG8_SB(1, 1), b3 + hstep, voffB); PG8_STAGE(PG8_SA(1, 0), a3, voffA);
;             PG8_WAIT_V(8); PG8_WAIT_L(0); PG8_BAR; PG8_MMA(1, 0, At, B0); PG8_MMA(1, 1, At, B1); PG8_BAR; PG8_SCHED;
	ds_read_b128 v[132:135], v154 offset:32768
	ds_read_b128 v[150:153], v154 offset:33792
	ds_read_b128 v[164:167], v154 offset:34816
	ds_read_b128 v[168:171], v154 offset:35840
	ds_read_b128 v[172:175], v154 offset:49152
	ds_read_b128 v[186:189], v154 offset:50176
	ds_read_b128 v[190:193], v154 offset:51200
	ds_read_b128 v[194:197], v154 offset:52224
	s_add_u32 s34, s34, 0x40000
	s_addc_u32 s35, s35, 0
	s_mov_b32 m0, s58
	ds_read_b128 v[198:201], v163 offset:32768
	ds_read_b128 v[202:205], v163 offset:33792
	ds_read_b128 v[206:209], v163 offset:34816
	ds_read_b128 v[210:213], v163 offset:35840
	ds_read_b128 v[214:217], v163 offset:36864
	ds_read_b128 v[234:237], v163 offset:37888
	ds_read_b128 v[238:241], v163 offset:38912
	ds_read_b128 v[242:245], v163 offset:39936
	global_load_lds_dwordx4 v136, s[34:35]
	s_mov_b32 m0, s59
	s_nop 0
	global_load_lds_dwordx4 v140, s[34:35]
	s_waitcnt vmcnt(8)
	s_waitcnt lgkmcnt(0)
	s_setprio 1
	s_barrier
	v_mfma_f32_16x16x32_bf16 v[124:127], v[132:135], v[198:201], v[124:127]
	v_mfma_f32_16x16x32_bf16 v[120:123], v[164:167], v[198:201], v[120:123]
	v_mfma_f32_16x16x32_bf16 v[112:115], v[132:135], v[206:209], v[112:115]
	v_mfma_f32_16x16x32_bf16 v[104:107], v[164:167], v[206:209], v[104:107]
	v_mfma_f32_16x16x32_bf16 v[96:99], v[132:135], v[214:217], v[96:99]
	v_mfma_f32_16x16x32_bf16 v[88:91], v[164:167], v[214:217], v[88:91]
	v_mfma_f32_16x16x32_bf16 v[80:83], v[132:135], v[238:241], v[80:83]
	v_mfma_f32_16x16x32_bf16 v[72:75], v[164:167], v[238:241], v[72:75]
	v_mfma_f32_16x16x32_bf16 v[124:127], v[150:153], v[202:205], v[124:127]
	v_mfma_f32_16x16x32_bf16 v[120:123], v[168:171], v[202:205], v[120:123]
	v_mfma_f32_16x16x32_bf16 v[112:115], v[150:153], v[210:213], v[112:115]
	v_mfma_f32_16x16x32_bf16 v[104:107], v[168:171], v[210:213], v[104:107]
	v_mfma_f32_16x16x32_bf16 v[96:99], v[150:153], v[234:237], v[96:99]
	v_mfma_f32_16x16x32_bf16 v[88:91], v[168:171], v[234:237], v[88:91]
	v_mfma_f32_16x16x32_bf16 v[80:83], v[150:153], v[242:245], v[80:83]
	v_mfma_f32_16x16x32_bf16 v[72:75], v[168:171], v[242:245], v[72:75]
	s_setprio 0
	s_setprio 1
	v_mfma_f32_16x16x32_bf16 v[116:119], v[172:175], v[198:201], v[116:119]
	v_mfma_f32_16x16x32_bf16 v[108:111], v[190:193], v[198:201], v[108:111]
	v_mfma_f32_16x16x32_bf16 v[100:103], v[172:175], v[206:209], v[100:103]
	v_mfma_f32_16x16x32_bf16 v[92:95], v[190:193], v[206:209], v[92:95]
	v_mfma_f32_16x16x32_bf16 v[84:87], v[172:175], v[214:217], v[84:87]
	v_mfma_f32_16x16x32_bf16 v[76:79], v[190:193], v[214:217], v[76:79]
	v_mfma_f32_16x16x32_bf16 v[68:71], v[172:175], v[238:241], v[68:71]
	v_mfma_f32_16x16x32_bf16 v[64:67], v[190:193], v[238:241], v[64:67]
	v_mfma_f32_16x16x32_bf16 v[116:119], v[186:189], v[202:205], v[116:119]
	v_mfma_f32_16x16x32_bf16 v[108:111], v[194:197], v[202:205], v[108:111]
	v_mfma_f32_16x16x32_bf16 v[100:103], v[186:189], v[210:213], v[100:103]
	v_mfma_f32_16x16x32_bf16 v[92:95], v[194:197], v[210:213], v[92:95]
	v_mfma_f32_16x16x32_bf16 v[84:87], v[186:189], v[234:237], v[84:87]
	v_mfma_f32_16x16x32_bf16 v[76:79], v[194:197], v[234:237], v[76:79]
	v_mfma_f32_16x16x32_bf16 v[68:71], v[186:189], v[242:245], v[68:71]
	s_setprio 0
	v_mfma_f32_16x16x32_bf16 v[64:67], v[194:197], v[242:245], v[64:67]
	s_barrier
	s_add_i32 m0, s2, 0x18000
	s_add_u32 s4, s4, 0x80
	s_addc_u32 s5, s5, 0
	ds_read_b128 v[198:201], v163 offset:49152
	ds_read_b128 v[202:205], v163 offset:50176
	ds_read_b128 v[206:209], v163 offset:51200
	ds_read_b128 v[210:213], v163 offset:52224
	ds_read_b128 v[214:217], v163 offset:53248
	ds_read_b128 v[234:237], v163 offset:54272
	ds_read_b128 v[238:241], v163 offset:55296
	ds_read_b128 v[242:245], v163 offset:56320
	global_load_lds_dwordx4 v138, s[4:5]
	s_add_i32 m0, s2, 0x1a000
	s_add_u32 s72, s4, 0x40000
	s_addc_u32 s73, s5, 0
	global_load_lds_dwordx4 v142, s[4:5]
	s_add_i32 m0, s2, 0x1c000
	s_sub_u32 s34, s34, 0x40000
	s_subb_u32 s35, s35, 0
	global_load_lds_dwordx4 v138, s[72:73]
	s_add_i32 m0, s2, 0x1e000
	s_add_u32 s34, s34, 0x80
	s_addc_u32 s35, s35, 0
	global_load_lds_dwordx4 v142, s[72:73]
	s_mov_b32 m0, s60
	s_nop 0
	global_load_lds_dwordx4 v136, s[34:35]
	s_mov_b32 m0, s61
	s_nop 0
	global_load_lds_dwordx4 v140, s[34:35]
	s_waitcnt vmcnt(8)
	s_waitcnt lgkmcnt(0)
	s_setprio 1
	s_barrier
	v_mfma_f32_16x16x32_bf16 v[60:63], v[132:135], v[198:201], v[60:63]
	v_mfma_f32_16x16x32_bf16 v[56:59], v[164:167], v[198:201], v[56:59]
	v_mfma_f32_16x16x32_bf16 v[48:51], v[132:135], v[206:209], v[48:51]
	v_mfma_f32_16x16x32_bf16 v[40:43], v[164:167], v[206:209], v[40:43]
	v_mfma_f32_16x16x32_bf16 v[32:35], v[132:135], v[214:217], v[32:35]
	v_mfma_f32_16x16x32_bf16 v[24:27], v[164:167], v[214:217], v[24:27]
	v_mfma_f32_16x16x32_bf16 v[16:19], v[132:135], v[238:241], v[16:19]
	v_mfma_f32_16x16x32_bf16 v[8:11], v[164:167], v[238:241], v[8:11]
	v_mfma_f32_16x16x32_bf16 v[60:63], v[150:153], v[202:205], v[60:63]
	v_mfma_f32_16x16x32_bf16 v[56:59], v[168:171], v[202:205], v[56:59]
	v_mfma_f32_16x16x32_bf16 v[48:51], v[150:153], v[210:213], v[48:51]
	v_mfma_f32_16x16x32_bf16 v[40:43], v[168:171], v[210:213], v[40:43]
	v_mfma_f32_16x16x32_bf16 v[32:35], v[150:153], v[234:237], v[32:35]
	v_mfma_f32_16x16x32_bf16 v[24:27], v[168:171], v[234:237], v[24:27]
	v_mfma_f32_16x16x32_bf16 v[16:19], v[150:153], v[242:245], v[16:19]
	v_mfma_f32_16x16x32_bf16 v[8:11], v[168:171], v[242:245], v[8:11]
	s_setprio 0
	s_setprio 1
	v_mfma_f32_16x16x32_bf16 v[52:55], v[172:175], v[198:201], v[52:55]
	v_mfma_f32_16x16x32_bf16 v[44:47], v[190:193], v[198:201], v[44:47]
	v_mfma_f32_16x16x32_bf16 v[36:39], v[172:175], v[206:209], v[36:39]
	v_mfma_f32_16x16x32_bf16 v[28:31], v[190:193], v[206:209], v[28:31]
	v_mfma_f32_16x16x32_bf16 v[20:23], v[172:175], v[214:217], v[20:23]
	v_mfma_f32_16x16x32_bf16 v[12:15], v[190:193], v[214:217], v[12:15]
	v_mfma_f32_16x16x32_bf16 v[4:7], v[172:175], v[238:241], v[4:7]
	v_mfma_f32_16x16x32_bf16 v[0:3], v[190:193], v[238:241], v[0:3]
	v_mfma_f32_16x16x32_bf16 v[52:55], v[186:189], v[202:205], v[52:55]
	v_mfma_f32_16x16x32_bf16 v[44:47], v[194:197], v[202:205], v[44:47]
	v_mfma_f32_16x16x32_bf16 v[36:39], v[186:189], v[210:213], v[36:39]
	v_mfma_f32_16x16x32_bf16 v[28:31], v[194:197], v[210:213], v[28:31]
	v_mfma_f32_16x16x32_bf16 v[20:23], v[186:189], v[234:237], v[20:23]
	v_mfma_f32_16x16x32_bf16 v[12:15], v[194:197], v[234:237], v[12:15]
	v_mfma_f32_16x16x32_bf16 v[4:7], v[186:189], v[242:245], v[4:7]
	s_setprio 0
	v_mfma_f32_16x16x32_bf16 v[0:3], v[194:197], v[242:245], v[0:3]
	s_barrier
	s_add_i32 s70, s70, 2
	s_add_u32 s42, s42, 0x100
	s_addc_u32 s43, s43, 0
	s_cmp_gt_u32 s70, 13
; #define PG8_STAGE(bufoff, gbase, voff) do { _Pragma("unroll") for (int _i = 0; _i < 2; ++_i) \
;         __builtin_amdgcn_global_load_lds((const unsigned*)((const char*)(gbase) + (voff)[_i]), (PG8_LAS unsigned*)(lds + (bufoff) + ldsw + _i * 8192), 16, 0, 0); } while (0)
; #define PG8_LDA(dst, b, h) do { _Pragma("unroll") for (int m = 0; m < 4; ++m) _Pragma("unroll") for (int k = 0; k < 2; ++k) dst[m][k] = *(const PG8_LAS bf16x8*)(lds + PG8_SA(b, h) + aoff + m * 2048 + k * 1024); } while (0)
; #define PG8_LDB(dst, b, h) do { _Pragma("unroll") for (int n = 0; n < 2; ++n) _Pragma("unroll") for (int k = 0; k < 2; ++k) dst[n][k] = *(const PG8_LAS bf16x8*)(lds + PG8_SB(b, h) + boff + n * 2048 + k * 1024); } while (0)
; #define PG8_WAIT_L(n) asm volatile("s_waitcnt lgkmcnt(" #n ")" ::: "memory")
; #define PG8_BAR __builtin_amdgcn_s_barrier()
; template <class Epi, class Sched, bool ALIGN_EPI = false, bool SP2 = false>
; __device__ __forceinline__ void gemm_phase(PG8_LAS unsigned char* lds, const Gemm g, const Sched& S, const Epi& E) {
;     ...
;             const bool last = (t == nt - 2);
;             const char* a1 = cA + (size_t)(t + 1) * kstep;
;             const char* a2 = last ? nA : cA + (size_t)(t + 2) * kstep; const char* b2 = last ? nB : cB + (size_t)(t + 2) * kstep;
;             const char* a3 = a2 + kstep; const char* b3 = b2 + kstep;
;             if (last && has_next) S.a_ready(nxt);
;             if constexpr (SP2) {
;             const int relax = __builtin_amdgcn_readfirstlane((t == 0 && ui > 0) ? 1 : 0);
;             PG8_LDB(B0, 0, 0); PG8_LDB(B1, 0, 1); PG8_SCHED; PG8_LDA(At, 0, 0); PG8_STAGE(PG8_SA(1, 1), a1 + hstep, voffA);
;             asm volatile("s_cmp_lg_u32 %0, 0\n\ts_cbranch_scc1 .Lrelax%=\n\ts_waitcnt vmcnt(8)\n.Lrelax%=:\n\ts_waitcnt vmcnt(%1)" :: "s"(relax), "n"(8 + Epi::NST) : "memory", "scc");
;             PG8_WAIT_L(0); PG8_BAR; PG8_MMA(0, 0, At, B0); PG8_MMA(0, 1, At, B1); PG8_BAR; PG8_SCHED;
;             PG8_LDA(At, 0, 1); PG8_STAGE(PG8_SB(0, 0), b2, voffB); PG8_STAGE(PG8_SB(0, 1), b2 + hstep, voffB); PG8_STAGE(PG8_SA(0, 0), a2, voffA);
;             asm volatile("s_cmp_lg_u32 %0, 0\n\ts_cbranch_scc1 .Lrelax%=\n\ts_waitcnt vmcnt(8)\n.Lrelax%=:\n\ts_waitcnt vmcnt(%1)" :: "s"(relax), "n"(8 + Epi::NST) : "memory", "scc");
;             PG8_WAIT_L(0); PG8_BAR; PG8_MMA(1, 0, At, B0); PG8_MMA(1, 1, At, B1); PG8_BAR; PG8_SCHED;
.LBB0_124:
	s_add_u32 s34, s28, s42
	s_addc_u32 s35, s29, s43
	s_add_u32 s72, s34, 0x40080
	s_addc_u32 s73, s35, 0
	s_add_u32 s34, s34, 0x100
	s_addc_u32 s35, s35, 0
	s_add_u32 s4, s68, s42
	s_addc_u32 s5, s69, s43
	s_cmpk_eq_i32 s42, 0x700
	s_cselect_b32 s35, s51, s35
	s_cselect_b32 s34, s66, s34
	s_cselect_b32 s5, s49, s5
	s_cselect_b32 s4, s67, s4
	ds_read_b128 v[132:135], v154
	ds_read_b128 v[150:153], v154 offset:1024
	ds_read_b128 v[164:167], v154 offset:2048
	ds_read_b128 v[168:171], v154 offset:3072
	ds_read_b128 v[172:175], v154 offset:16384
	ds_read_b128 v[186:189], v154 offset:17408
	ds_read_b128 v[190:193], v154 offset:18432
	ds_read_b128 v[194:197], v154 offset:19456
	s_add_i32 m0, s37, 0xc000
	ds_read_b128 v[198:201], v163
	ds_read_b128 v[202:205], v163 offset:1024
	ds_read_b128 v[206:209], v163 offset:2048
	ds_read_b128 v[210:213], v163 offset:3072
	ds_read_b128 v[214:217], v163 offset:4096
	ds_read_b128 v[234:237], v163 offset:5120
	ds_read_b128 v[238:241], v163 offset:6144
	ds_read_b128 v[242:245], v163 offset:7168
	global_load_lds_dwordx4 v146, s[72:73]
	s_add_i32 m0, s37, 0xe000
	s_nop 0
	global_load_lds_dwordx4 v148, s[72:73]
	s_waitcnt vmcnt(8)
	s_waitcnt lgkmcnt(0)
	s_setprio 1
	s_barrier
	v_mfma_f32_16x16x32_bf16 v[124:127], v[132:135], v[198:201], v[124:127]
	v_mfma_f32_16x16x32_bf16 v[120:123], v[164:167], v[198:201], v[120:123]
	v_mfma_f32_16x16x32_bf16 v[112:115], v[132:135], v[206:209], v[112:115]
	v_mfma_f32_16x16x32_bf16 v[104:107], v[164:167], v[206:209], v[104:107]
	v_mfma_f32_16x16x32_bf16 v[96:99], v[132:135], v[214:217], v[96:99]
	v_mfma_f32_16x16x32_bf16 v[88:91], v[164:167], v[214:217], v[88:91]
	v_mfma_f32_16x16x32_bf16 v[80:83], v[132:135], v[238:241], v[80:83]
	v_mfma_f32_16x16x32_bf16 v[72:75], v[164:167], v[238:241], v[72:75]
	v_mfma_f32_16x16x32_bf16 v[124:127], v[150:153], v[202:205], v[124:127]
	v_mfma_f32_16x16x32_bf16 v[120:123], v[168:171], v[202:205], v[120:123]
	v_mfma_f32_16x16x32_bf16 v[112:115], v[150:153], v[210:213], v[112:115]
	v_mfma_f32_16x16x32_bf16 v[104:107], v[168:171], v[210:213], v[104:107]
	v_mfma_f32_16x16x32_bf16 v[96:99], v[150:153], v[234:237], v[96:99]
	v_mfma_f32_16x16x32_bf16 v[88:91], v[168:171], v[234:237], v[88:91]
	v_mfma_f32_16x16x32_bf16 v[80:83], v[150:153], v[242:245], v[80:83]
	v_mfma_f32_16x16x32_bf16 v[72:75], v[168:171], v[242:245], v[72:75]
	s_setprio 0
	s_setprio 1
	v_mfma_f32_16x16x32_bf16 v[116:119], v[172:175], v[198:201], v[116:119]
	v_mfma_f32_16x16x32_bf16 v[108:111], v[190:193], v[198:201], v[108:111]
	v_mfma_f32_16x16x32_bf16 v[100:103], v[172:175], v[206:209], v[100:103]
	v_mfma_f32_16x16x32_bf16 v[92:95], v[190:193], v[206:209], v[92:95]
	v_mfma_f32_16x16x32_bf16 v[84:87], v[172:175], v[214:217], v[84:87]
	v_mfma_f32_16x16x32_bf16 v[76:79], v[190:193], v[214:217], v[76:79]
	v_mfma_f32_16x16x32_bf16 v[68:71], v[172:175], v[238:241], v[68:71]
	v_mfma_f32_16x16x32_bf16 v[64:67], v[190:193], v[238:241], v[64:67]
	v_mfma_f32_16x16x32_bf16 v[116:119], v[186:189], v[202:205], v[116:119]
	v_mfma_f32_16x16x32_bf16 v[108:111], v[194:197], v[202:205], v[108:111]
	v_mfma_f32_16x16x32_bf16 v[100:103], v[186:189], v[210:213], v[100:103]
	v_mfma_f32_16x16x32_bf16 v[92:95], v[194:197], v[210:213], v[92:95]
	v_mfma_f32_16x16x32_bf16 v[84:87], v[186:189], v[234:237], v[84:87]
	v_mfma_f32_16x16x32_bf16 v[76:79], v[194:197], v[234:237], v[76:79]
	v_mfma_f32_16x16x32_bf16 v[68:71], v[186:189], v[242:245], v[68:71]
	s_setprio 0
	v_mfma_f32_16x16x32_bf16 v[64:67], v[194:197], v[242:245], v[64:67]
	s_barrier
	s_add_i32 m0, s2, 0x10000
	ds_read_b128 v[198:201], v163 offset:16384
	ds_read_b128 v[202:205], v163 offset:17408
	ds_read_b128 v[206:209], v163 offset:18432
	ds_read_b128 v[210:213], v163 offset:19456
	ds_read_b128 v[214:217], v163 offset:20480
	ds_read_b128 v[234:237], v163 offset:21504
	ds_read_b128 v[238:241], v163 offset:22528
	ds_read_b128 v[242:245], v163 offset:23552
	global_load_lds_dwordx4 v138, s[4:5]
	s_add_i32 m0, s2, 0x12000
	s_add_u32 s72, s4, 0x40000
	s_addc_u32 s73, s5, 0
	global_load_lds_dwordx4 v142, s[4:5]
	s_add_i32 m0, s2, 0x14000
	s_nop 0
	global_load_lds_dwordx4 v138, s[72:73]
	s_add_i32 m0, s2, 0x16000
	s_nop 0
	global_load_lds_dwordx4 v142, s[72:73]
	s_mov_b32 m0, s37
	s_nop 0
	global_load_lds_dwordx4 v136, s[34:35]
	s_mov_b32 m0, s57
	s_nop 0
	global_load_lds_dwordx4 v140, s[34:35]
	s_waitcnt vmcnt(8)
	s_waitcnt lgkmcnt(0)
	s_setprio 1
	s_barrier
	v_mfma_f32_16x16x32_bf16 v[60:63], v[132:135], v[198:201], v[60:63]
	v_mfma_f32_16x16x32_bf16 v[56:59], v[164:167], v[198:201], v[56:59]
	v_mfma_f32_16x16x32_bf16 v[48:51], v[132:135], v[206:209], v[48:51]
	v_mfma_f32_16x16x32_bf16 v[40:43], v[164:167], v[206:209], v[40:43]
	v_mfma_f32_16x16x32_bf16 v[32:35], v[132:135], v[214:217], v[32:35]
	v_mfma_f32_16x16x32_bf16 v[24:27], v[164:167], v[214:217], v[24:27]
	v_mfma_f32_16x16x32_bf16 v[16:19], v[132:135], v[238:241], v[16:19]
	v_mfma_f32_16x16x32_bf16 v[8:11], v[164:167], v[238:241], v[8:11]
	v_mfma_f32_16x16x32_bf16 v[60:63], v[150:153], v[202:205], v[60:63]
	v_mfma_f32_16x16x32_bf16 v[56:59], v[168:171], v[202:205], v[56:59]
	v_mfma_f32_16x16x32_bf16 v[48:51], v[150:153], v[210:213], v[48:51]
	v_mfma_f32_16x16x32_bf16 v[40:43], v[168:171], v[210:213], v[40:43]
	v_mfma_f32_16x16x32_bf16 v[32:35], v[150:153], v[234:237], v[32:35]
	v_mfma_f32_16x16x32_bf16 v[24:27], v[168:171], v[234:237], v[24:27]
	v_mfma_f32_16x16x32_bf16 v[16:19], v[150:153], v[242:245], v[16:19]
	v_mfma_f32_16x16x32_bf16 v[8:11], v[168:171], v[242:245], v[8:11]
	s_setprio 0
	s_setprio 1
	v_mfma_f32_16x16x32_bf16 v[52:55], v[172:175], v[198:201], v[52:55]
	v_mfma_f32_16x16x32_bf16 v[44:47], v[190:193], v[198:201], v[44:47]
	v_mfma_f32_16x16x32_bf16 v[36:39], v[172:175], v[206:209], v[36:39]
	v_mfma_f32_16x16x32_bf16 v[28:31], v[190:193], v[206:209], v[28:31]
	v_mfma_f32_16x16x32_bf16 v[20:23], v[172:175], v[214:217], v[20:23]
	v_mfma_f32_16x16x32_bf16 v[12:15], v[190:193], v[214:217], v[12:15]
	v_mfma_f32_16x16x32_bf16 v[4:7], v[172:175], v[238:241], v[4:7]
	v_mfma_f32_16x16x32_bf16 v[0:3], v[190:193], v[238:241], v[0:3]
	v_mfma_f32_16x16x32_bf16 v[52:55], v[186:189], v[202:205], v[52:55]
	v_mfma_f32_16x16x32_bf16 v[44:47], v[194:197], v[202:205], v[44:47]
	v_mfma_f32_16x16x32_bf16 v[36:39], v[186:189], v[210:213], v[36:39]
	v_mfma_f32_16x16x32_bf16 v[28:31], v[194:197], v[210:213], v[28:31]
	v_mfma_f32_16x16x32_bf16 v[20:23], v[186:189], v[234:237], v[20:23]
	v_mfma_f32_16x16x32_bf16 v[12:15], v[194:197], v[234:237], v[12:15]
	v_mfma_f32_16x16x32_bf16 v[4:7], v[186:189], v[242:245], v[4:7]
	s_setprio 0
	v_mfma_f32_16x16x32_bf16 v[0:3], v[194:197], v[242:245], v[0:3]
	s_barrier
; #define PG8_STAGE(bufoff, gbase, voff) do { _Pragma("unroll") for (int _i = 0; _i < 2; ++_i) \
;         __builtin_amdgcn_global_load_lds((const unsigned*)((const char*)(gbase) + (voff)[_i]), (PG8_LAS unsigned*)(lds + (bufoff) + ldsw + _i * 8192), 16, 0, 0); } while (0)
; #define PG8_LDA(dst, b, h) do { _Pragma("unroll") for (int m = 0; m < 4; ++m) _Pragma("unroll") for (int k = 0; k < 2; ++k) dst[m][k] = *(const PG8_LAS bf16x8*)(lds + PG8_SA(b, h) + aoff + m * 2048 + k * 1024); } while (0)
; #define PG8_LDB(dst, b, h) do { _Pragma("unroll") for (int n = 0; n < 2; ++n) _Pragma("unroll") for (int k = 0; k < 2; ++k) dst[n][k] = *(const PG8_LAS bf16x8*)(lds + PG8_SB(b, h) + boff + n * 2048 + k * 1024); } while (0)
; #define PG8_MMA(ai, bj, At, Bt) do { __builtin_amdgcn_s_setprio(1); _Pragma("unroll") for (int m = 0; m < 4; ++m) _Pragma("unroll") for (int n = 0; n < 2; ++n) _Pragma("unroll") for (int k = 0; k < 2; ++k) \
;         acc[ai][bj][m][n] = __builtin_amdgcn_mfma_f32_16x16x32_bf16(Bt[n][k], At[m][k], acc[ai][bj][m][n], 0, 0, 0); __builtin_amdgcn_s_setprio(0); } while (0)
; #define PG8_WAIT_V(n) asm volatile("s_waitcnt vmcnt(" #n ")" ::: "memory")
; #define PG8_WAIT_L(n) asm volatile("s_waitcnt lgkmcnt(" #n ")" ::: "memory")
; #define PG8_BAR __builtin_amdgcn_s_barrier()
; #define PG8_SCHED __builtin_amdgcn_sched_barrier(0)
; template <class Epi, class Sched, bool ALIGN_EPI = false, bool SP2 = false>
; __device__ __forceinline__ void gemm_phase(PG8_LAS unsigned char* lds, const Gemm g, const Sched& S, const Epi& E) {
;     ...
;             PG8_LDB(B0, 1, 0); PG8_LDB(B1, 1, 1); PG8_SCHED; PG8_LDA(At, 1, 0); PG8_STAGE(PG8_SA(0, 1), a2 + hstep, voffA);
;             PG8_WAIT_V(8); PG8_WAIT_L(0); PG8_BAR; PG8_MMA(0, 0, At, B0); PG8_MMA(0, 1, At, B1); PG8_BAR; PG8_SCHED;
;             PG8_LDA(At, 1, 1); PG8_STAGE(PG8_SB(1, 0), b3, voffB); PG8_STAGE(PG8_SB(1, 1), b3 + hstep, voffB); PG8_STAGE(PG8_SA(1, 0), a3, voffA);
;             PG8_WAIT_V(8); PG8_WAIT_L(0); PG8_BAR; PG8_MMA(1, 0, At, B0); PG8_MMA(1, 1, At, B1); PG8_BAR; PG8_SCHED;
	ds_read_b128 v[132:135], v154 offset:32768
	ds_read_b128 v[150:153], v154 offset:33792
	ds_read_b128 v[164:167], v154 offset:34816
	ds_read_b128 v[168:171], v154 offset:35840
	ds_read_b128 v[172:175], v154 offset:49152
	ds_read_b128 v[186:189], v154 offset:50176
	ds_read_b128 v[190:193], v154 offset:51200
	ds_read_b128 v[194:197], v154 offset:52224
	s_add_u32 s34, s34, 0x40000
	s_addc_u32 s35, s35, 0
	s_mov_b32 m0, s58
	ds_read_b128 v[198:201], v163 offset:32768
	ds_read_b128 v[202:205], v163 offset:33792
	ds_read_b128 v[206:209], v163 offset:34816
	ds_read_b128 v[210:213], v163 offset:35840
	ds_read_b128 v[214:217], v163 offset:36864
	ds_read_b128 v[234:237], v163 offset:37888
	ds_read_b128 v[238:241], v163 offset:38912
	ds_read_b128 v[242:245], v163 offset:39936
	global_load_lds_dwordx4 v136, s[34:35]
	s_mov_b32 m0, s59
	s_nop 0
	global_load_lds_dwordx4 v140, s[34:35]
	s_waitcnt vmcnt(8)
	s_waitcnt lgkmcnt(0)
	s_setprio 1
	s_barrier
	v_mfma_f32_16x16x32_bf16 v[124:127], v[132:135], v[198:201], v[124:127]
	v_mfma_f32_16x16x32_bf16 v[120:123], v[164:167], v[198:201], v[120:123]
	v_mfma_f32_16x16x32_bf16 v[112:115], v[132:135], v[206:209], v[112:115]
	v_mfma_f32_16x16x32_bf16 v[104:107], v[164:167], v[206:209], v[104:107]
	v_mfma_f32_16x16x32_bf16 v[96:99], v[132:135], v[214:217], v[96:99]
	v_mfma_f32_16x16x32_bf16 v[88:91], v[164:167], v[214:217], v[88:91]
	v_mfma_f32_16x16x32_bf16 v[80:83], v[132:135], v[238:241], v[80:83]
	v_mfma_f32_16x16x32_bf16 v[72:75], v[164:167], v[238:241], v[72:75]
	v_mfma_f32_16x16x32_bf16 v[124:127], v[150:153], v[202:205], v[124:127]
	v_mfma_f32_16x16x32_bf16 v[120:123], v[168:171], v[202:205], v[120:123]
	v_mfma_f32_16x16x32_bf16 v[112:115], v[150:153], v[210:213], v[112:115]
	v_mfma_f32_16x16x32_bf16 v[104:107], v[168:171], v[210:213], v[104:107]
	v_mfma_f32_16x16x32_bf16 v[96:99], v[150:153], v[234:237], v[96:99]
	v_mfma_f32_16x16x32_bf16 v[88:91], v[168:171], v[234:237], v[88:91]
	v_mfma_f32_16x16x32_bf16 v[80:83], v[150:153], v[242:245], v[80:83]
	v_mfma_f32_16x16x32_bf16 v[72:75], v[168:171], v[242:245], v[72:75]
	s_setprio 0
	s_setprio 1
	v_mfma_f32_16x16x32_bf16 v[116:119], v[172:175], v[198:201], v[116:119]
	v_mfma_f32_16x16x32_bf16 v[108:111], v[190:193], v[198:201], v[108:111]
	v_mfma_f32_16x16x32_bf16 v[100:103], v[172:175], v[206:209], v[100:103]
	v_mfma_f32_16x16x32_bf16 v[92:95], v[190:193], v[206:209], v[92:95]
	v_mfma_f32_16x16x32_bf16 v[84:87], v[172:175], v[214:217], v[84:87]
	v_mfma_f32_16x16x32_bf16 v[76:79], v[190:193], v[214:217], v[76:79]
	v_mfma_f32_16x16x32_bf16 v[68:71], v[172:175], v[238:241], v[68:71]
	v_mfma_f32_16x16x32_bf16 v[64:67], v[190:193], v[238:241], v[64:67]
	v_mfma_f32_16x16x32_bf16 v[116:119], v[186:189], v[202:205], v[116:119]
	v_mfma_f32_16x16x32_bf16 v[108:111], v[194:197], v[202:205], v[108:111]
	v_mfma_f32_16x16x32_bf16 v[100:103], v[186:189], v[210:213], v[100:103]
	v_mfma_f32_16x16x32_bf16 v[92:95], v[194:197], v[210:213], v[92:95]
	v_mfma_f32_16x16x32_bf16 v[84:87], v[186:189], v[234:237], v[84:87]
	v_mfma_f32_16x16x32_bf16 v[76:79], v[194:197], v[234:237], v[76:79]
	v_mfma_f32_16x16x32_bf16 v[68:71], v[186:189], v[242:245], v[68:71]
	s_setprio 0
	v_mfma_f32_16x16x32_bf16 v[64:67], v[194:197], v[242:245], v[64:67]
	s_barrier
	s_add_i32 m0, s2, 0x18000
	s_add_u32 s4, s4, 0x80
	s_addc_u32 s5, s5, 0
	ds_read_b128 v[198:201], v163 offset:49152
	ds_read_b128 v[202:205], v163 offset:50176
	ds_read_b128 v[206:209], v163 offset:51200
	ds_read_b128 v[210:213], v163 offset:52224
	ds_read_b128 v[214:217], v163 offset:53248
	ds_read_b128 v[234:237], v163 offset:54272
	ds_read_b128 v[238:241], v163 offset:55296
	ds_read_b128 v[242:245], v163 offset:56320
	global_load_lds_dwordx4 v138, s[4:5]
	s_add_i32 m0, s2, 0x1a000
	s_add_u32 s72, s4, 0x40000
	s_addc_u32 s73, s5, 0
	global_load_lds_dwordx4 v142, s[4:5]
	s_add_i32 m0, s2, 0x1c000
	s_sub_u32 s34, s34, 0x40000
	s_subb_u32 s35, s35, 0
	global_load_lds_dwordx4 v138, s[72:73]
	s_add_i32 m0, s2, 0x1e000
	s_add_u32 s34, s34, 0x80
	s_addc_u32 s35, s35, 0
	global_load_lds_dwordx4 v142, s[72:73]
	s_mov_b32 m0, s60
	s_nop 0
	global_load_lds_dwordx4 v136, s[34:35]
	s_mov_b32 m0, s61
	s_nop 0
	global_load_lds_dwordx4 v140, s[34:35]
	s_waitcnt vmcnt(8)
	s_waitcnt lgkmcnt(0)
	s_setprio 1
	s_barrier
	v_mfma_f32_16x16x32_bf16 v[60:63], v[132:135], v[198:201], v[60:63]
	v_mfma_f32_16x16x32_bf16 v[56:59], v[164:167], v[198:201], v[56:59]
	v_mfma_f32_16x16x32_bf16 v[48:51], v[132:135], v[206:209], v[48:51]
	v_mfma_f32_16x16x32_bf16 v[40:43], v[164:167], v[206:209], v[40:43]
	v_mfma_f32_16x16x32_bf16 v[32:35], v[132:135], v[214:217], v[32:35]
	v_mfma_f32_16x16x32_bf16 v[24:27], v[164:167], v[214:217], v[24:27]
	v_mfma_f32_16x16x32_bf16 v[16:19], v[132:135], v[238:241], v[16:19]
	v_mfma_f32_16x16x32_bf16 v[8:11], v[164:167], v[238:241], v[8:11]
	v_mfma_f32_16x16x32_bf16 v[60:63], v[150:153], v[202:205], v[60:63]
	v_mfma_f32_16x16x32_bf16 v[56:59], v[168:171], v[202:205], v[56:59]
	v_mfma_f32_16x16x32_bf16 v[48:51], v[150:153], v[210:213], v[48:51]
	v_mfma_f32_16x16x32_bf16 v[40:43], v[168:171], v[210:213], v[40:43]
	v_mfma_f32_16x16x32_bf16 v[32:35], v[150:153], v[234:237], v[32:35]
	v_mfma_f32_16x16x32_bf16 v[24:27], v[168:171], v[234:237], v[24:27]
	v_mfma_f32_16x16x32_bf16 v[16:19], v[150:153], v[242:245], v[16:19]
	v_mfma_f32_16x16x32_bf16 v[8:11], v[168:171], v[242:245], v[8:11]
	s_setprio 0
	s_setprio 1
	v_mfma_f32_16x16x32_bf16 v[52:55], v[172:175], v[198:201], v[52:55]
	v_mfma_f32_16x16x32_bf16 v[44:47], v[190:193], v[198:201], v[44:47]
	v_mfma_f32_16x16x32_bf16 v[36:39], v[172:175], v[206:209], v[36:39]
	v_mfma_f32_16x16x32_bf16 v[28:31], v[190:193], v[206:209], v[28:31]
	v_mfma_f32_16x16x32_bf16 v[20:23], v[172:175], v[214:217], v[20:23]
	v_mfma_f32_16x16x32_bf16 v[12:15], v[190:193], v[214:217], v[12:15]
	v_mfma_f32_16x16x32_bf16 v[4:7], v[172:175], v[238:241], v[4:7]
	v_mfma_f32_16x16x32_bf16 v[0:3], v[190:193], v[238:241], v[0:3]
	v_mfma_f32_16x16x32_bf16 v[52:55], v[186:189], v[202:205], v[52:55]
	v_mfma_f32_16x16x32_bf16 v[44:47], v[194:197], v[202:205], v[44:47]
	v_mfma_f32_16x16x32_bf16 v[36:39], v[186:189], v[210:213], v[36:39]
	v_mfma_f32_16x16x32_bf16 v[28:31], v[194:197], v[210:213], v[28:31]
	v_mfma_f32_16x16x32_bf16 v[20:23], v[186:189], v[234:237], v[20:23]
	v_mfma_f32_16x16x32_bf16 v[12:15], v[194:197], v[234:237], v[12:15]
	v_mfma_f32_16x16x32_bf16 v[4:7], v[186:189], v[242:245], v[4:7]
	s_setprio 0
	v_mfma_f32_16x16x32_bf16 v[0:3], v[194:197], v[242:245], v[0:3]
	s_barrier
	s_add_i32 s70, s70, 2
	s_add_u32 s42, s42, 0x100
	s_addc_u32 s43, s43, 0
	s_cmp_gt_u32 s70, 13
	s_cbranch_scc0 .LBB0_124

; #define PG8_STAGE(bufoff, gbase, voff) do { _Pragma("unroll") for (int _i = 0; _i < 2; ++_i) \
;         __builtin_amdgcn_global_load_lds((const unsigned*)((const char*)(gbase) + (voff)[_i]), (PG8_LAS unsigned*)(lds + (bufoff) + ldsw + _i * 8192), 16, 0, 0); } while (0)
; #define PG8_LDA(dst, b, h) do { _Pragma("unroll") for (int m = 0; m < 4; ++m) _Pragma("unroll") for (int k = 0; k < 2; ++k) dst[m][k] = *(const PG8_LAS bf16x8*)(lds + PG8_SA(b, h) + aoff + m * 2048 + k * 1024); } while (0)
; #define PG8_LDB(dst, b, h) do { _Pragma("unroll") for (int n = 0; n < 2; ++n) _Pragma("unroll") for (int k = 0; k < 2; ++k) dst[n][k] = *(const PG8_LAS bf16x8*)(lds + PG8_SB(b, h) + boff + n * 2048 + k * 1024); } while (0)
; #define PG8_MMA(ai, bj, At, Bt) do { __builtin_amdgcn_s_setprio(1); _Pragma("unroll") for (int m = 0; m < 4; ++m) _Pragma("unroll") for (int n = 0; n < 2; ++n) _Pragma("unroll") for (int k = 0; k < 2; ++k) \
;         acc[ai][bj][m][n] = __builtin_amdgcn_mfma_f32_16x16x32_bf16(Bt[n][k], At[m][k], acc[ai][bj][m][n], 0, 0, 0); __builtin_amdgcn_s_setprio(0); } while (0)
; #define PG8_WAIT_L(n) asm volatile("s_waitcnt lgkmcnt(" #n ")" ::: "memory")
; #define PG8_BAR __builtin_amdgcn_s_barrier()
; #define PG8_SCHED __builtin_amdgcn_sched_barrier(0)
; template <class Epi, class Sched, bool ALIGN_EPI = false, bool SP2 = false>
; __device__ __forceinline__ void gemm_phase(PG8_LAS unsigned char* lds, const Gemm g, const Sched& S, const Epi& E) {
;     ...
;             PG8_LDB(B0, 0, 0); PG8_LDB(B1, 0, 1); PG8_SCHED; PG8_LDA(At, 0, 0); PG8_STAGE(PG8_SA(1, 1), a1 + hstep, voffA);
;             asm volatile("s_cmp_lg_u32 %0, 0\n\ts_cbranch_scc1 .Lrelax%=\n\ts_waitcnt vmcnt(8)\n.Lrelax%=:\n\ts_waitcnt vmcnt(%1)" :: "s"(relax), "n"(8 + Epi::NST) : "memory", "scc");
;             PG8_WAIT_L(0); PG8_BAR; PG8_MMA(0, 0, At, B0); PG8_MMA(0, 1, At, B1); PG8_BAR; PG8_SCHED;
;             PG8_LDA(At, 0, 1); PG8_STAGE(PG8_SB(0, 0), b2, voffB); PG8_STAGE(PG8_SB(0, 1), b2 + hstep, voffB); PG8_STAGE(PG8_SA(0, 0), a2, voffA);
;             asm volatile("s_cmp_lg_u32 %0, 0\n\ts_cbranch_scc1 .Lrelax%=\n\ts_waitcnt vmcnt(8)\n.Lrelax%=:\n\ts_waitcnt vmcnt(%1)" :: "s"(relax), "n"(8 + Epi::NST) : "memory", "scc");
;             PG8_WAIT_L(0); PG8_BAR; PG8_MMA(1, 0, At, B0); PG8_MMA(1, 1, At, B1); PG8_BAR; PG8_SCHED;
.Lmy_glup_rx1:
	s_waitcnt vmcnt(16)
	s_waitcnt lgkmcnt(0)
	s_setprio 1
	s_barrier
	v_mfma_f32_16x16x32_bf16 v[148:151], v[60:63], v[194:197], 0
	v_mfma_f32_16x16x32_bf16 v[144:147], v[76:79], v[194:197], 0
	v_mfma_f32_16x16x32_bf16 v[132:135], v[60:63], v[202:205], 0
	v_mfma_f32_16x16x32_bf16 v[124:127], v[76:79], v[202:205], 0
	v_mfma_f32_16x16x32_bf16 v[116:119], v[60:63], v[210:213], 0
	v_mfma_f32_16x16x32_bf16 v[108:111], v[76:79], v[210:213], 0
	v_mfma_f32_16x16x32_bf16 v[100:103], v[60:63], v[234:237], 0
	v_mfma_f32_16x16x32_bf16 v[92:95], v[76:79], v[234:237], 0
	v_mfma_f32_16x16x32_bf16 v[148:151], v[68:71], v[198:201], v[148:151]
	v_mfma_f32_16x16x32_bf16 v[144:147], v[80:83], v[198:201], v[144:147]
	v_mfma_f32_16x16x32_bf16 v[132:135], v[68:71], v[206:209], v[132:135]
	v_mfma_f32_16x16x32_bf16 v[124:127], v[80:83], v[206:209], v[124:127]
	v_mfma_f32_16x16x32_bf16 v[116:119], v[68:71], v[214:217], v[116:119]
	v_mfma_f32_16x16x32_bf16 v[108:111], v[80:83], v[214:217], v[108:111]
	v_mfma_f32_16x16x32_bf16 v[100:103], v[68:71], v[238:241], v[100:103]
	v_mfma_f32_16x16x32_bf16 v[92:95], v[80:83], v[238:241], v[92:95]
	s_setprio 0
	s_setprio 1
	v_mfma_f32_16x16x32_bf16 v[140:143], v[88:91], v[194:197], 0
	v_mfma_f32_16x16x32_bf16 v[136:139], v[168:171], v[194:197], 0
	v_mfma_f32_16x16x32_bf16 v[128:131], v[88:91], v[202:205], 0
	v_mfma_f32_16x16x32_bf16 v[120:123], v[168:171], v[202:205], 0
	v_mfma_f32_16x16x32_bf16 v[112:115], v[88:91], v[210:213], 0
	v_mfma_f32_16x16x32_bf16 v[104:107], v[168:171], v[210:213], 0
	v_mfma_f32_16x16x32_bf16 v[96:99], v[88:91], v[234:237], 0
	v_mfma_f32_16x16x32_bf16 v[84:87], v[168:171], v[234:237], 0
	v_mfma_f32_16x16x32_bf16 v[140:143], v[164:167], v[198:201], v[140:143]
	v_mfma_f32_16x16x32_bf16 v[136:139], v[172:175], v[198:201], v[136:139]
	v_mfma_f32_16x16x32_bf16 v[128:131], v[164:167], v[206:209], v[128:131]
	v_mfma_f32_16x16x32_bf16 v[120:123], v[172:175], v[206:209], v[120:123]
	v_mfma_f32_16x16x32_bf16 v[112:115], v[164:167], v[214:217], v[112:115]
	v_mfma_f32_16x16x32_bf16 v[104:107], v[172:175], v[214:217], v[104:107]
	v_mfma_f32_16x16x32_bf16 v[96:99], v[164:167], v[238:241], v[96:99]
	s_setprio 0
	v_mfma_f32_16x16x32_bf16 v[84:87], v[172:175], v[238:241], v[84:87]
	s_barrier
	s_add_i32 m0, s2, 0x10000
	ds_read_b128 v[194:197], v193 offset:16384
	ds_read_b128 v[198:201], v193 offset:17408
	ds_read_b128 v[202:205], v193 offset:18432
	ds_read_b128 v[206:209], v193 offset:19456
	ds_read_b128 v[210:213], v193 offset:20480
	ds_read_b128 v[214:217], v193 offset:21504
	ds_read_b128 v[234:237], v193 offset:22528
	ds_read_b128 v[238:241], v193 offset:23552
	global_load_lds_dwordx4 v176, s[4:5]
	s_add_i32 m0, s2, 0x12000
	s_add_u32 s70, s4, 0x40000
	s_addc_u32 s71, s5, 0
	global_load_lds_dwordx4 v156, s[4:5]
	s_add_i32 m0, s2, 0x14000
	s_nop 0
	global_load_lds_dwordx4 v176, s[70:71]
	s_add_i32 m0, s2, 0x16000
	s_nop 0
	global_load_lds_dwordx4 v156, s[70:71]
	s_mov_b32 m0, s37
	s_nop 0
	global_load_lds_dwordx4 v152, s[34:35]
	s_mov_b32 m0, s57
	s_nop 0
	global_load_lds_dwordx4 v154, s[34:35]
	s_cmp_lg_u32 s30, 0
	s_cbranch_scc1 .Lmy_glup_rx2
	s_waitcnt vmcnt(8)
.Lmy_glup_rx2:
	s_waitcnt vmcnt(16)
	s_waitcnt lgkmcnt(0)
	s_setprio 1
	s_barrier
	v_mfma_f32_16x16x32_bf16 v[72:75], v[60:63], v[194:197], 0
	v_mfma_f32_16x16x32_bf16 v[52:55], v[76:79], v[194:197], 0
	v_mfma_f32_16x16x32_bf16 v[44:47], v[60:63], v[202:205], 0
	v_mfma_f32_16x16x32_bf16 v[36:39], v[76:79], v[202:205], 0
	v_mfma_f32_16x16x32_bf16 v[28:31], v[60:63], v[210:213], 0
	v_mfma_f32_16x16x32_bf16 v[20:23], v[76:79], v[210:213], 0
	v_mfma_f32_16x16x32_bf16 v[12:15], v[60:63], v[234:237], 0
	v_mfma_f32_16x16x32_bf16 v[4:7], v[76:79], v[234:237], 0
	v_mfma_f32_16x16x32_bf16 v[72:75], v[68:71], v[198:201], v[72:75]
	v_mfma_f32_16x16x32_bf16 v[52:55], v[80:83], v[198:201], v[52:55]
	v_mfma_f32_16x16x32_bf16 v[44:47], v[68:71], v[206:209], v[44:47]
	v_mfma_f32_16x16x32_bf16 v[36:39], v[80:83], v[206:209], v[36:39]
	v_mfma_f32_16x16x32_bf16 v[28:31], v[68:71], v[214:217], v[28:31]
	v_mfma_f32_16x16x32_bf16 v[20:23], v[80:83], v[214:217], v[20:23]
	v_mfma_f32_16x16x32_bf16 v[12:15], v[68:71], v[238:241], v[12:15]
	v_mfma_f32_16x16x32_bf16 v[4:7], v[80:83], v[238:241], v[4:7]
	s_setprio 0
	s_setprio 1
	v_mfma_f32_16x16x32_bf16 v[48:51], v[168:171], v[194:197], 0
	v_mfma_f32_16x16x32_bf16 v[40:43], v[88:91], v[202:205], 0
	v_mfma_f32_16x16x32_bf16 v[32:35], v[168:171], v[202:205], 0
	v_mfma_f32_16x16x32_bf16 v[24:27], v[88:91], v[210:213], 0
	v_mfma_f32_16x16x32_bf16 v[16:19], v[168:171], v[210:213], 0
	v_mfma_f32_16x16x32_bf16 v[8:11], v[88:91], v[234:237], 0
	v_mfma_f32_16x16x32_bf16 v[0:3], v[168:171], v[234:237], 0
	v_mfma_f32_16x16x32_bf16 v[60:63], v[88:91], v[194:197], 0
	v_mfma_f32_16x16x32_bf16 v[48:51], v[172:175], v[198:201], v[48:51]
	v_mfma_f32_16x16x32_bf16 v[40:43], v[164:167], v[206:209], v[40:43]
	v_mfma_f32_16x16x32_bf16 v[32:35], v[172:175], v[206:209], v[32:35]
	v_mfma_f32_16x16x32_bf16 v[24:27], v[164:167], v[214:217], v[24:27]
	v_mfma_f32_16x16x32_bf16 v[16:19], v[172:175], v[214:217], v[16:19]
	v_mfma_f32_16x16x32_bf16 v[8:11], v[164:167], v[238:241], v[8:11]
	v_mfma_f32_16x16x32_bf16 v[0:3], v[172:175], v[238:241], v[0:3]
	s_setprio 0
	v_mfma_f32_16x16x32_bf16 v[60:63], v[164:167], v[198:201], v[60:63]
	s_barrier
; #define PG8_STAGE(bufoff, gbase, voff) do { _Pragma("unroll") for (int _i = 0; _i < 2; ++_i) \
;         __builtin_amdgcn_global_load_lds((const unsigned*)((const char*)(gbase) + (voff)[_i]), (PG8_LAS unsigned*)(lds + (bufoff) + ldsw + _i * 8192), 16, 0, 0); } while (0)
; #define PG8_LDA(dst, b, h) do { _Pragma("unroll") for (int m = 0; m < 4; ++m) _Pragma("unroll") for (int k = 0; k < 2; ++k) dst[m][k] = *(const PG8_LAS bf16x8*)(lds + PG8_SA(b, h) + aoff + m * 2048 + k * 1024); } while (0)
; #define PG8_LDB(dst, b, h) do { _Pragma("unroll") for (int n = 0; n < 2; ++n) _Pragma("unroll") for (int k = 0; k < 2; ++k) dst[n][k] = *(const PG8_LAS bf16x8*)(lds + PG8_SB(b, h) + boff + n * 2048 + k * 1024); } while (0)
; #define PG8_MMA(ai, bj, At, Bt) do { __builtin_amdgcn_s_setprio(1); _Pragma("unroll") for (int m = 0; m < 4; ++m) _Pragma("unroll") for (int n = 0; n < 2; ++n) _Pragma("unroll") for (int k = 0; k < 2; ++k) \
;         acc[ai][bj][m][n] = __builtin_amdgcn_mfma_f32_16x16x32_bf16(Bt[n][k], At[m][k], acc[ai][bj][m][n], 0, 0, 0); __builtin_amdgcn_s_setprio(0); } while (0)
; #define PG8_WAIT_V(n) asm volatile("s_waitcnt vmcnt(" #n ")" ::: "memory")
; #define PG8_WAIT_L(n) asm volatile("s_waitcnt lgkmcnt(" #n ")" ::: "memory")
; #define PG8_BAR __builtin_amdgcn_s_barrier()
; #define PG8_SCHED __builtin_amdgcn_sched_barrier(0)
; template <class Epi, class Sched, bool ALIGN_EPI = false, bool SP2 = false>
; __device__ __forceinline__ void gemm_phase(PG8_LAS unsigned char* lds, const Gemm g, const Sched& S, const Epi& E) {
;     ...
;             PG8_LDB(B0, 1, 0); PG8_LDB(B1, 1, 1); PG8_SCHED; PG8_LDA(At, 1, 0); PG8_STAGE(PG8_SA(0, 1), a2 + hstep, voffA);
;             PG8_WAIT_V(8); PG8_WAIT_L(0); PG8_BAR; PG8_MMA(0, 0, At, B0); PG8_MMA(0, 1, At, B1); PG8_BAR; PG8_SCHED;
;             PG8_LDA(At, 1, 1); PG8_STAGE(PG8_SB(1, 0), b3, voffB); PG8_STAGE(PG8_SB(1, 1), b3 + hstep, voffB); PG8_STAGE(PG8_SA(1, 0), a3, voffA);
;             PG8_WAIT_V(8); PG8_WAIT_L(0); PG8_BAR; PG8_MMA(1, 0, At, B0); PG8_MMA(1, 1, At, B1); PG8_BAR; PG8_SCHED;
	ds_read_b128 v[64:67], v242 offset:32768
	ds_read_b128 v[68:71], v242 offset:33792
	ds_read_b128 v[76:79], v242 offset:34816
	ds_read_b128 v[80:83], v242 offset:35840
	ds_read_b128 v[88:91], v242 offset:49152
	ds_read_b128 v[164:167], v242 offset:50176
	ds_read_b128 v[168:171], v242 offset:51200
	ds_read_b128 v[172:175], v242 offset:52224
	s_add_u32 s34, s34, 0x40000
	s_addc_u32 s35, s35, 0
	s_mov_b32 m0, s58
	ds_read_b128 v[194:197], v193 offset:32768
	ds_read_b128 v[198:201], v193 offset:33792
	ds_read_b128 v[202:205], v193 offset:34816
	ds_read_b128 v[206:209], v193 offset:35840
	ds_read_b128 v[210:213], v193 offset:36864
	ds_read_b128 v[214:217], v193 offset:37888
	ds_read_b128 v[234:237], v193 offset:38912
	ds_read_b128 v[238:241], v193 offset:39936
	global_load_lds_dwordx4 v152, s[34:35]
	s_mov_b32 m0, s59
	s_nop 0
	global_load_lds_dwordx4 v154, s[34:35]
	s_waitcnt vmcnt(8)
	s_waitcnt lgkmcnt(0)
	s_setprio 1
	s_barrier
	v_mfma_f32_16x16x32_bf16 v[148:151], v[64:67], v[194:197], v[148:151]
	v_mfma_f32_16x16x32_bf16 v[144:147], v[76:79], v[194:197], v[144:147]
	v_mfma_f32_16x16x32_bf16 v[132:135], v[64:67], v[202:205], v[132:135]
	v_mfma_f32_16x16x32_bf16 v[124:127], v[76:79], v[202:205], v[124:127]
	v_mfma_f32_16x16x32_bf16 v[116:119], v[64:67], v[210:213], v[116:119]
	v_mfma_f32_16x16x32_bf16 v[108:111], v[76:79], v[210:213], v[108:111]
	v_mfma_f32_16x16x32_bf16 v[100:103], v[64:67], v[234:237], v[100:103]
	v_mfma_f32_16x16x32_bf16 v[92:95], v[76:79], v[234:237], v[92:95]
	v_mfma_f32_16x16x32_bf16 v[148:151], v[68:71], v[198:201], v[148:151]
	v_mfma_f32_16x16x32_bf16 v[144:147], v[80:83], v[198:201], v[144:147]
	v_mfma_f32_16x16x32_bf16 v[132:135], v[68:71], v[206:209], v[132:135]
	v_mfma_f32_16x16x32_bf16 v[124:127], v[80:83], v[206:209], v[124:127]
	v_mfma_f32_16x16x32_bf16 v[116:119], v[68:71], v[214:217], v[116:119]
	v_mfma_f32_16x16x32_bf16 v[108:111], v[80:83], v[214:217], v[108:111]
	v_mfma_f32_16x16x32_bf16 v[100:103], v[68:71], v[238:241], v[100:103]
	v_mfma_f32_16x16x32_bf16 v[92:95], v[80:83], v[238:241], v[92:95]
	s_setprio 0
	s_setprio 1
	v_mfma_f32_16x16x32_bf16 v[140:143], v[88:91], v[194:197], v[140:143]
	v_mfma_f32_16x16x32_bf16 v[136:139], v[168:171], v[194:197], v[136:139]
	v_mfma_f32_16x16x32_bf16 v[128:131], v[88:91], v[202:205], v[128:131]
	v_mfma_f32_16x16x32_bf16 v[120:123], v[168:171], v[202:205], v[120:123]
	v_mfma_f32_16x16x32_bf16 v[112:115], v[88:91], v[210:213], v[112:115]
	v_mfma_f32_16x16x32_bf16 v[104:107], v[168:171], v[210:213], v[104:107]
	v_mfma_f32_16x16x32_bf16 v[96:99], v[88:91], v[234:237], v[96:99]
	v_mfma_f32_16x16x32_bf16 v[84:87], v[168:171], v[234:237], v[84:87]
	v_mfma_f32_16x16x32_bf16 v[140:143], v[164:167], v[198:201], v[140:143]
	v_mfma_f32_16x16x32_bf16 v[136:139], v[172:175], v[198:201], v[136:139]
	v_mfma_f32_16x16x32_bf16 v[128:131], v[164:167], v[206:209], v[128:131]
	v_mfma_f32_16x16x32_bf16 v[120:123], v[172:175], v[206:209], v[120:123]
	v_mfma_f32_16x16x32_bf16 v[112:115], v[164:167], v[214:217], v[112:115]
	v_mfma_f32_16x16x32_bf16 v[104:107], v[172:175], v[214:217], v[104:107]
	v_mfma_f32_16x16x32_bf16 v[96:99], v[164:167], v[238:241], v[96:99]
	s_setprio 0
	v_mfma_f32_16x16x32_bf16 v[84:87], v[172:175], v[238:241], v[84:87]
	s_barrier
	s_add_i32 m0, s2, 0x18000
	s_add_u32 s4, s4, 0x80
	s_addc_u32 s5, s5, 0
	ds_read_b128 v[194:197], v193 offset:49152
	ds_read_b128 v[198:201], v193 offset:50176
	ds_read_b128 v[202:205], v193 offset:51200
	ds_read_b128 v[206:209], v193 offset:52224
	ds_read_b128 v[210:213], v193 offset:53248
	ds_read_b128 v[214:217], v193 offset:54272
	ds_read_b128 v[234:237], v193 offset:55296
	ds_read_b128 v[238:241], v193 offset:56320
	global_load_lds_dwordx4 v176, s[4:5]
	s_add_i32 m0, s2, 0x1a000
	s_add_u32 s70, s4, 0x40000
	s_addc_u32 s71, s5, 0
	global_load_lds_dwordx4 v156, s[4:5]
	s_add_i32 m0, s2, 0x1c000
	s_sub_u32 s34, s34, 0x40000
	s_subb_u32 s35, s35, 0
	global_load_lds_dwordx4 v176, s[70:71]
	s_add_i32 m0, s2, 0x1e000
	s_add_u32 s34, s34, 0x80
	s_addc_u32 s35, s35, 0
	global_load_lds_dwordx4 v156, s[70:71]
	s_mov_b32 m0, s60
	s_nop 0
	global_load_lds_dwordx4 v152, s[34:35]
	s_mov_b32 m0, s61
	s_nop 0
	global_load_lds_dwordx4 v154, s[34:35]
	s_waitcnt vmcnt(8)
	s_waitcnt lgkmcnt(0)
	s_setprio 1
	s_barrier
	v_mfma_f32_16x16x32_bf16 v[72:75], v[64:67], v[194:197], v[72:75]
	v_mfma_f32_16x16x32_bf16 v[52:55], v[76:79], v[194:197], v[52:55]
	v_mfma_f32_16x16x32_bf16 v[44:47], v[64:67], v[202:205], v[44:47]
	v_mfma_f32_16x16x32_bf16 v[36:39], v[76:79], v[202:205], v[36:39]
	v_mfma_f32_16x16x32_bf16 v[28:31], v[64:67], v[210:213], v[28:31]
	v_mfma_f32_16x16x32_bf16 v[20:23], v[76:79], v[210:213], v[20:23]
	v_mfma_f32_16x16x32_bf16 v[12:15], v[64:67], v[234:237], v[12:15]
	v_mfma_f32_16x16x32_bf16 v[4:7], v[76:79], v[234:237], v[4:7]
	v_mfma_f32_16x16x32_bf16 v[72:75], v[68:71], v[198:201], v[72:75]
	v_mfma_f32_16x16x32_bf16 v[52:55], v[80:83], v[198:201], v[52:55]
	v_mfma_f32_16x16x32_bf16 v[44:47], v[68:71], v[206:209], v[44:47]
	v_mfma_f32_16x16x32_bf16 v[36:39], v[80:83], v[206:209], v[36:39]
	v_mfma_f32_16x16x32_bf16 v[28:31], v[68:71], v[214:217], v[28:31]
	v_mfma_f32_16x16x32_bf16 v[20:23], v[80:83], v[214:217], v[20:23]
	v_mfma_f32_16x16x32_bf16 v[12:15], v[68:71], v[238:241], v[12:15]
	v_mfma_f32_16x16x32_bf16 v[4:7], v[80:83], v[238:241], v[4:7]
	s_setprio 0
	s_setprio 1
	v_mfma_f32_16x16x32_bf16 v[60:63], v[88:91], v[194:197], v[60:63]
	v_mfma_f32_16x16x32_bf16 v[48:51], v[168:171], v[194:197], v[48:51]
	v_mfma_f32_16x16x32_bf16 v[40:43], v[88:91], v[202:205], v[40:43]
	v_mfma_f32_16x16x32_bf16 v[32:35], v[168:171], v[202:205], v[32:35]
	v_mfma_f32_16x16x32_bf16 v[24:27], v[88:91], v[210:213], v[24:27]
	v_mfma_f32_16x16x32_bf16 v[16:19], v[168:171], v[210:213], v[16:19]
	v_mfma_f32_16x16x32_bf16 v[8:11], v[88:91], v[234:237], v[8:11]
	v_mfma_f32_16x16x32_bf16 v[0:3], v[168:171], v[234:237], v[0:3]
	v_mfma_f32_16x16x32_bf16 v[64:67], v[164:167], v[198:201], v[60:63]
	v_mfma_f32_16x16x32_bf16 v[48:51], v[172:175], v[198:201], v[48:51]
	v_mfma_f32_16x16x32_bf16 v[40:43], v[164:167], v[206:209], v[40:43]
	v_mfma_f32_16x16x32_bf16 v[32:35], v[172:175], v[206:209], v[32:35]
	v_mfma_f32_16x16x32_bf16 v[24:27], v[164:167], v[214:217], v[24:27]
	v_mfma_f32_16x16x32_bf16 v[16:19], v[172:175], v[214:217], v[16:19]
	v_mfma_f32_16x16x32_bf16 v[8:11], v[164:167], v[238:241], v[8:11]
	s_setprio 0
	v_mfma_f32_16x16x32_bf16 v[0:3], v[172:175], v[238:241], v[0:3]
	s_barrier
	s_add_i32 s69, s69, 2
	s_add_u32 s40, s40, 0x100
	s_addc_u32 s41, s41, 0
	s_cmp_gt_u32 s69, 13
; #define PG8_STAGE(bufoff, gbase, voff) do { _Pragma("unroll") for (int _i = 0; _i < 2; ++_i) \
;         __builtin_amdgcn_global_load_lds((const unsigned*)((const char*)(gbase) + (voff)[_i]), (PG8_LAS unsigned*)(lds + (bufoff) + ldsw + _i * 8192), 16, 0, 0); } while (0)
; #define PG8_LDA(dst, b, h) do { _Pragma("unroll") for (int m = 0; m < 4; ++m) _Pragma("unroll") for (int k = 0; k < 2; ++k) dst[m][k] = *(const PG8_LAS bf16x8*)(lds + PG8_SA(b, h) + aoff + m * 2048 + k * 1024); } while (0)
; #define PG8_LDB(dst, b, h) do { _Pragma("unroll") for (int n = 0; n < 2; ++n) _Pragma("unroll") for (int k = 0; k < 2; ++k) dst[n][k] = *(const PG8_LAS bf16x8*)(lds + PG8_SB(b, h) + boff + n * 2048 + k * 1024); } while (0)
; #define PG8_WAIT_L(n) asm volatile("s_waitcnt lgkmcnt(" #n ")" ::: "memory")
; #define PG8_BAR __builtin_amdgcn_s_barrier()
; template <class Epi, class Sched, bool ALIGN_EPI = false, bool SP2 = false>
; __device__ __forceinline__ void gemm_phase(PG8_LAS unsigned char* lds, const Gemm g, const Sched& S, const Epi& E) {
;     ...
;             const bool last = (t == nt - 2);
;             const char* a1 = cA + (size_t)(t + 1) * kstep;
;             const char* a2 = last ? nA : cA + (size_t)(t + 2) * kstep; const char* b2 = last ? nB : cB + (size_t)(t + 2) * kstep;
;             const char* a3 = a2 + kstep; const char* b3 = b2 + kstep;
;             if (last && has_next) S.a_ready(nxt);
;             if constexpr (SP2) {
;             const int relax = __builtin_amdgcn_readfirstlane((t == 0 && ui > 0) ? 1 : 0);
;             PG8_LDB(B0, 0, 0); PG8_LDB(B1, 0, 1); PG8_SCHED; PG8_LDA(At, 0, 0); PG8_STAGE(PG8_SA(1, 1), a1 + hstep, voffA);
;             asm volatile("s_cmp_lg_u32 %0, 0\n\ts_cbranch_scc1 .Lrelax%=\n\ts_waitcnt vmcnt(8)\n.Lrelax%=:\n\ts_waitcnt vmcnt(%1)" :: "s"(relax), "n"(8 + Epi::NST) : "memory", "scc");
;             PG8_WAIT_L(0); PG8_BAR; PG8_MMA(0, 0, At, B0); PG8_MMA(0, 1, At, B1); PG8_BAR; PG8_SCHED;
;             PG8_LDA(At, 0, 1); PG8_STAGE(PG8_SB(0, 0), b2, voffB); PG8_STAGE(PG8_SB(0, 1), b2 + hstep, voffB); PG8_STAGE(PG8_SA(0, 0), a2, voffA);
;             asm volatile("s_cmp_lg_u32 %0, 0\n\ts_cbranch_scc1 .Lrelax%=\n\ts_waitcnt vmcnt(8)\n.Lrelax%=:\n\ts_waitcnt vmcnt(%1)" :: "s"(relax), "n"(8 + Epi::NST) : "memory", "scc");
;             PG8_WAIT_L(0); PG8_BAR; PG8_MMA(1, 0, At, B0); PG8_MMA(1, 1, At, B1); PG8_BAR; PG8_SCHED;
.LBB0_156:
	s_add_u32 s34, s28, s40
	s_addc_u32 s35, s29, s41
	s_add_u32 s70, s34, 0x40080
	s_addc_u32 s71, s35, 0
	s_add_u32 s34, s34, 0x100
	s_addc_u32 s35, s35, 0
	s_add_u32 s4, s67, s40
	s_addc_u32 s5, s68, s41
	s_cmpk_eq_i32 s40, 0x700
	s_cselect_b32 s35, s51, s35
	s_cselect_b32 s34, s65, s34
	s_cselect_b32 s5, s49, s5
	s_cselect_b32 s4, s66, s4
	ds_read_b128 v[60:63], v242
	ds_read_b128 v[68:71], v242 offset:1024
	ds_read_b128 v[76:79], v242 offset:2048
	ds_read_b128 v[80:83], v242 offset:3072
	ds_read_b128 v[88:91], v242 offset:16384
	ds_read_b128 v[164:167], v242 offset:17408
	ds_read_b128 v[168:171], v242 offset:18432
	ds_read_b128 v[172:175], v242 offset:19456
	s_add_i32 m0, s37, 0xc000
	ds_read_b128 v[194:197], v193
	ds_read_b128 v[198:201], v193 offset:1024
	ds_read_b128 v[202:205], v193 offset:2048
	ds_read_b128 v[206:209], v193 offset:3072
	ds_read_b128 v[210:213], v193 offset:4096
	ds_read_b128 v[214:217], v193 offset:5120
	ds_read_b128 v[234:237], v193 offset:6144
	ds_read_b128 v[238:241], v193 offset:7168
	global_load_lds_dwordx4 v160, s[70:71]
	s_add_i32 m0, s37, 0xe000
	s_nop 0
	global_load_lds_dwordx4 v162, s[70:71]
	s_waitcnt vmcnt(8)
	s_waitcnt lgkmcnt(0)
	s_setprio 1
	s_barrier
	v_mfma_f32_16x16x32_bf16 v[148:151], v[60:63], v[194:197], v[148:151]
	v_mfma_f32_16x16x32_bf16 v[144:147], v[76:79], v[194:197], v[144:147]
	v_mfma_f32_16x16x32_bf16 v[132:135], v[60:63], v[202:205], v[132:135]
	v_mfma_f32_16x16x32_bf16 v[124:127], v[76:79], v[202:205], v[124:127]
	v_mfma_f32_16x16x32_bf16 v[116:119], v[60:63], v[210:213], v[116:119]
	v_mfma_f32_16x16x32_bf16 v[108:111], v[76:79], v[210:213], v[108:111]
	v_mfma_f32_16x16x32_bf16 v[100:103], v[60:63], v[234:237], v[100:103]
	v_mfma_f32_16x16x32_bf16 v[92:95], v[76:79], v[234:237], v[92:95]
	v_mfma_f32_16x16x32_bf16 v[148:151], v[68:71], v[198:201], v[148:151]
	v_mfma_f32_16x16x32_bf16 v[144:147], v[80:83], v[198:201], v[144:147]
	v_mfma_f32_16x16x32_bf16 v[132:135], v[68:71], v[206:209], v[132:135]
	v_mfma_f32_16x16x32_bf16 v[124:127], v[80:83], v[206:209], v[124:127]
	v_mfma_f32_16x16x32_bf16 v[116:119], v[68:71], v[214:217], v[116:119]
	v_mfma_f32_16x16x32_bf16 v[108:111], v[80:83], v[214:217], v[108:111]
	v_mfma_f32_16x16x32_bf16 v[100:103], v[68:71], v[238:241], v[100:103]
	v_mfma_f32_16x16x32_bf16 v[92:95], v[80:83], v[238:241], v[92:95]
	s_setprio 0
	s_setprio 1
	v_mfma_f32_16x16x32_bf16 v[140:143], v[88:91], v[194:197], v[140:143]
	v_mfma_f32_16x16x32_bf16 v[136:139], v[168:171], v[194:197], v[136:139]
	v_mfma_f32_16x16x32_bf16 v[128:131], v[88:91], v[202:205], v[128:131]
	v_mfma_f32_16x16x32_bf16 v[120:123], v[168:171], v[202:205], v[120:123]
	v_mfma_f32_16x16x32_bf16 v[112:115], v[88:91], v[210:213], v[112:115]
	v_mfma_f32_16x16x32_bf16 v[104:107], v[168:171], v[210:213], v[104:107]
	v_mfma_f32_16x16x32_bf16 v[96:99], v[88:91], v[234:237], v[96:99]
	v_mfma_f32_16x16x32_bf16 v[84:87], v[168:171], v[234:237], v[84:87]
	v_mfma_f32_16x16x32_bf16 v[140:143], v[164:167], v[198:201], v[140:143]
	v_mfma_f32_16x16x32_bf16 v[136:139], v[172:175], v[198:201], v[136:139]
	v_mfma_f32_16x16x32_bf16 v[128:131], v[164:167], v[206:209], v[128:131]
	v_mfma_f32_16x16x32_bf16 v[120:123], v[172:175], v[206:209], v[120:123]
	v_mfma_f32_16x16x32_bf16 v[112:115], v[164:167], v[214:217], v[112:115]
	v_mfma_f32_16x16x32_bf16 v[104:107], v[172:175], v[214:217], v[104:107]
	v_mfma_f32_16x16x32_bf16 v[96:99], v[164:167], v[238:241], v[96:99]
	s_setprio 0
	v_mfma_f32_16x16x32_bf16 v[84:87], v[172:175], v[238:241], v[84:87]
	s_barrier
	s_add_i32 m0, s2, 0x10000
	ds_read_b128 v[194:197], v193 offset:16384
	ds_read_b128 v[198:201], v193 offset:17408
	ds_read_b128 v[202:205], v193 offset:18432
	ds_read_b128 v[206:209], v193 offset:19456
	ds_read_b128 v[210:213], v193 offset:20480
	ds_read_b128 v[214:217], v193 offset:21504
	ds_read_b128 v[234:237], v193 offset:22528
	ds_read_b128 v[238:241], v193 offset:23552
	global_load_lds_dwordx4 v176, s[4:5]
	s_add_i32 m0, s2, 0x12000
	s_add_u32 s70, s4, 0x40000
	s_addc_u32 s71, s5, 0
	global_load_lds_dwordx4 v156, s[4:5]
	s_add_i32 m0, s2, 0x14000
	s_nop 0
	global_load_lds_dwordx4 v176, s[70:71]
	s_add_i32 m0, s2, 0x16000
	s_nop 0
	global_load_lds_dwordx4 v156, s[70:71]
	s_mov_b32 m0, s37
	s_nop 0
	global_load_lds_dwordx4 v152, s[34:35]
	s_mov_b32 m0, s57
	s_nop 0
	global_load_lds_dwordx4 v154, s[34:35]
	s_waitcnt vmcnt(8)
	s_waitcnt lgkmcnt(0)
	s_setprio 1
	s_barrier
	v_mfma_f32_16x16x32_bf16 v[72:75], v[60:63], v[194:197], v[72:75]
	v_mfma_f32_16x16x32_bf16 v[52:55], v[76:79], v[194:197], v[52:55]
	v_mfma_f32_16x16x32_bf16 v[44:47], v[60:63], v[202:205], v[44:47]
	v_mfma_f32_16x16x32_bf16 v[36:39], v[76:79], v[202:205], v[36:39]
	v_mfma_f32_16x16x32_bf16 v[28:31], v[60:63], v[210:213], v[28:31]
	v_mfma_f32_16x16x32_bf16 v[20:23], v[76:79], v[210:213], v[20:23]
	v_mfma_f32_16x16x32_bf16 v[12:15], v[60:63], v[234:237], v[12:15]
	v_mfma_f32_16x16x32_bf16 v[4:7], v[76:79], v[234:237], v[4:7]
	v_mfma_f32_16x16x32_bf16 v[72:75], v[68:71], v[198:201], v[72:75]
	v_mfma_f32_16x16x32_bf16 v[52:55], v[80:83], v[198:201], v[52:55]
	v_mfma_f32_16x16x32_bf16 v[44:47], v[68:71], v[206:209], v[44:47]
	v_mfma_f32_16x16x32_bf16 v[36:39], v[80:83], v[206:209], v[36:39]
	v_mfma_f32_16x16x32_bf16 v[28:31], v[68:71], v[214:217], v[28:31]
	v_mfma_f32_16x16x32_bf16 v[20:23], v[80:83], v[214:217], v[20:23]
	v_mfma_f32_16x16x32_bf16 v[12:15], v[68:71], v[238:241], v[12:15]
	v_mfma_f32_16x16x32_bf16 v[4:7], v[80:83], v[238:241], v[4:7]
	s_setprio 0
	s_setprio 1
	v_mfma_f32_16x16x32_bf16 v[48:51], v[168:171], v[194:197], v[48:51]
	v_mfma_f32_16x16x32_bf16 v[40:43], v[88:91], v[202:205], v[40:43]
	v_mfma_f32_16x16x32_bf16 v[32:35], v[168:171], v[202:205], v[32:35]
	v_mfma_f32_16x16x32_bf16 v[24:27], v[88:91], v[210:213], v[24:27]
	v_mfma_f32_16x16x32_bf16 v[16:19], v[168:171], v[210:213], v[16:19]
	v_mfma_f32_16x16x32_bf16 v[8:11], v[88:91], v[234:237], v[8:11]
	v_mfma_f32_16x16x32_bf16 v[0:3], v[168:171], v[234:237], v[0:3]
	v_mfma_f32_16x16x32_bf16 v[60:63], v[88:91], v[194:197], v[64:67]
	v_mfma_f32_16x16x32_bf16 v[48:51], v[172:175], v[198:201], v[48:51]
	v_mfma_f32_16x16x32_bf16 v[40:43], v[164:167], v[206:209], v[40:43]
	v_mfma_f32_16x16x32_bf16 v[32:35], v[172:175], v[206:209], v[32:35]
	v_mfma_f32_16x16x32_bf16 v[24:27], v[164:167], v[214:217], v[24:27]
	v_mfma_f32_16x16x32_bf16 v[16:19], v[172:175], v[214:217], v[16:19]
	v_mfma_f32_16x16x32_bf16 v[8:11], v[164:167], v[238:241], v[8:11]
	v_mfma_f32_16x16x32_bf16 v[0:3], v[172:175], v[238:241], v[0:3]
	s_setprio 0
	v_mfma_f32_16x16x32_bf16 v[60:63], v[164:167], v[198:201], v[60:63]
	s_barrier
; #define PG8_STAGE(bufoff, gbase, voff) do { _Pragma("unroll") for (int _i = 0; _i < 2; ++_i) \
;         __builtin_amdgcn_global_load_lds((const unsigned*)((const char*)(gbase) + (voff)[_i]), (PG8_LAS unsigned*)(lds + (bufoff) + ldsw + _i * 8192), 16, 0, 0); } while (0)
; #define PG8_LDA(dst, b, h) do { _Pragma("unroll") for (int m = 0; m < 4; ++m) _Pragma("unroll") for (int k = 0; k < 2; ++k) dst[m][k] = *(const PG8_LAS bf16x8*)(lds + PG8_SA(b, h) + aoff + m * 2048 + k * 1024); } while (0)
; #define PG8_LDB(dst, b, h) do { _Pragma("unroll") for (int n = 0; n < 2; ++n) _Pragma("unroll") for (int k = 0; k < 2; ++k) dst[n][k] = *(const PG8_LAS bf16x8*)(lds + PG8_SB(b, h) + boff + n * 2048 + k * 1024); } while (0)
; #define PG8_MMA(ai, bj, At, Bt) do { __builtin_amdgcn_s_setprio(1); _Pragma("unroll") for (int m = 0; m < 4; ++m) _Pragma("unroll") for (int n = 0; n < 2; ++n) _Pragma("unroll") for (int k = 0; k < 2; ++k) \
;         acc[ai][bj][m][n] = __builtin_amdgcn_mfma_f32_16x16x32_bf16(Bt[n][k], At[m][k], acc[ai][bj][m][n], 0, 0, 0); __builtin_amdgcn_s_setprio(0); } while (0)
; #define PG8_WAIT_V(n) asm volatile("s_waitcnt vmcnt(" #n ")" ::: "memory")
; #define PG8_WAIT_L(n) asm volatile("s_waitcnt lgkmcnt(" #n ")" ::: "memory")
; #define PG8_BAR __builtin_amdgcn_s_barrier()
; #define PG8_SCHED __builtin_amdgcn_sched_barrier(0)
; template <class Epi, class Sched, bool ALIGN_EPI = false, bool SP2 = false>
; __device__ __forceinline__ void gemm_phase(PG8_LAS unsigned char* lds, const Gemm g, const Sched& S, const Epi& E) {
;     ...
;             PG8_LDB(B0, 1, 0); PG8_LDB(B1, 1, 1); PG8_SCHED; PG8_LDA(At, 1, 0); PG8_STAGE(PG8_SA(0, 1), a2 + hstep, voffA);
;             PG8_WAIT_V(8); PG8_WAIT_L(0); PG8_BAR; PG8_MMA(0, 0, At, B0); PG8_MMA(0, 1, At, B1); PG8_BAR; PG8_SCHED;
;             PG8_LDA(At, 1, 1); PG8_STAGE(PG8_SB(1, 0), b3, voffB); PG8_STAGE(PG8_SB(1, 1), b3 + hstep, voffB); PG8_STAGE(PG8_SA(1, 0), a3, voffA);
;             PG8_WAIT_V(8); PG8_WAIT_L(0); PG8_BAR; PG8_MMA(1, 0, At, B0); PG8_MMA(1, 1, At, B1); PG8_BAR; PG8_SCHED;
	ds_read_b128 v[64:67], v242 offset:32768
	ds_read_b128 v[68:71], v242 offset:33792
	ds_read_b128 v[76:79], v242 offset:34816
	ds_read_b128 v[80:83], v242 offset:35840
	ds_read_b128 v[88:91], v242 offset:49152
	ds_read_b128 v[164:167], v242 offset:50176
	ds_read_b128 v[168:171], v242 offset:51200
	ds_read_b128 v[172:175], v242 offset:52224
	s_add_u32 s34, s34, 0x40000
	s_addc_u32 s35, s35, 0
	s_mov_b32 m0, s58
	ds_read_b128 v[194:197], v193 offset:32768
	ds_read_b128 v[198:201], v193 offset:33792
	ds_read_b128 v[202:205], v193 offset:34816
	ds_read_b128 v[206:209], v193 offset:35840
	ds_read_b128 v[210:213], v193 offset:36864
	ds_read_b128 v[214:217], v193 offset:37888
	ds_read_b128 v[234:237], v193 offset:38912
	ds_read_b128 v[238:241], v193 offset:39936
	global_load_lds_dwordx4 v152, s[34:35]
	s_mov_b32 m0, s59
	s_nop 0
	global_load_lds_dwordx4 v154, s[34:35]
	s_waitcnt vmcnt(8)
	s_waitcnt lgkmcnt(0)
	s_setprio 1
	s_barrier
	v_mfma_f32_16x16x32_bf16 v[148:151], v[64:67], v[194:197], v[148:151]
	v_mfma_f32_16x16x32_bf16 v[144:147], v[76:79], v[194:197], v[144:147]
	v_mfma_f32_16x16x32_bf16 v[132:135], v[64:67], v[202:205], v[132:135]
	v_mfma_f32_16x16x32_bf16 v[124:127], v[76:79], v[202:205], v[124:127]
	v_mfma_f32_16x16x32_bf16 v[116:119], v[64:67], v[210:213], v[116:119]
	v_mfma_f32_16x16x32_bf16 v[108:111], v[76:79], v[210:213], v[108:111]
	v_mfma_f32_16x16x32_bf16 v[100:103], v[64:67], v[234:237], v[100:103]
	v_mfma_f32_16x16x32_bf16 v[92:95], v[76:79], v[234:237], v[92:95]
	v_mfma_f32_16x16x32_bf16 v[148:151], v[68:71], v[198:201], v[148:151]
	v_mfma_f32_16x16x32_bf16 v[144:147], v[80:83], v[198:201], v[144:147]
	v_mfma_f32_16x16x32_bf16 v[132:135], v[68:71], v[206:209], v[132:135]
	v_mfma_f32_16x16x32_bf16 v[124:127], v[80:83], v[206:209], v[124:127]
	v_mfma_f32_16x16x32_bf16 v[116:119], v[68:71], v[214:217], v[116:119]
	v_mfma_f32_16x16x32_bf16 v[108:111], v[80:83], v[214:217], v[108:111]
	v_mfma_f32_16x16x32_bf16 v[100:103], v[68:71], v[238:241], v[100:103]
	v_mfma_f32_16x16x32_bf16 v[92:95], v[80:83], v[238:241], v[92:95]
	s_setprio 0
	s_setprio 1
	v_mfma_f32_16x16x32_bf16 v[140:143], v[88:91], v[194:197], v[140:143]
	v_mfma_f32_16x16x32_bf16 v[136:139], v[168:171], v[194:197], v[136:139]
	v_mfma_f32_16x16x32_bf16 v[128:131], v[88:91], v[202:205], v[128:131]
	v_mfma_f32_16x16x32_bf16 v[120:123], v[168:171], v[202:205], v[120:123]
	v_mfma_f32_16x16x32_bf16 v[112:115], v[88:91], v[210:213], v[112:115]
	v_mfma_f32_16x16x32_bf16 v[104:107], v[168:171], v[210:213], v[104:107]
	v_mfma_f32_16x16x32_bf16 v[96:99], v[88:91], v[234:237], v[96:99]
	v_mfma_f32_16x16x32_bf16 v[84:87], v[168:171], v[234:237], v[84:87]
	v_mfma_f32_16x16x32_bf16 v[140:143], v[164:167], v[198:201], v[140:143]
	v_mfma_f32_16x16x32_bf16 v[136:139], v[172:175], v[198:201], v[136:139]
	v_mfma_f32_16x16x32_bf16 v[128:131], v[164:167], v[206:209], v[128:131]
	v_mfma_f32_16x16x32_bf16 v[120:123], v[172:175], v[206:209], v[120:123]
	v_mfma_f32_16x16x32_bf16 v[112:115], v[164:167], v[214:217], v[112:115]
	v_mfma_f32_16x16x32_bf16 v[104:107], v[172:175], v[214:217], v[104:107]
	v_mfma_f32_16x16x32_bf16 v[96:99], v[164:167], v[238:241], v[96:99]
	s_setprio 0
	v_mfma_f32_16x16x32_bf16 v[84:87], v[172:175], v[238:241], v[84:87]
	s_barrier
	s_add_i32 m0, s2, 0x18000
	s_add_u32 s4, s4, 0x80
	s_addc_u32 s5, s5, 0
	ds_read_b128 v[194:197], v193 offset:49152
	ds_read_b128 v[198:201], v193 offset:50176
	ds_read_b128 v[202:205], v193 offset:51200
	ds_read_b128 v[206:209], v193 offset:52224
	ds_read_b128 v[210:213], v193 offset:53248
	ds_read_b128 v[214:217], v193 offset:54272
	ds_read_b128 v[234:237], v193 offset:55296
	ds_read_b128 v[238:241], v193 offset:56320
	global_load_lds_dwordx4 v176, s[4:5]
	s_add_i32 m0, s2, 0x1a000
	s_add_u32 s70, s4, 0x40000
	s_addc_u32 s71, s5, 0
	global_load_lds_dwordx4 v156, s[4:5]
	s_add_i32 m0, s2, 0x1c000
	s_sub_u32 s34, s34, 0x40000
	s_subb_u32 s35, s35, 0
	global_load_lds_dwordx4 v176, s[70:71]
	s_add_i32 m0, s2, 0x1e000
	s_add_u32 s34, s34, 0x80
	s_addc_u32 s35, s35, 0
	global_load_lds_dwordx4 v156, s[70:71]
	s_mov_b32 m0, s60
	s_nop 0
	global_load_lds_dwordx4 v152, s[34:35]
	s_mov_b32 m0, s61
	s_nop 0
	global_load_lds_dwordx4 v154, s[34:35]
	s_waitcnt vmcnt(8)
	s_waitcnt lgkmcnt(0)
	s_setprio 1
	s_barrier
	v_mfma_f32_16x16x32_bf16 v[72:75], v[64:67], v[194:197], v[72:75]
	v_mfma_f32_16x16x32_bf16 v[52:55], v[76:79], v[194:197], v[52:55]
	v_mfma_f32_16x16x32_bf16 v[44:47], v[64:67], v[202:205], v[44:47]
	v_mfma_f32_16x16x32_bf16 v[36:39], v[76:79], v[202:205], v[36:39]
	v_mfma_f32_16x16x32_bf16 v[28:31], v[64:67], v[210:213], v[28:31]
	v_mfma_f32_16x16x32_bf16 v[20:23], v[76:79], v[210:213], v[20:23]
	v_mfma_f32_16x16x32_bf16 v[12:15], v[64:67], v[234:237], v[12:15]
	v_mfma_f32_16x16x32_bf16 v[4:7], v[76:79], v[234:237], v[4:7]
	v_mfma_f32_16x16x32_bf16 v[72:75], v[68:71], v[198:201], v[72:75]
	v_mfma_f32_16x16x32_bf16 v[52:55], v[80:83], v[198:201], v[52:55]
	v_mfma_f32_16x16x32_bf16 v[44:47], v[68:71], v[206:209], v[44:47]
	v_mfma_f32_16x16x32_bf16 v[36:39], v[80:83], v[206:209], v[36:39]
	v_mfma_f32_16x16x32_bf16 v[28:31], v[68:71], v[214:217], v[28:31]
	v_mfma_f32_16x16x32_bf16 v[20:23], v[80:83], v[214:217], v[20:23]
	v_mfma_f32_16x16x32_bf16 v[12:15], v[68:71], v[238:241], v[12:15]
	v_mfma_f32_16x16x32_bf16 v[4:7], v[80:83], v[238:241], v[4:7]
	s_setprio 0
	s_setprio 1
	v_mfma_f32_16x16x32_bf16 v[60:63], v[88:91], v[194:197], v[60:63]
	v_mfma_f32_16x16x32_bf16 v[48:51], v[168:171], v[194:197], v[48:51]
	v_mfma_f32_16x16x32_bf16 v[40:43], v[88:91], v[202:205], v[40:43]
	v_mfma_f32_16x16x32_bf16 v[32:35], v[168:171], v[202:205], v[32:35]
	v_mfma_f32_16x16x32_bf16 v[24:27], v[88:91], v[210:213], v[24:27]
	v_mfma_f32_16x16x32_bf16 v[16:19], v[168:171], v[210:213], v[16:19]
	v_mfma_f32_16x16x32_bf16 v[8:11], v[88:91], v[234:237], v[8:11]
	v_mfma_f32_16x16x32_bf16 v[0:3], v[168:171], v[234:237], v[0:3]
	v_mfma_f32_16x16x32_bf16 v[64:67], v[164:167], v[198:201], v[60:63]
	v_mfma_f32_16x16x32_bf16 v[48:51], v[172:175], v[198:201], v[48:51]
	v_mfma_f32_16x16x32_bf16 v[40:43], v[164:167], v[206:209], v[40:43]
	v_mfma_f32_16x16x32_bf16 v[32:35], v[172:175], v[206:209], v[32:35]
	v_mfma_f32_16x16x32_bf16 v[24:27], v[164:167], v[214:217], v[24:27]
	v_mfma_f32_16x16x32_bf16 v[16:19], v[172:175], v[214:217], v[16:19]
	v_mfma_f32_16x16x32_bf16 v[8:11], v[164:167], v[238:241], v[8:11]
	s_setprio 0
	v_mfma_f32_16x16x32_bf16 v[0:3], v[172:175], v[238:241], v[0:3]
	s_barrier
	s_add_i32 s69, s69, 2
	s_add_u32 s40, s40, 0x100
	s_addc_u32 s41, s41, 0
	s_cmp_gt_u32 s69, 13
	s_cbranch_scc0 .LBB0_156

; #define PG8_STAGE(bufoff, gbase, voff) do { _Pragma("unroll") for (int _i = 0; _i < 2; ++_i) \
;         __builtin_amdgcn_global_load_lds((const unsigned*)((const char*)(gbase) + (voff)[_i]), (PG8_LAS unsigned*)(lds + (bufoff) + ldsw + _i * 8192), 16, 0, 0); } while (0)
; #define PG8_LDA(dst, b, h) do { _Pragma("unroll") for (int m = 0; m < 4; ++m) _Pragma("unroll") for (int k = 0; k < 2; ++k) dst[m][k] = *(const PG8_LAS bf16x8*)(lds + PG8_SA(b, h) + aoff + m * 2048 + k * 1024); } while (0)
; #define PG8_LDB(dst, b, h) do { _Pragma("unroll") for (int n = 0; n < 2; ++n) _Pragma("unroll") for (int k = 0; k < 2; ++k) dst[n][k] = *(const PG8_LAS bf16x8*)(lds + PG8_SB(b, h) + boff + n * 2048 + k * 1024); } while (0)
; #define PG8_MMA(ai, bj, At, Bt) do { __builtin_amdgcn_s_setprio(1); _Pragma("unroll") for (int m = 0; m < 4; ++m) _Pragma("unroll") for (int n = 0; n < 2; ++n) _Pragma("unroll") for (int k = 0; k < 2; ++k) \
;         acc[ai][bj][m][n] = __builtin_amdgcn_mfma_f32_16x16x32_bf16(Bt[n][k], At[m][k], acc[ai][bj][m][n], 0, 0, 0); __builtin_amdgcn_s_setprio(0); } while (0)
; #define PG8_WAIT_L(n) asm volatile("s_waitcnt lgkmcnt(" #n ")" ::: "memory")
; #define PG8_BAR __builtin_amdgcn_s_barrier()
; #define PG8_SCHED __builtin_amdgcn_sched_barrier(0)
; template <class Epi, class Sched, bool ALIGN_EPI = false, bool SP2 = false>
; __device__ __forceinline__ void gemm_phase(PG8_LAS unsigned char* lds, const Gemm g, const Sched& S, const Epi& E) {
;     ...
;             PG8_LDB(B0, 0, 0); PG8_LDB(B1, 0, 1); PG8_SCHED; PG8_LDA(At, 0, 0); PG8_STAGE(PG8_SA(1, 1), a1 + hstep, voffA);
;             asm volatile("s_cmp_lg_u32 %0, 0\n\ts_cbranch_scc1 .Lrelax%=\n\ts_waitcnt vmcnt(8)\n.Lrelax%=:\n\ts_waitcnt vmcnt(%1)" :: "s"(relax), "n"(8 + Epi::NST) : "memory", "scc");
;             PG8_WAIT_L(0); PG8_BAR; PG8_MMA(0, 0, At, B0); PG8_MMA(0, 1, At, B1); PG8_BAR; PG8_SCHED;
;             PG8_LDA(At, 0, 1); PG8_STAGE(PG8_SB(0, 0), b2, voffB); PG8_STAGE(PG8_SB(0, 1), b2 + hstep, voffB); PG8_STAGE(PG8_SA(0, 0), a2, voffA);
;             asm volatile("s_cmp_lg_u32 %0, 0\n\ts_cbranch_scc1 .Lrelax%=\n\ts_waitcnt vmcnt(8)\n.Lrelax%=:\n\ts_waitcnt vmcnt(%1)" :: "s"(relax), "n"(8 + Epi::NST) : "memory", "scc");
;             PG8_WAIT_L(0); PG8_BAR; PG8_MMA(1, 0, At, B0); PG8_MMA(1, 1, At, B1); PG8_BAR; PG8_SCHED;
.Lmy_residp_rx1:
	s_waitcnt vmcnt(32)
	s_waitcnt lgkmcnt(0)
	s_setprio 1
	s_barrier
	v_mfma_f32_16x16x32_bf16 v[140:143], v[68:71], v[164:167], 0
	v_mfma_f32_16x16x32_bf16 v[136:139], v[76:79], v[164:167], 0
	v_mfma_f32_16x16x32_bf16 v[124:127], v[68:71], v[172:175], 0
	v_mfma_f32_16x16x32_bf16 v[120:123], v[76:79], v[172:175], 0
	v_mfma_f32_16x16x32_bf16 v[108:111], v[68:71], v[200:203], 0
	v_mfma_f32_16x16x32_bf16 v[104:107], v[76:79], v[200:203], 0
	v_mfma_f32_16x16x32_bf16 v[92:95], v[68:71], v[208:211], 0
	v_mfma_f32_16x16x32_bf16 v[88:91], v[76:79], v[208:211], 0
	v_mfma_f32_16x16x32_bf16 v[140:143], v[72:75], v[168:171], v[140:143]
	v_mfma_f32_16x16x32_bf16 v[136:139], v[144:147], v[168:171], v[136:139]
	v_mfma_f32_16x16x32_bf16 v[124:127], v[72:75], v[196:199], v[124:127]
	v_mfma_f32_16x16x32_bf16 v[120:123], v[144:147], v[196:199], v[120:123]
	v_mfma_f32_16x16x32_bf16 v[108:111], v[72:75], v[204:207], v[108:111]
	v_mfma_f32_16x16x32_bf16 v[104:107], v[144:147], v[204:207], v[104:107]
	v_mfma_f32_16x16x32_bf16 v[92:95], v[72:75], v[212:215], v[92:95]
	v_mfma_f32_16x16x32_bf16 v[88:91], v[144:147], v[212:215], v[88:91]
	s_setprio 0
	s_setprio 1
	v_mfma_f32_16x16x32_bf16 v[132:135], v[148:151], v[164:167], 0
	v_mfma_f32_16x16x32_bf16 v[128:131], v[156:159], v[164:167], 0
	v_mfma_f32_16x16x32_bf16 v[116:119], v[148:151], v[172:175], 0
	v_mfma_f32_16x16x32_bf16 v[112:115], v[156:159], v[172:175], 0
	v_mfma_f32_16x16x32_bf16 v[100:103], v[148:151], v[200:203], 0
	v_mfma_f32_16x16x32_bf16 v[96:99], v[156:159], v[200:203], 0
	v_mfma_f32_16x16x32_bf16 v[84:87], v[148:151], v[208:211], 0
	v_mfma_f32_16x16x32_bf16 v[80:83], v[156:159], v[208:211], 0
	v_mfma_f32_16x16x32_bf16 v[132:135], v[152:155], v[168:171], v[132:135]
	v_mfma_f32_16x16x32_bf16 v[128:131], v[160:163], v[168:171], v[128:131]
	v_mfma_f32_16x16x32_bf16 v[116:119], v[152:155], v[196:199], v[116:119]
	v_mfma_f32_16x16x32_bf16 v[112:115], v[160:163], v[196:199], v[112:115]
	v_mfma_f32_16x16x32_bf16 v[100:103], v[152:155], v[204:207], v[100:103]
	v_mfma_f32_16x16x32_bf16 v[96:99], v[160:163], v[204:207], v[96:99]
	v_mfma_f32_16x16x32_bf16 v[84:87], v[152:155], v[212:215], v[84:87]
	s_setprio 0
	v_mfma_f32_16x16x32_bf16 v[80:83], v[160:163], v[212:215], v[80:83]
	s_barrier
	s_add_i32 m0, s35, 0x10000
	ds_read_b128 v[164:167], v236 offset:16384
	ds_read_b128 v[168:171], v236 offset:17408
	ds_read_b128 v[172:175], v236 offset:18432
	ds_read_b128 v[196:199], v236 offset:19456
	ds_read_b128 v[200:203], v236 offset:20480
	ds_read_b128 v[204:207], v236 offset:21504
	ds_read_b128 v[208:211], v236 offset:22528
	ds_read_b128 v[212:215], v236 offset:23552
	global_load_lds_dwordx4 v176, s[74:75]
	s_add_i32 m0, s35, 0x12000
	s_add_u32 s76, s74, s22
	s_addc_u32 s77, s75, 0
	global_load_lds_dwordx4 v190, s[74:75]
	s_add_i32 m0, s35, 0x14000
	s_nop 0
	global_load_lds_dwordx4 v176, s[76:77]
	s_add_i32 m0, s35, 0x16000
	s_nop 0
	global_load_lds_dwordx4 v190, s[76:77]
	s_mov_b32 m0, s36
	s_nop 0
	global_load_lds_dwordx4 v186, s[4:5]
	s_mov_b32 m0, s37
	s_nop 0
	global_load_lds_dwordx4 v188, s[4:5]
	s_cmp_lg_u32 s30, 0
	s_cbranch_scc1 .Lmy_residp_rx2
	s_waitcnt vmcnt(8)
.Lmy_residp_rx2:
	s_waitcnt vmcnt(32)
	s_waitcnt lgkmcnt(0)
	s_setprio 1
	s_barrier
	v_mfma_f32_16x16x32_bf16 v[60:63], v[68:71], v[164:167], 0
	v_mfma_f32_16x16x32_bf16 v[56:59], v[76:79], v[164:167], 0
	v_mfma_f32_16x16x32_bf16 v[44:47], v[68:71], v[172:175], 0
	v_mfma_f32_16x16x32_bf16 v[40:43], v[76:79], v[172:175], 0
	v_mfma_f32_16x16x32_bf16 v[28:31], v[68:71], v[200:203], 0
	v_mfma_f32_16x16x32_bf16 v[24:27], v[76:79], v[200:203], 0
	v_mfma_f32_16x16x32_bf16 v[12:15], v[68:71], v[208:211], 0
	v_mfma_f32_16x16x32_bf16 v[8:11], v[76:79], v[208:211], 0
	v_mfma_f32_16x16x32_bf16 v[60:63], v[72:75], v[168:171], v[60:63]
	v_mfma_f32_16x16x32_bf16 v[56:59], v[144:147], v[168:171], v[56:59]
	v_mfma_f32_16x16x32_bf16 v[44:47], v[72:75], v[196:199], v[44:47]
	v_mfma_f32_16x16x32_bf16 v[40:43], v[144:147], v[196:199], v[40:43]
	v_mfma_f32_16x16x32_bf16 v[28:31], v[72:75], v[204:207], v[28:31]
	v_mfma_f32_16x16x32_bf16 v[24:27], v[144:147], v[204:207], v[24:27]
	v_mfma_f32_16x16x32_bf16 v[12:15], v[72:75], v[212:215], v[12:15]
	v_mfma_f32_16x16x32_bf16 v[8:11], v[144:147], v[212:215], v[8:11]
	s_setprio 0
	s_setprio 1
	v_mfma_f32_16x16x32_bf16 v[52:55], v[148:151], v[164:167], 0
	v_mfma_f32_16x16x32_bf16 v[48:51], v[156:159], v[164:167], 0
	v_mfma_f32_16x16x32_bf16 v[36:39], v[148:151], v[172:175], 0
	v_mfma_f32_16x16x32_bf16 v[32:35], v[156:159], v[172:175], 0
	v_mfma_f32_16x16x32_bf16 v[20:23], v[148:151], v[200:203], 0
	v_mfma_f32_16x16x32_bf16 v[16:19], v[156:159], v[200:203], 0
	v_mfma_f32_16x16x32_bf16 v[4:7], v[148:151], v[208:211], 0
	v_mfma_f32_16x16x32_bf16 v[0:3], v[156:159], v[208:211], 0
	v_mfma_f32_16x16x32_bf16 v[52:55], v[152:155], v[168:171], v[52:55]
	v_mfma_f32_16x16x32_bf16 v[48:51], v[160:163], v[168:171], v[48:51]
	v_mfma_f32_16x16x32_bf16 v[36:39], v[152:155], v[196:199], v[36:39]
	v_mfma_f32_16x16x32_bf16 v[32:35], v[160:163], v[196:199], v[32:35]
	v_mfma_f32_16x16x32_bf16 v[20:23], v[152:155], v[204:207], v[20:23]
	v_mfma_f32_16x16x32_bf16 v[16:19], v[160:163], v[204:207], v[16:19]
	v_mfma_f32_16x16x32_bf16 v[4:7], v[152:155], v[212:215], v[4:7]
	s_setprio 0
	v_mfma_f32_16x16x32_bf16 v[0:3], v[160:163], v[212:215], v[0:3]
	s_barrier
; #define PG8_STAGE(bufoff, gbase, voff) do { _Pragma("unroll") for (int _i = 0; _i < 2; ++_i) \
;         __builtin_amdgcn_global_load_lds((const unsigned*)((const char*)(gbase) + (voff)[_i]), (PG8_LAS unsigned*)(lds + (bufoff) + ldsw + _i * 8192), 16, 0, 0); } while (0)
; #define PG8_LDA(dst, b, h) do { _Pragma("unroll") for (int m = 0; m < 4; ++m) _Pragma("unroll") for (int k = 0; k < 2; ++k) dst[m][k] = *(const PG8_LAS bf16x8*)(lds + PG8_SA(b, h) + aoff + m * 2048 + k * 1024); } while (0)
; #define PG8_LDB(dst, b, h) do { _Pragma("unroll") for (int n = 0; n < 2; ++n) _Pragma("unroll") for (int k = 0; k < 2; ++k) dst[n][k] = *(const PG8_LAS bf16x8*)(lds + PG8_SB(b, h) + boff + n * 2048 + k * 1024); } while (0)
; #define PG8_MMA(ai, bj, At, Bt) do { __builtin_amdgcn_s_setprio(1); _Pragma("unroll") for (int m = 0; m < 4; ++m) _Pragma("unroll") for (int n = 0; n < 2; ++n) _Pragma("unroll") for (int k = 0; k < 2; ++k) \
;         acc[ai][bj][m][n] = __builtin_amdgcn_mfma_f32_16x16x32_bf16(Bt[n][k], At[m][k], acc[ai][bj][m][n], 0, 0, 0); __builtin_amdgcn_s_setprio(0); } while (0)
; #define PG8_WAIT_V(n) asm volatile("s_waitcnt vmcnt(" #n ")" ::: "memory")
; #define PG8_WAIT_L(n) asm volatile("s_waitcnt lgkmcnt(" #n ")" ::: "memory")
; #define PG8_BAR __builtin_amdgcn_s_barrier()
; #define PG8_SCHED __builtin_amdgcn_sched_barrier(0)
; template <class Epi, class Sched, bool ALIGN_EPI = false, bool SP2 = false>
; __device__ __forceinline__ void gemm_phase(PG8_LAS unsigned char* lds, const Gemm g, const Sched& S, const Epi& E) {
;     ...
;             PG8_LDB(B0, 1, 0); PG8_LDB(B1, 1, 1); PG8_SCHED; PG8_LDA(At, 1, 0); PG8_STAGE(PG8_SA(0, 1), a2 + hstep, voffA);
;             PG8_WAIT_V(8); PG8_WAIT_L(0); PG8_BAR; PG8_MMA(0, 0, At, B0); PG8_MMA(0, 1, At, B1); PG8_BAR; PG8_SCHED;
;             PG8_LDA(At, 1, 1); PG8_STAGE(PG8_SB(1, 0), b3, voffB); PG8_STAGE(PG8_SB(1, 1), b3 + hstep, voffB); PG8_STAGE(PG8_SA(1, 0), a3, voffA);
;             PG8_WAIT_V(8); PG8_WAIT_L(0); PG8_BAR; PG8_MMA(1, 0, At, B0); PG8_MMA(1, 1, At, B1); PG8_BAR; PG8_SCHED;
	ds_read_b128 v[68:71], v216 offset:32768
	ds_read_b128 v[72:75], v216 offset:33792
	ds_read_b128 v[76:79], v216 offset:34816
	ds_read_b128 v[144:147], v216 offset:35840
	ds_read_b128 v[148:151], v216 offset:49152
	ds_read_b128 v[152:155], v216 offset:50176
	ds_read_b128 v[156:159], v216 offset:51200
	ds_read_b128 v[160:163], v216 offset:52224
	s_add_u32 s4, s4, s22
	s_addc_u32 s5, s5, 0
	s_mov_b32 m0, s58
	ds_read_b128 v[164:167], v236 offset:32768
	ds_read_b128 v[168:171], v236 offset:33792
	ds_read_b128 v[172:175], v236 offset:34816
	ds_read_b128 v[196:199], v236 offset:35840
	ds_read_b128 v[200:203], v236 offset:36864
	ds_read_b128 v[204:207], v236 offset:37888
	ds_read_b128 v[208:211], v236 offset:38912
	ds_read_b128 v[212:215], v236 offset:39936
	global_load_lds_dwordx4 v186, s[4:5]
	s_mov_b32 m0, s59
	s_nop 0
	global_load_lds_dwordx4 v188, s[4:5]
	s_waitcnt vmcnt(8)
	s_waitcnt lgkmcnt(0)
	s_setprio 1
	s_barrier
	v_mfma_f32_16x16x32_bf16 v[140:143], v[68:71], v[164:167], v[140:143]
	v_mfma_f32_16x16x32_bf16 v[136:139], v[76:79], v[164:167], v[136:139]
	v_mfma_f32_16x16x32_bf16 v[124:127], v[68:71], v[172:175], v[124:127]
	v_mfma_f32_16x16x32_bf16 v[120:123], v[76:79], v[172:175], v[120:123]
	v_mfma_f32_16x16x32_bf16 v[108:111], v[68:71], v[200:203], v[108:111]
	v_mfma_f32_16x16x32_bf16 v[104:107], v[76:79], v[200:203], v[104:107]
	v_mfma_f32_16x16x32_bf16 v[92:95], v[68:71], v[208:211], v[92:95]
	v_mfma_f32_16x16x32_bf16 v[88:91], v[76:79], v[208:211], v[88:91]
	v_mfma_f32_16x16x32_bf16 v[140:143], v[72:75], v[168:171], v[140:143]
	v_mfma_f32_16x16x32_bf16 v[136:139], v[144:147], v[168:171], v[136:139]
	v_mfma_f32_16x16x32_bf16 v[124:127], v[72:75], v[196:199], v[124:127]
	v_mfma_f32_16x16x32_bf16 v[120:123], v[144:147], v[196:199], v[120:123]
	v_mfma_f32_16x16x32_bf16 v[108:111], v[72:75], v[204:207], v[108:111]
	v_mfma_f32_16x16x32_bf16 v[104:107], v[144:147], v[204:207], v[104:107]
	v_mfma_f32_16x16x32_bf16 v[92:95], v[72:75], v[212:215], v[92:95]
	v_mfma_f32_16x16x32_bf16 v[88:91], v[144:147], v[212:215], v[88:91]
	s_setprio 0
	s_setprio 1
	v_mfma_f32_16x16x32_bf16 v[132:135], v[148:151], v[164:167], v[132:135]
	v_mfma_f32_16x16x32_bf16 v[128:131], v[156:159], v[164:167], v[128:131]
	v_mfma_f32_16x16x32_bf16 v[116:119], v[148:151], v[172:175], v[116:119]
	v_mfma_f32_16x16x32_bf16 v[112:115], v[156:159], v[172:175], v[112:115]
	v_mfma_f32_16x16x32_bf16 v[100:103], v[148:151], v[200:203], v[100:103]
	v_mfma_f32_16x16x32_bf16 v[96:99], v[156:159], v[200:203], v[96:99]
	v_mfma_f32_16x16x32_bf16 v[84:87], v[148:151], v[208:211], v[84:87]
	v_mfma_f32_16x16x32_bf16 v[80:83], v[156:159], v[208:211], v[80:83]
	v_mfma_f32_16x16x32_bf16 v[132:135], v[152:155], v[168:171], v[132:135]
	v_mfma_f32_16x16x32_bf16 v[128:131], v[160:163], v[168:171], v[128:131]
	v_mfma_f32_16x16x32_bf16 v[116:119], v[152:155], v[196:199], v[116:119]
	v_mfma_f32_16x16x32_bf16 v[112:115], v[160:163], v[196:199], v[112:115]
	v_mfma_f32_16x16x32_bf16 v[100:103], v[152:155], v[204:207], v[100:103]
	v_mfma_f32_16x16x32_bf16 v[96:99], v[160:163], v[204:207], v[96:99]
	v_mfma_f32_16x16x32_bf16 v[84:87], v[152:155], v[212:215], v[84:87]
	s_setprio 0
	v_mfma_f32_16x16x32_bf16 v[80:83], v[160:163], v[212:215], v[80:83]
	s_barrier
	s_add_i32 m0, s35, 0x18000
	s_add_u32 s74, s74, 0x80
	s_addc_u32 s75, s75, 0
	ds_read_b128 v[164:167], v236 offset:49152
	ds_read_b128 v[168:171], v236 offset:50176
	ds_read_b128 v[172:175], v236 offset:51200
	ds_read_b128 v[196:199], v236 offset:52224
	ds_read_b128 v[200:203], v236 offset:53248
	ds_read_b128 v[204:207], v236 offset:54272
	ds_read_b128 v[208:211], v236 offset:55296
	ds_read_b128 v[212:215], v236 offset:56320
	global_load_lds_dwordx4 v176, s[74:75]
	s_add_i32 m0, s35, 0x1a000
	s_add_u32 s76, s74, s22
	s_addc_u32 s77, s75, 0
	global_load_lds_dwordx4 v190, s[74:75]
	s_add_i32 m0, s35, 0x1c000
	s_sub_u32 s4, s4, s22
	s_subb_u32 s5, s5, 0
	global_load_lds_dwordx4 v176, s[76:77]
	s_add_i32 m0, s35, 0x1e000
	s_add_u32 s4, s4, 0x80
	s_addc_u32 s5, s5, 0
	global_load_lds_dwordx4 v190, s[76:77]
	s_mov_b32 m0, s60
	s_nop 0
	global_load_lds_dwordx4 v186, s[4:5]
	s_mov_b32 m0, s61
	s_nop 0
	global_load_lds_dwordx4 v188, s[4:5]
	s_waitcnt vmcnt(8)
	s_waitcnt lgkmcnt(0)
	s_setprio 1
	s_barrier
	v_mfma_f32_16x16x32_bf16 v[60:63], v[68:71], v[164:167], v[60:63]
	v_mfma_f32_16x16x32_bf16 v[56:59], v[76:79], v[164:167], v[56:59]
	v_mfma_f32_16x16x32_bf16 v[44:47], v[68:71], v[172:175], v[44:47]
	v_mfma_f32_16x16x32_bf16 v[40:43], v[76:79], v[172:175], v[40:43]
	v_mfma_f32_16x16x32_bf16 v[28:31], v[68:71], v[200:203], v[28:31]
	v_mfma_f32_16x16x32_bf16 v[24:27], v[76:79], v[200:203], v[24:27]
	v_mfma_f32_16x16x32_bf16 v[12:15], v[68:71], v[208:211], v[12:15]
	v_mfma_f32_16x16x32_bf16 v[8:11], v[76:79], v[208:211], v[8:11]
	v_mfma_f32_16x16x32_bf16 v[60:63], v[72:75], v[168:171], v[60:63]
	v_mfma_f32_16x16x32_bf16 v[56:59], v[144:147], v[168:171], v[56:59]
	v_mfma_f32_16x16x32_bf16 v[44:47], v[72:75], v[196:199], v[44:47]
	v_mfma_f32_16x16x32_bf16 v[40:43], v[144:147], v[196:199], v[40:43]
	v_mfma_f32_16x16x32_bf16 v[28:31], v[72:75], v[204:207], v[28:31]
	v_mfma_f32_16x16x32_bf16 v[24:27], v[144:147], v[204:207], v[24:27]
	v_mfma_f32_16x16x32_bf16 v[12:15], v[72:75], v[212:215], v[12:15]
	v_mfma_f32_16x16x32_bf16 v[8:11], v[144:147], v[212:215], v[8:11]
	s_setprio 0
	s_setprio 1
	v_mfma_f32_16x16x32_bf16 v[52:55], v[148:151], v[164:167], v[52:55]
	v_mfma_f32_16x16x32_bf16 v[48:51], v[156:159], v[164:167], v[48:51]
	v_mfma_f32_16x16x32_bf16 v[36:39], v[148:151], v[172:175], v[36:39]
	v_mfma_f32_16x16x32_bf16 v[32:35], v[156:159], v[172:175], v[32:35]
	v_mfma_f32_16x16x32_bf16 v[20:23], v[148:151], v[200:203], v[20:23]
	v_mfma_f32_16x16x32_bf16 v[16:19], v[156:159], v[200:203], v[16:19]
	v_mfma_f32_16x16x32_bf16 v[4:7], v[148:151], v[208:211], v[4:7]
	v_mfma_f32_16x16x32_bf16 v[0:3], v[156:159], v[208:211], v[0:3]
	v_mfma_f32_16x16x32_bf16 v[52:55], v[152:155], v[168:171], v[52:55]
	v_mfma_f32_16x16x32_bf16 v[48:51], v[160:163], v[168:171], v[48:51]
	v_mfma_f32_16x16x32_bf16 v[36:39], v[152:155], v[196:199], v[36:39]
	v_mfma_f32_16x16x32_bf16 v[32:35], v[160:163], v[196:199], v[32:35]
	v_mfma_f32_16x16x32_bf16 v[20:23], v[152:155], v[204:207], v[20:23]
	v_mfma_f32_16x16x32_bf16 v[16:19], v[160:163], v[204:207], v[16:19]
	v_mfma_f32_16x16x32_bf16 v[4:7], v[152:155], v[212:215], v[4:7]
	s_setprio 0
	v_mfma_f32_16x16x32_bf16 v[0:3], v[160:163], v[212:215], v[0:3]
	s_barrier
	s_add_u32 s42, s42, 0x100
	s_addc_u32 s43, s43, 0
	s_cmp_ge_u32 s72, s63
	s_mov_b32 s71, s72
; #define PG8_STAGE(bufoff, gbase, voff) do { _Pragma("unroll") for (int _i = 0; _i < 2; ++_i) \
;         __builtin_amdgcn_global_load_lds((const unsigned*)((const char*)(gbase) + (voff)[_i]), (PG8_LAS unsigned*)(lds + (bufoff) + ldsw + _i * 8192), 16, 0, 0); } while (0)
; #define PG8_LDA(dst, b, h) do { _Pragma("unroll") for (int m = 0; m < 4; ++m) _Pragma("unroll") for (int k = 0; k < 2; ++k) dst[m][k] = *(const PG8_LAS bf16x8*)(lds + PG8_SA(b, h) + aoff + m * 2048 + k * 1024); } while (0)
; #define PG8_LDB(dst, b, h) do { _Pragma("unroll") for (int n = 0; n < 2; ++n) _Pragma("unroll") for (int k = 0; k < 2; ++k) dst[n][k] = *(const PG8_LAS bf16x8*)(lds + PG8_SB(b, h) + boff + n * 2048 + k * 1024); } while (0)
; #define PG8_WAIT_L(n) asm volatile("s_waitcnt lgkmcnt(" #n ")" ::: "memory")
; #define PG8_BAR __builtin_amdgcn_s_barrier()
; template <class Epi, class Sched, bool ALIGN_EPI = false, bool SP2 = false>
; __device__ __forceinline__ void gemm_phase(PG8_LAS unsigned char* lds, const Gemm g, const Sched& S, const Epi& E) {
;     ...
;             const bool last = (t == nt - 2);
;             const char* a1 = cA + (size_t)(t + 1) * kstep;
;             const char* a2 = last ? nA : cA + (size_t)(t + 2) * kstep; const char* b2 = last ? nB : cB + (size_t)(t + 2) * kstep;
;             const char* a3 = a2 + kstep; const char* b3 = b2 + kstep;
;             if (last && has_next) S.a_ready(nxt);
;             if constexpr (SP2) {
;             const int relax = __builtin_amdgcn_readfirstlane((t == 0 && ui > 0) ? 1 : 0);
;             PG8_LDB(B0, 0, 0); PG8_LDB(B1, 0, 1); PG8_SCHED; PG8_LDA(At, 0, 0); PG8_STAGE(PG8_SA(1, 1), a1 + hstep, voffA);
;             asm volatile("s_cmp_lg_u32 %0, 0\n\ts_cbranch_scc1 .Lrelax%=\n\ts_waitcnt vmcnt(8)\n.Lrelax%=:\n\ts_waitcnt vmcnt(%1)" :: "s"(relax), "n"(8 + Epi::NST) : "memory", "scc");
;             PG8_WAIT_L(0); PG8_BAR; PG8_MMA(0, 0, At, B0); PG8_MMA(0, 1, At, B1); PG8_BAR; PG8_SCHED;
;             PG8_LDA(At, 0, 1); PG8_STAGE(PG8_SB(0, 0), b2, voffB); PG8_STAGE(PG8_SB(0, 1), b2 + hstep, voffB); PG8_STAGE(PG8_SA(0, 0), a2, voffA);
;             asm volatile("s_cmp_lg_u32 %0, 0\n\ts_cbranch_scc1 .Lrelax%=\n\ts_waitcnt vmcnt(8)\n.Lrelax%=:\n\ts_waitcnt vmcnt(%1)" :: "s"(relax), "n"(8 + Epi::NST) : "memory", "scc");
;             PG8_WAIT_L(0); PG8_BAR; PG8_MMA(1, 0, At, B0); PG8_MMA(1, 1, At, B1); PG8_BAR; PG8_SCHED;
.LBB0_193:
	s_add_i32 s72, s71, 2
	s_add_u32 s4, s28, s42
	s_addc_u32 s5, s29, s43
	s_add_u32 s76, s4, 0x80
	s_addc_u32 s77, s5, 0
	s_add_u32 s4, s4, 0x100
	s_addc_u32 s5, s5, 0
	s_add_u32 s74, s2, s42
	s_addc_u32 s75, s70, s43
	s_cmp_eq_u32 s64, s71
	s_cselect_b32 s5, s55, s5
	s_cselect_b32 s4, s54, s4
	s_cselect_b32 s75, s57, s75
	s_cselect_b32 s74, s56, s74
	ds_read_b128 v[68:71], v216
	ds_read_b128 v[72:75], v216 offset:1024
	ds_read_b128 v[76:79], v216 offset:2048
	ds_read_b128 v[144:147], v216 offset:3072
	ds_read_b128 v[148:151], v216 offset:16384
	ds_read_b128 v[152:155], v216 offset:17408
	ds_read_b128 v[156:159], v216 offset:18432
	ds_read_b128 v[160:163], v216 offset:19456
	s_add_i32 m0, s36, 0xc000
	ds_read_b128 v[164:167], v236
	ds_read_b128 v[168:171], v236 offset:1024
	ds_read_b128 v[172:175], v236 offset:2048
	ds_read_b128 v[196:199], v236 offset:3072
	ds_read_b128 v[200:203], v236 offset:4096
	ds_read_b128 v[204:207], v236 offset:5120
	ds_read_b128 v[208:211], v236 offset:6144
	ds_read_b128 v[212:215], v236 offset:7168
	global_load_lds_dwordx4 v192, s[76:77]
	s_add_i32 m0, s36, 0xe000
	s_nop 0
	global_load_lds_dwordx4 v194, s[76:77]
	s_waitcnt vmcnt(8)
	s_waitcnt lgkmcnt(0)
	s_setprio 1
	s_barrier
	v_mfma_f32_16x16x32_bf16 v[140:143], v[68:71], v[164:167], v[140:143]
	v_mfma_f32_16x16x32_bf16 v[136:139], v[76:79], v[164:167], v[136:139]
	v_mfma_f32_16x16x32_bf16 v[124:127], v[68:71], v[172:175], v[124:127]
	v_mfma_f32_16x16x32_bf16 v[120:123], v[76:79], v[172:175], v[120:123]
	v_mfma_f32_16x16x32_bf16 v[108:111], v[68:71], v[200:203], v[108:111]
	v_mfma_f32_16x16x32_bf16 v[104:107], v[76:79], v[200:203], v[104:107]
	v_mfma_f32_16x16x32_bf16 v[92:95], v[68:71], v[208:211], v[92:95]
	v_mfma_f32_16x16x32_bf16 v[88:91], v[76:79], v[208:211], v[88:91]
	v_mfma_f32_16x16x32_bf16 v[140:143], v[72:75], v[168:171], v[140:143]
	v_mfma_f32_16x16x32_bf16 v[136:139], v[144:147], v[168:171], v[136:139]
	v_mfma_f32_16x16x32_bf16 v[124:127], v[72:75], v[196:199], v[124:127]
	v_mfma_f32_16x16x32_bf16 v[120:123], v[144:147], v[196:199], v[120:123]
	v_mfma_f32_16x16x32_bf16 v[108:111], v[72:75], v[204:207], v[108:111]
	v_mfma_f32_16x16x32_bf16 v[104:107], v[144:147], v[204:207], v[104:107]
	v_mfma_f32_16x16x32_bf16 v[92:95], v[72:75], v[212:215], v[92:95]
	v_mfma_f32_16x16x32_bf16 v[88:91], v[144:147], v[212:215], v[88:91]
	s_setprio 0
	s_setprio 1
	v_mfma_f32_16x16x32_bf16 v[132:135], v[148:151], v[164:167], v[132:135]
	v_mfma_f32_16x16x32_bf16 v[128:131], v[156:159], v[164:167], v[128:131]
	v_mfma_f32_16x16x32_bf16 v[116:119], v[148:151], v[172:175], v[116:119]
	v_mfma_f32_16x16x32_bf16 v[112:115], v[156:159], v[172:175], v[112:115]
	v_mfma_f32_16x16x32_bf16 v[100:103], v[148:151], v[200:203], v[100:103]
	v_mfma_f32_16x16x32_bf16 v[96:99], v[156:159], v[200:203], v[96:99]
	v_mfma_f32_16x16x32_bf16 v[84:87], v[148:151], v[208:211], v[84:87]
	v_mfma_f32_16x16x32_bf16 v[80:83], v[156:159], v[208:211], v[80:83]
	v_mfma_f32_16x16x32_bf16 v[132:135], v[152:155], v[168:171], v[132:135]
	v_mfma_f32_16x16x32_bf16 v[128:131], v[160:163], v[168:171], v[128:131]
	v_mfma_f32_16x16x32_bf16 v[116:119], v[152:155], v[196:199], v[116:119]
	v_mfma_f32_16x16x32_bf16 v[112:115], v[160:163], v[196:199], v[112:115]
	v_mfma_f32_16x16x32_bf16 v[100:103], v[152:155], v[204:207], v[100:103]
	v_mfma_f32_16x16x32_bf16 v[96:99], v[160:163], v[204:207], v[96:99]
	v_mfma_f32_16x16x32_bf16 v[84:87], v[152:155], v[212:215], v[84:87]
	s_setprio 0
	v_mfma_f32_16x16x32_bf16 v[80:83], v[160:163], v[212:215], v[80:83]
	s_barrier
	s_add_i32 m0, s35, 0x10000
	ds_read_b128 v[164:167], v236 offset:16384
	ds_read_b128 v[168:171], v236 offset:17408
	ds_read_b128 v[172:175], v236 offset:18432
	ds_read_b128 v[196:199], v236 offset:19456
	ds_read_b128 v[200:203], v236 offset:20480
	ds_read_b128 v[204:207], v236 offset:21504
	ds_read_b128 v[208:211], v236 offset:22528
	ds_read_b128 v[212:215], v236 offset:23552
	global_load_lds_dwordx4 v176, s[74:75]
	s_add_i32 m0, s35, 0x12000
	s_add_u32 s76, s74, s22
	s_addc_u32 s77, s75, 0
	global_load_lds_dwordx4 v190, s[74:75]
	s_add_i32 m0, s35, 0x14000
	s_nop 0
	global_load_lds_dwordx4 v176, s[76:77]
	s_add_i32 m0, s35, 0x16000
	s_nop 0
	global_load_lds_dwordx4 v190, s[76:77]
	s_mov_b32 m0, s36
	s_nop 0
	global_load_lds_dwordx4 v186, s[4:5]
	s_mov_b32 m0, s37
	s_nop 0
	global_load_lds_dwordx4 v188, s[4:5]
	s_waitcnt vmcnt(8)
	s_waitcnt lgkmcnt(0)
	s_setprio 1
	s_barrier
	v_mfma_f32_16x16x32_bf16 v[60:63], v[68:71], v[164:167], v[60:63]
	v_mfma_f32_16x16x32_bf16 v[56:59], v[76:79], v[164:167], v[56:59]
	v_mfma_f32_16x16x32_bf16 v[44:47], v[68:71], v[172:175], v[44:47]
	v_mfma_f32_16x16x32_bf16 v[40:43], v[76:79], v[172:175], v[40:43]
	v_mfma_f32_16x16x32_bf16 v[28:31], v[68:71], v[200:203], v[28:31]
	v_mfma_f32_16x16x32_bf16 v[24:27], v[76:79], v[200:203], v[24:27]
	v_mfma_f32_16x16x32_bf16 v[12:15], v[68:71], v[208:211], v[12:15]
	v_mfma_f32_16x16x32_bf16 v[8:11], v[76:79], v[208:211], v[8:11]
	v_mfma_f32_16x16x32_bf16 v[60:63], v[72:75], v[168:171], v[60:63]
	v_mfma_f32_16x16x32_bf16 v[56:59], v[144:147], v[168:171], v[56:59]
	v_mfma_f32_16x16x32_bf16 v[44:47], v[72:75], v[196:199], v[44:47]
	v_mfma_f32_16x16x32_bf16 v[40:43], v[144:147], v[196:199], v[40:43]
	v_mfma_f32_16x16x32_bf16 v[28:31], v[72:75], v[204:207], v[28:31]
	v_mfma_f32_16x16x32_bf16 v[24:27], v[144:147], v[204:207], v[24:27]
	v_mfma_f32_16x16x32_bf16 v[12:15], v[72:75], v[212:215], v[12:15]
	v_mfma_f32_16x16x32_bf16 v[8:11], v[144:147], v[212:215], v[8:11]
	s_setprio 0
	s_setprio 1
	v_mfma_f32_16x16x32_bf16 v[52:55], v[148:151], v[164:167], v[52:55]
	v_mfma_f32_16x16x32_bf16 v[48:51], v[156:159], v[164:167], v[48:51]
	v_mfma_f32_16x16x32_bf16 v[36:39], v[148:151], v[172:175], v[36:39]
	v_mfma_f32_16x16x32_bf16 v[32:35], v[156:159], v[172:175], v[32:35]
	v_mfma_f32_16x16x32_bf16 v[20:23], v[148:151], v[200:203], v[20:23]
	v_mfma_f32_16x16x32_bf16 v[16:19], v[156:159], v[200:203], v[16:19]
	v_mfma_f32_16x16x32_bf16 v[4:7], v[148:151], v[208:211], v[4:7]
	v_mfma_f32_16x16x32_bf16 v[0:3], v[156:159], v[208:211], v[0:3]
	v_mfma_f32_16x16x32_bf16 v[52:55], v[152:155], v[168:171], v[52:55]
	v_mfma_f32_16x16x32_bf16 v[48:51], v[160:163], v[168:171], v[48:51]
	v_mfma_f32_16x16x32_bf16 v[36:39], v[152:155], v[196:199], v[36:39]
	v_mfma_f32_16x16x32_bf16 v[32:35], v[160:163], v[196:199], v[32:35]
	v_mfma_f32_16x16x32_bf16 v[20:23], v[152:155], v[204:207], v[20:23]
	v_mfma_f32_16x16x32_bf16 v[16:19], v[160:163], v[204:207], v[16:19]
	v_mfma_f32_16x16x32_bf16 v[4:7], v[152:155], v[212:215], v[4:7]
	s_setprio 0
	v_mfma_f32_16x16x32_bf16 v[0:3], v[160:163], v[212:215], v[0:3]
	s_barrier
; #define PG8_STAGE(bufoff, gbase, voff) do { _Pragma("unroll") for (int _i = 0; _i < 2; ++_i) \
;         __builtin_amdgcn_global_load_lds((const unsigned*)((const char*)(gbase) + (voff)[_i]), (PG8_LAS unsigned*)(lds + (bufoff) + ldsw + _i * 8192), 16, 0, 0); } while (0)
; #define PG8_LDA(dst, b, h) do { _Pragma("unroll") for (int m = 0; m < 4; ++m) _Pragma("unroll") for (int k = 0; k < 2; ++k) dst[m][k] = *(const PG8_LAS bf16x8*)(lds + PG8_SA(b, h) + aoff + m * 2048 + k * 1024); } while (0)
; #define PG8_LDB(dst, b, h) do { _Pragma("unroll") for (int n = 0; n < 2; ++n) _Pragma("unroll") for (int k = 0; k < 2; ++k) dst[n][k] = *(const PG8_LAS bf16x8*)(lds + PG8_SB(b, h) + boff + n * 2048 + k * 1024); } while (0)
; #define PG8_MMA(ai, bj, At, Bt) do { __builtin_amdgcn_s_setprio(1); _Pragma("unroll") for (int m = 0; m < 4; ++m) _Pragma("unroll") for (int n = 0; n < 2; ++n) _Pragma("unroll") for (int k = 0; k < 2; ++k) \
;         acc[ai][bj][m][n] = __builtin_amdgcn_mfma_f32_16x16x32_bf16(Bt[n][k], At[m][k], acc[ai][bj][m][n], 0, 0, 0); __builtin_amdgcn_s_setprio(0); } while (0)
; #define PG8_WAIT_V(n) asm volatile("s_waitcnt vmcnt(" #n ")" ::: "memory")
; #define PG8_WAIT_L(n) asm volatile("s_waitcnt lgkmcnt(" #n ")" ::: "memory")
; #define PG8_BAR __builtin_amdgcn_s_barrier()
; #define PG8_SCHED __builtin_amdgcn_sched_barrier(0)
; template <class Epi, class Sched, bool ALIGN_EPI = false, bool SP2 = false>
; __device__ __forceinline__ void gemm_phase(PG8_LAS unsigned char* lds, const Gemm g, const Sched& S, const Epi& E) {
;     ...
;             PG8_LDB(B0, 1, 0); PG8_LDB(B1, 1, 1); PG8_SCHED; PG8_LDA(At, 1, 0); PG8_STAGE(PG8_SA(0, 1), a2 + hstep, voffA);
;             PG8_WAIT_V(8); PG8_WAIT_L(0); PG8_BAR; PG8_MMA(0, 0, At, B0); PG8_MMA(0, 1, At, B1); PG8_BAR; PG8_SCHED;
;             PG8_LDA(At, 1, 1); PG8_STAGE(PG8_SB(1, 0), b3, voffB); PG8_STAGE(PG8_SB(1, 1), b3 + hstep, voffB); PG8_STAGE(PG8_SA(1, 0), a3, voffA);
;             PG8_WAIT_V(8); PG8_WAIT_L(0); PG8_BAR; PG8_MMA(1, 0, At, B0); PG8_MMA(1, 1, At, B1); PG8_BAR; PG8_SCHED;
	ds_read_b128 v[68:71], v216 offset:32768
	ds_read_b128 v[72:75], v216 offset:33792
	ds_read_b128 v[76:79], v216 offset:34816
	ds_read_b128 v[144:147], v216 offset:35840
	ds_read_b128 v[148:151], v216 offset:49152
	ds_read_b128 v[152:155], v216 offset:50176
	ds_read_b128 v[156:159], v216 offset:51200
	ds_read_b128 v[160:163], v216 offset:52224
	s_add_u32 s4, s4, s22
	s_addc_u32 s5, s5, 0
	s_mov_b32 m0, s58
	ds_read_b128 v[164:167], v236 offset:32768
	ds_read_b128 v[168:171], v236 offset:33792
	ds_read_b128 v[172:175], v236 offset:34816
	ds_read_b128 v[196:199], v236 offset:35840
	ds_read_b128 v[200:203], v236 offset:36864
	ds_read_b128 v[204:207], v236 offset:37888
	ds_read_b128 v[208:211], v236 offset:38912
	ds_read_b128 v[212:215], v236 offset:39936
	global_load_lds_dwordx4 v186, s[4:5]
	s_mov_b32 m0, s59
	s_nop 0
	global_load_lds_dwordx4 v188, s[4:5]
	s_waitcnt vmcnt(8)
	s_waitcnt lgkmcnt(0)
	s_setprio 1
	s_barrier
	v_mfma_f32_16x16x32_bf16 v[140:143], v[68:71], v[164:167], v[140:143]
	v_mfma_f32_16x16x32_bf16 v[136:139], v[76:79], v[164:167], v[136:139]
	v_mfma_f32_16x16x32_bf16 v[124:127], v[68:71], v[172:175], v[124:127]
	v_mfma_f32_16x16x32_bf16 v[120:123], v[76:79], v[172:175], v[120:123]
	v_mfma_f32_16x16x32_bf16 v[108:111], v[68:71], v[200:203], v[108:111]
	v_mfma_f32_16x16x32_bf16 v[104:107], v[76:79], v[200:203], v[104:107]
	v_mfma_f32_16x16x32_bf16 v[92:95], v[68:71], v[208:211], v[92:95]
	v_mfma_f32_16x16x32_bf16 v[88:91], v[76:79], v[208:211], v[88:91]
	v_mfma_f32_16x16x32_bf16 v[140:143], v[72:75], v[168:171], v[140:143]
	v_mfma_f32_16x16x32_bf16 v[136:139], v[144:147], v[168:171], v[136:139]
	v_mfma_f32_16x16x32_bf16 v[124:127], v[72:75], v[196:199], v[124:127]
	v_mfma_f32_16x16x32_bf16 v[120:123], v[144:147], v[196:199], v[120:123]
	v_mfma_f32_16x16x32_bf16 v[108:111], v[72:75], v[204:207], v[108:111]
	v_mfma_f32_16x16x32_bf16 v[104:107], v[144:147], v[204:207], v[104:107]
	v_mfma_f32_16x16x32_bf16 v[92:95], v[72:75], v[212:215], v[92:95]
	v_mfma_f32_16x16x32_bf16 v[88:91], v[144:147], v[212:215], v[88:91]
	s_setprio 0
	s_setprio 1
	v_mfma_f32_16x16x32_bf16 v[132:135], v[148:151], v[164:167], v[132:135]
	v_mfma_f32_16x16x32_bf16 v[128:131], v[156:159], v[164:167], v[128:131]
	v_mfma_f32_16x16x32_bf16 v[116:119], v[148:151], v[172:175], v[116:119]
	v_mfma_f32_16x16x32_bf16 v[112:115], v[156:159], v[172:175], v[112:115]
	v_mfma_f32_16x16x32_bf16 v[100:103], v[148:151], v[200:203], v[100:103]
	v_mfma_f32_16x16x32_bf16 v[96:99], v[156:159], v[200:203], v[96:99]
	v_mfma_f32_16x16x32_bf16 v[84:87], v[148:151], v[208:211], v[84:87]
	v_mfma_f32_16x16x32_bf16 v[80:83], v[156:159], v[208:211], v[80:83]
	v_mfma_f32_16x16x32_bf16 v[132:135], v[152:155], v[168:171], v[132:135]
	v_mfma_f32_16x16x32_bf16 v[128:131], v[160:163], v[168:171], v[128:131]
	v_mfma_f32_16x16x32_bf16 v[116:119], v[152:155], v[196:199], v[116:119]
	v_mfma_f32_16x16x32_bf16 v[112:115], v[160:163], v[196:199], v[112:115]
	v_mfma_f32_16x16x32_bf16 v[100:103], v[152:155], v[204:207], v[100:103]
	v_mfma_f32_16x16x32_bf16 v[96:99], v[160:163], v[204:207], v[96:99]
	v_mfma_f32_16x16x32_bf16 v[84:87], v[152:155], v[212:215], v[84:87]
	s_setprio 0
	v_mfma_f32_16x16x32_bf16 v[80:83], v[160:163], v[212:215], v[80:83]
	s_barrier
	s_add_i32 m0, s35, 0x18000
	s_add_u32 s74, s74, 0x80
	s_addc_u32 s75, s75, 0
	ds_read_b128 v[164:167], v236 offset:49152
	ds_read_b128 v[168:171], v236 offset:50176
	ds_read_b128 v[172:175], v236 offset:51200
	ds_read_b128 v[196:199], v236 offset:52224
	ds_read_b128 v[200:203], v236 offset:53248
	ds_read_b128 v[204:207], v236 offset:54272
	ds_read_b128 v[208:211], v236 offset:55296
	ds_read_b128 v[212:215], v236 offset:56320
	global_load_lds_dwordx4 v176, s[74:75]
	s_add_i32 m0, s35, 0x1a000
	s_add_u32 s76, s74, s22
	s_addc_u32 s77, s75, 0
	global_load_lds_dwordx4 v190, s[74:75]
	s_add_i32 m0, s35, 0x1c000
	s_sub_u32 s4, s4, s22
	s_subb_u32 s5, s5, 0
	global_load_lds_dwordx4 v176, s[76:77]
	s_add_i32 m0, s35, 0x1e000
	s_add_u32 s4, s4, 0x80
	s_addc_u32 s5, s5, 0
	global_load_lds_dwordx4 v190, s[76:77]
	s_mov_b32 m0, s60
	s_nop 0
	global_load_lds_dwordx4 v186, s[4:5]
	s_mov_b32 m0, s61
	s_nop 0
	global_load_lds_dwordx4 v188, s[4:5]
	s_waitcnt vmcnt(8)
	s_waitcnt lgkmcnt(0)
	s_setprio 1
	s_barrier
	v_mfma_f32_16x16x32_bf16 v[60:63], v[68:71], v[164:167], v[60:63]
	v_mfma_f32_16x16x32_bf16 v[56:59], v[76:79], v[164:167], v[56:59]
	v_mfma_f32_16x16x32_bf16 v[44:47], v[68:71], v[172:175], v[44:47]
	v_mfma_f32_16x16x32_bf16 v[40:43], v[76:79], v[172:175], v[40:43]
	v_mfma_f32_16x16x32_bf16 v[28:31], v[68:71], v[200:203], v[28:31]
	v_mfma_f32_16x16x32_bf16 v[24:27], v[76:79], v[200:203], v[24:27]
	v_mfma_f32_16x16x32_bf16 v[12:15], v[68:71], v[208:211], v[12:15]
	v_mfma_f32_16x16x32_bf16 v[8:11], v[76:79], v[208:211], v[8:11]
	v_mfma_f32_16x16x32_bf16 v[60:63], v[72:75], v[168:171], v[60:63]
	v_mfma_f32_16x16x32_bf16 v[56:59], v[144:147], v[168:171], v[56:59]
	v_mfma_f32_16x16x32_bf16 v[44:47], v[72:75], v[196:199], v[44:47]
	v_mfma_f32_16x16x32_bf16 v[40:43], v[144:147], v[196:199], v[40:43]
	v_mfma_f32_16x16x32_bf16 v[28:31], v[72:75], v[204:207], v[28:31]
	v_mfma_f32_16x16x32_bf16 v[24:27], v[144:147], v[204:207], v[24:27]
	v_mfma_f32_16x16x32_bf16 v[12:15], v[72:75], v[212:215], v[12:15]
	v_mfma_f32_16x16x32_bf16 v[8:11], v[144:147], v[212:215], v[8:11]
	s_setprio 0
	s_setprio 1
	v_mfma_f32_16x16x32_bf16 v[52:55], v[148:151], v[164:167], v[52:55]
	v_mfma_f32_16x16x32_bf16 v[48:51], v[156:159], v[164:167], v[48:51]
	v_mfma_f32_16x16x32_bf16 v[36:39], v[148:151], v[172:175], v[36:39]
	v_mfma_f32_16x16x32_bf16 v[32:35], v[156:159], v[172:175], v[32:35]
	v_mfma_f32_16x16x32_bf16 v[20:23], v[148:151], v[200:203], v[20:23]
	v_mfma_f32_16x16x32_bf16 v[16:19], v[156:159], v[200:203], v[16:19]
	v_mfma_f32_16x16x32_bf16 v[4:7], v[148:151], v[208:211], v[4:7]
	v_mfma_f32_16x16x32_bf16 v[0:3], v[156:159], v[208:211], v[0:3]
	v_mfma_f32_16x16x32_bf16 v[52:55], v[152:155], v[168:171], v[52:55]
	v_mfma_f32_16x16x32_bf16 v[48:51], v[160:163], v[168:171], v[48:51]
	v_mfma_f32_16x16x32_bf16 v[36:39], v[152:155], v[196:199], v[36:39]
	v_mfma_f32_16x16x32_bf16 v[32:35], v[160:163], v[196:199], v[32:35]
	v_mfma_f32_16x16x32_bf16 v[20:23], v[152:155], v[204:207], v[20:23]
	v_mfma_f32_16x16x32_bf16 v[16:19], v[160:163], v[204:207], v[16:19]
	v_mfma_f32_16x16x32_bf16 v[4:7], v[152:155], v[212:215], v[4:7]
	s_setprio 0
	v_mfma_f32_16x16x32_bf16 v[0:3], v[160:163], v[212:215], v[0:3]
	s_barrier
	s_add_u32 s42, s42, 0x100
	s_addc_u32 s43, s43, 0
	s_cmp_ge_u32 s72, s63
	s_mov_b32 s71, s72
	s_cbranch_scc0 .LBB0_193

; #define PG8_STAGE(bufoff, gbase, voff) do { _Pragma("unroll") for (int _i = 0; _i < 2; ++_i) \
;         __builtin_amdgcn_global_load_lds((const unsigned*)((const char*)(gbase) + (voff)[_i]), (PG8_LAS unsigned*)(lds + (bufoff) + ldsw + _i * 8192), 16, 0, 0); } while (0)
; #define PG8_LDA(dst, b, h) do { _Pragma("unroll") for (int m = 0; m < 4; ++m) _Pragma("unroll") for (int k = 0; k < 2; ++k) dst[m][k] = *(const PG8_LAS bf16x8*)(lds + PG8_SA(b, h) + aoff + m * 2048 + k * 1024); } while (0)
; #define PG8_MMA(ai, bj, At, Bt) do { __builtin_amdgcn_s_setprio(1); _Pragma("unroll") for (int m = 0; m < 4; ++m) _Pragma("unroll") for (int n = 0; n < 2; ++n) _Pragma("unroll") for (int k = 0; k < 2; ++k) \
;         acc[ai][bj][m][n] = __builtin_amdgcn_mfma_f32_16x16x32_bf16(Bt[n][k], At[m][k], acc[ai][bj][m][n], 0, 0, 0); __builtin_amdgcn_s_setprio(0); } while (0)
; #define PG8_WAIT_L(n) asm volatile("s_waitcnt lgkmcnt(" #n ")" ::: "memory")
; #define PG8_BAR __builtin_amdgcn_s_barrier()
; #define PG8_SCHED __builtin_amdgcn_sched_barrier(0)
; template <class Epi, class Sched, bool ALIGN_EPI = false, bool SP2 = false>
; __device__ __forceinline__ void gemm_phase(PG8_LAS unsigned char* lds, const Gemm g, const Sched& S, const Epi& E) {
;     ...
;             asm volatile("s_cmp_lg_u32 %0, 0\n\ts_cbranch_scc1 .Lrelax%=\n\ts_waitcnt vmcnt(8)\n.Lrelax%=:\n\ts_waitcnt vmcnt(%1)" :: "s"(relax), "n"(8 + Epi::NST) : "memory", "scc");
;             PG8_WAIT_L(0); PG8_BAR; PG8_MMA(0, 0, At, B0); PG8_MMA(0, 1, At, B1); PG8_BAR; PG8_SCHED;
;             PG8_LDA(At, 0, 1); PG8_STAGE(PG8_SB(0, 0), b2, voffB); PG8_STAGE(PG8_SB(0, 1), b2 + hstep, voffB); PG8_STAGE(PG8_SA(0, 0), a2, voffA);
;             asm volatile("s_cmp_lg_u32 %0, 0\n\ts_cbranch_scc1 .Lrelax%=\n\ts_waitcnt vmcnt(8)\n.Lrelax%=:\n\ts_waitcnt vmcnt(%1)" :: "s"(relax), "n"(8 + Epi::NST) : "memory", "scc");
;             PG8_WAIT_L(0); PG8_BAR; PG8_MMA(1, 0, At, B0); PG8_MMA(1, 1, At, B1); PG8_BAR; PG8_SCHED;
.Lmy_swp_rx1:
	s_waitcnt vmcnt(16)
	s_waitcnt lgkmcnt(0)
	s_setprio 1
	s_barrier
	v_mfma_f32_16x16x32_bf16 v[132:135], v[60:63], v[198:201], 0
	v_mfma_f32_16x16x32_bf16 v[124:127], v[152:155], v[198:201], 0
	v_mfma_f32_16x16x32_bf16 v[116:119], v[60:63], v[206:209], 0
	v_mfma_f32_16x16x32_bf16 v[108:111], v[152:155], v[206:209], 0
	v_mfma_f32_16x16x32_bf16 v[100:103], v[60:63], v[214:217], 0
	v_mfma_f32_16x16x32_bf16 v[92:95], v[152:155], v[214:217], 0
	v_mfma_f32_16x16x32_bf16 v[84:87], v[60:63], v[238:241], 0
	v_mfma_f32_16x16x32_bf16 v[76:79], v[152:155], v[238:241], 0
	v_mfma_f32_16x16x32_bf16 v[132:135], v[148:151], v[202:205], v[132:135]
	v_mfma_f32_16x16x32_bf16 v[124:127], v[166:169], v[202:205], v[124:127]
	v_mfma_f32_16x16x32_bf16 v[116:119], v[148:151], v[210:213], v[116:119]
	v_mfma_f32_16x16x32_bf16 v[108:111], v[166:169], v[210:213], v[108:111]
	v_mfma_f32_16x16x32_bf16 v[100:103], v[148:151], v[234:237], v[100:103]
	v_mfma_f32_16x16x32_bf16 v[92:95], v[166:169], v[234:237], v[92:95]
	v_mfma_f32_16x16x32_bf16 v[84:87], v[148:151], v[242:245], v[84:87]
	v_mfma_f32_16x16x32_bf16 v[76:79], v[166:169], v[242:245], v[76:79]
	s_setprio 0
	s_setprio 1
	v_mfma_f32_16x16x32_bf16 v[128:131], v[170:173], v[198:201], 0
	v_mfma_f32_16x16x32_bf16 v[120:123], v[190:193], v[198:201], 0
	v_mfma_f32_16x16x32_bf16 v[112:115], v[170:173], v[206:209], 0
	v_mfma_f32_16x16x32_bf16 v[104:107], v[190:193], v[206:209], 0
	v_mfma_f32_16x16x32_bf16 v[96:99], v[170:173], v[214:217], 0
	v_mfma_f32_16x16x32_bf16 v[88:91], v[190:193], v[214:217], 0
	v_mfma_f32_16x16x32_bf16 v[80:83], v[170:173], v[238:241], 0
	v_mfma_f32_16x16x32_bf16 v[72:75], v[190:193], v[238:241], 0
	v_mfma_f32_16x16x32_bf16 v[128:131], v[186:189], v[202:205], v[128:131]
	v_mfma_f32_16x16x32_bf16 v[120:123], v[194:197], v[202:205], v[120:123]
	v_mfma_f32_16x16x32_bf16 v[112:115], v[186:189], v[210:213], v[112:115]
	v_mfma_f32_16x16x32_bf16 v[104:107], v[194:197], v[210:213], v[104:107]
	v_mfma_f32_16x16x32_bf16 v[96:99], v[186:189], v[234:237], v[96:99]
	v_mfma_f32_16x16x32_bf16 v[88:91], v[194:197], v[234:237], v[88:91]
	v_mfma_f32_16x16x32_bf16 v[80:83], v[186:189], v[242:245], v[80:83]
	s_setprio 0
	v_mfma_f32_16x16x32_bf16 v[72:75], v[194:197], v[242:245], v[72:75]
	s_barrier
	s_add_i32 m0, s29, 0x10000
	ds_read_b128 v[198:201], v165 offset:16384
	ds_read_b128 v[202:205], v165 offset:17408
	ds_read_b128 v[206:209], v165 offset:18432
	ds_read_b128 v[210:213], v165 offset:19456
	ds_read_b128 v[214:217], v165 offset:20480
	ds_read_b128 v[234:237], v165 offset:21504
	ds_read_b128 v[238:241], v165 offset:22528
	ds_read_b128 v[242:245], v165 offset:23552
	global_load_lds_dwordx4 v176, s[4:5]
	s_add_i32 m0, s29, 0x12000
	s_add_u32 s64, s4, 0x40000
	s_addc_u32 s65, s5, 0
	global_load_lds_dwordx4 v140, s[4:5]
	s_add_i32 m0, s29, 0x14000
	s_nop 0
	global_load_lds_dwordx4 v176, s[64:65]
	s_add_i32 m0, s29, 0x16000
	s_nop 0
	global_load_lds_dwordx4 v140, s[64:65]
	s_mov_b32 m0, s31
	s_nop 0
	global_load_lds_dwordx4 v136, s[34:35]
	s_mov_b32 m0, s52
	s_nop 0
	global_load_lds_dwordx4 v138, s[34:35]
	s_cmp_lg_u32 s48, 0
	s_cbranch_scc1 .Lmy_swp_rx2
	s_waitcnt vmcnt(8)
.Lmy_swp_rx2:
	s_waitcnt vmcnt(16)
	s_waitcnt lgkmcnt(0)
	s_setprio 1
	s_barrier
	v_mfma_f32_16x16x32_bf16 v[68:71], v[60:63], v[198:201], 0
	v_mfma_f32_16x16x32_bf16 v[52:55], v[152:155], v[198:201], 0
	v_mfma_f32_16x16x32_bf16 v[44:47], v[60:63], v[206:209], 0
	v_mfma_f32_16x16x32_bf16 v[36:39], v[152:155], v[206:209], 0
	v_mfma_f32_16x16x32_bf16 v[28:31], v[60:63], v[214:217], 0
	v_mfma_f32_16x16x32_bf16 v[20:23], v[152:155], v[214:217], 0
	v_mfma_f32_16x16x32_bf16 v[12:15], v[60:63], v[238:241], 0
	v_mfma_f32_16x16x32_bf16 v[4:7], v[152:155], v[238:241], 0
	v_mfma_f32_16x16x32_bf16 v[68:71], v[148:151], v[202:205], v[68:71]
	v_mfma_f32_16x16x32_bf16 v[52:55], v[166:169], v[202:205], v[52:55]
	v_mfma_f32_16x16x32_bf16 v[44:47], v[148:151], v[210:213], v[44:47]
	v_mfma_f32_16x16x32_bf16 v[36:39], v[166:169], v[210:213], v[36:39]
	v_mfma_f32_16x16x32_bf16 v[28:31], v[148:151], v[234:237], v[28:31]
	v_mfma_f32_16x16x32_bf16 v[20:23], v[166:169], v[234:237], v[20:23]
	v_mfma_f32_16x16x32_bf16 v[12:15], v[148:151], v[242:245], v[12:15]
	v_mfma_f32_16x16x32_bf16 v[4:7], v[166:169], v[242:245], v[4:7]
	s_setprio 0
	s_setprio 1
	v_mfma_f32_16x16x32_bf16 v[48:51], v[190:193], v[198:201], 0
	v_mfma_f32_16x16x32_bf16 v[40:43], v[170:173], v[206:209], 0
	v_mfma_f32_16x16x32_bf16 v[32:35], v[190:193], v[206:209], 0
	v_mfma_f32_16x16x32_bf16 v[24:27], v[170:173], v[214:217], 0
	v_mfma_f32_16x16x32_bf16 v[16:19], v[190:193], v[214:217], 0
	v_mfma_f32_16x16x32_bf16 v[8:11], v[170:173], v[238:241], 0
	v_mfma_f32_16x16x32_bf16 v[0:3], v[190:193], v[238:241], 0
	v_mfma_f32_16x16x32_bf16 v[60:63], v[170:173], v[198:201], 0
	v_mfma_f32_16x16x32_bf16 v[48:51], v[194:197], v[202:205], v[48:51]
	v_mfma_f32_16x16x32_bf16 v[40:43], v[186:189], v[210:213], v[40:43]
	v_mfma_f32_16x16x32_bf16 v[32:35], v[194:197], v[210:213], v[32:35]
	v_mfma_f32_16x16x32_bf16 v[24:27], v[186:189], v[234:237], v[24:27]
	v_mfma_f32_16x16x32_bf16 v[16:19], v[194:197], v[234:237], v[16:19]
	v_mfma_f32_16x16x32_bf16 v[8:11], v[186:189], v[242:245], v[8:11]
	v_mfma_f32_16x16x32_bf16 v[0:3], v[194:197], v[242:245], v[0:3]
	s_setprio 0
	v_mfma_f32_16x16x32_bf16 v[60:63], v[186:189], v[202:205], v[60:63]
	s_barrier
; #define PG8_STAGE(bufoff, gbase, voff) do { _Pragma("unroll") for (int _i = 0; _i < 2; ++_i) \
;         __builtin_amdgcn_global_load_lds((const unsigned*)((const char*)(gbase) + (voff)[_i]), (PG8_LAS unsigned*)(lds + (bufoff) + ldsw + _i * 8192), 16, 0, 0); } while (0)
; #define PG8_LDA(dst, b, h) do { _Pragma("unroll") for (int m = 0; m < 4; ++m) _Pragma("unroll") for (int k = 0; k < 2; ++k) dst[m][k] = *(const PG8_LAS bf16x8*)(lds + PG8_SA(b, h) + aoff + m * 2048 + k * 1024); } while (0)
; #define PG8_LDB(dst, b, h) do { _Pragma("unroll") for (int n = 0; n < 2; ++n) _Pragma("unroll") for (int k = 0; k < 2; ++k) dst[n][k] = *(const PG8_LAS bf16x8*)(lds + PG8_SB(b, h) + boff + n * 2048 + k * 1024); } while (0)
; #define PG8_MMA(ai, bj, At, Bt) do { __builtin_amdgcn_s_setprio(1); _Pragma("unroll") for (int m = 0; m < 4; ++m) _Pragma("unroll") for (int n = 0; n < 2; ++n) _Pragma("unroll") for (int k = 0; k < 2; ++k) \
;         acc[ai][bj][m][n] = __builtin_amdgcn_mfma_f32_16x16x32_bf16(Bt[n][k], At[m][k], acc[ai][bj][m][n], 0, 0, 0); __builtin_amdgcn_s_setprio(0); } while (0)
; #define PG8_WAIT_V(n) asm volatile("s_waitcnt vmcnt(" #n ")" ::: "memory")
; #define PG8_WAIT_L(n) asm volatile("s_waitcnt lgkmcnt(" #n ")" ::: "memory")
; #define PG8_BAR __builtin_amdgcn_s_barrier()
; #define PG8_SCHED __builtin_amdgcn_sched_barrier(0)
; template <class Epi, class Sched, bool ALIGN_EPI = false, bool SP2 = false>
; __device__ __forceinline__ void gemm_phase(PG8_LAS unsigned char* lds, const Gemm g, const Sched& S, const Epi& E) {
;     ...
;             PG8_LDB(B0, 1, 0); PG8_LDB(B1, 1, 1); PG8_SCHED; PG8_LDA(At, 1, 0); PG8_STAGE(PG8_SA(0, 1), a2 + hstep, voffA);
;             PG8_WAIT_V(8); PG8_WAIT_L(0); PG8_BAR; PG8_MMA(0, 0, At, B0); PG8_MMA(0, 1, At, B1); PG8_BAR; PG8_SCHED;
;             PG8_LDA(At, 1, 1); PG8_STAGE(PG8_SB(1, 0), b3, voffB); PG8_STAGE(PG8_SB(1, 1), b3 + hstep, voffB); PG8_STAGE(PG8_SA(1, 0), a3, voffA);
;             PG8_WAIT_V(8); PG8_WAIT_L(0); PG8_BAR; PG8_MMA(1, 0, At, B0); PG8_MMA(1, 1, At, B1); PG8_BAR; PG8_SCHED;
	ds_read_b128 v[64:67], v156 offset:32768
	ds_read_b128 v[148:151], v156 offset:33792
	ds_read_b128 v[152:155], v156 offset:34816
	ds_read_b128 v[166:169], v156 offset:35840
	ds_read_b128 v[170:173], v156 offset:49152
	ds_read_b128 v[186:189], v156 offset:50176
	ds_read_b128 v[190:193], v156 offset:51200
	ds_read_b128 v[194:197], v156 offset:52224
	s_add_u32 s34, s34, 0x40000
	s_addc_u32 s35, s35, 0
	s_mov_b32 m0, s53
	ds_read_b128 v[198:201], v165 offset:32768
	ds_read_b128 v[202:205], v165 offset:33792
	ds_read_b128 v[206:209], v165 offset:34816
	ds_read_b128 v[210:213], v165 offset:35840
	ds_read_b128 v[214:217], v165 offset:36864
	ds_read_b128 v[234:237], v165 offset:37888
	ds_read_b128 v[238:241], v165 offset:38912
	ds_read_b128 v[242:245], v165 offset:39936
	global_load_lds_dwordx4 v136, s[34:35]
	s_mov_b32 m0, s54
	s_nop 0
	global_load_lds_dwordx4 v138, s[34:35]
	s_waitcnt vmcnt(8)
	s_waitcnt lgkmcnt(0)
	s_setprio 1
	s_barrier
	v_mfma_f32_16x16x32_bf16 v[132:135], v[64:67], v[198:201], v[132:135]
	v_mfma_f32_16x16x32_bf16 v[124:127], v[152:155], v[198:201], v[124:127]
	v_mfma_f32_16x16x32_bf16 v[116:119], v[64:67], v[206:209], v[116:119]
	v_mfma_f32_16x16x32_bf16 v[108:111], v[152:155], v[206:209], v[108:111]
	v_mfma_f32_16x16x32_bf16 v[100:103], v[64:67], v[214:217], v[100:103]
	v_mfma_f32_16x16x32_bf16 v[92:95], v[152:155], v[214:217], v[92:95]
	v_mfma_f32_16x16x32_bf16 v[84:87], v[64:67], v[238:241], v[84:87]
	v_mfma_f32_16x16x32_bf16 v[76:79], v[152:155], v[238:241], v[76:79]
	v_mfma_f32_16x16x32_bf16 v[132:135], v[148:151], v[202:205], v[132:135]
	v_mfma_f32_16x16x32_bf16 v[124:127], v[166:169], v[202:205], v[124:127]
	v_mfma_f32_16x16x32_bf16 v[116:119], v[148:151], v[210:213], v[116:119]
	v_mfma_f32_16x16x32_bf16 v[108:111], v[166:169], v[210:213], v[108:111]
	v_mfma_f32_16x16x32_bf16 v[100:103], v[148:151], v[234:237], v[100:103]
	v_mfma_f32_16x16x32_bf16 v[92:95], v[166:169], v[234:237], v[92:95]
	v_mfma_f32_16x16x32_bf16 v[84:87], v[148:151], v[242:245], v[84:87]
	v_mfma_f32_16x16x32_bf16 v[76:79], v[166:169], v[242:245], v[76:79]
	s_setprio 0
	s_setprio 1
	v_mfma_f32_16x16x32_bf16 v[128:131], v[170:173], v[198:201], v[128:131]
	v_mfma_f32_16x16x32_bf16 v[120:123], v[190:193], v[198:201], v[120:123]
	v_mfma_f32_16x16x32_bf16 v[112:115], v[170:173], v[206:209], v[112:115]
	v_mfma_f32_16x16x32_bf16 v[104:107], v[190:193], v[206:209], v[104:107]
	v_mfma_f32_16x16x32_bf16 v[96:99], v[170:173], v[214:217], v[96:99]
	v_mfma_f32_16x16x32_bf16 v[88:91], v[190:193], v[214:217], v[88:91]
	v_mfma_f32_16x16x32_bf16 v[80:83], v[170:173], v[238:241], v[80:83]
	v_mfma_f32_16x16x32_bf16 v[72:75], v[190:193], v[238:241], v[72:75]
	v_mfma_f32_16x16x32_bf16 v[128:131], v[186:189], v[202:205], v[128:131]
	v_mfma_f32_16x16x32_bf16 v[120:123], v[194:197], v[202:205], v[120:123]
	v_mfma_f32_16x16x32_bf16 v[112:115], v[186:189], v[210:213], v[112:115]
	v_mfma_f32_16x16x32_bf16 v[104:107], v[194:197], v[210:213], v[104:107]
	v_mfma_f32_16x16x32_bf16 v[96:99], v[186:189], v[234:237], v[96:99]
	v_mfma_f32_16x16x32_bf16 v[88:91], v[194:197], v[234:237], v[88:91]
	v_mfma_f32_16x16x32_bf16 v[80:83], v[186:189], v[242:245], v[80:83]
	s_setprio 0
	v_mfma_f32_16x16x32_bf16 v[72:75], v[194:197], v[242:245], v[72:75]
	s_barrier
	s_add_i32 m0, s29, 0x18000
	s_add_u32 s4, s4, 0x80
	s_addc_u32 s5, s5, 0
	ds_read_b128 v[198:201], v165 offset:49152
	ds_read_b128 v[202:205], v165 offset:50176
	ds_read_b128 v[206:209], v165 offset:51200
	ds_read_b128 v[210:213], v165 offset:52224
	ds_read_b128 v[214:217], v165 offset:53248
	ds_read_b128 v[234:237], v165 offset:54272
	ds_read_b128 v[238:241], v165 offset:55296
	ds_read_b128 v[242:245], v165 offset:56320
	global_load_lds_dwordx4 v176, s[4:5]
	s_add_i32 m0, s29, 0x1a000
	s_add_u32 s64, s4, 0x40000
	s_addc_u32 s65, s5, 0
	global_load_lds_dwordx4 v140, s[4:5]
	s_add_i32 m0, s29, 0x1c000
	s_add_u32 s34, s34, 0xfffc0080
	s_addc_u32 s35, s35, -1
	global_load_lds_dwordx4 v176, s[64:65]
	s_add_i32 m0, s29, 0x1e000
	s_nop 0
	global_load_lds_dwordx4 v140, s[64:65]
	s_mov_b32 m0, s55
	s_nop 0
	global_load_lds_dwordx4 v136, s[34:35]
	s_mov_b32 m0, s56
	s_nop 0
	global_load_lds_dwordx4 v138, s[34:35]
	s_waitcnt vmcnt(8)
	s_waitcnt lgkmcnt(0)
	s_setprio 1
	s_barrier
	v_mfma_f32_16x16x32_bf16 v[68:71], v[64:67], v[198:201], v[68:71]
	v_mfma_f32_16x16x32_bf16 v[52:55], v[152:155], v[198:201], v[52:55]
	v_mfma_f32_16x16x32_bf16 v[44:47], v[64:67], v[206:209], v[44:47]
	v_mfma_f32_16x16x32_bf16 v[36:39], v[152:155], v[206:209], v[36:39]
	v_mfma_f32_16x16x32_bf16 v[28:31], v[64:67], v[214:217], v[28:31]
	v_mfma_f32_16x16x32_bf16 v[20:23], v[152:155], v[214:217], v[20:23]
	v_mfma_f32_16x16x32_bf16 v[12:15], v[64:67], v[238:241], v[12:15]
	v_mfma_f32_16x16x32_bf16 v[4:7], v[152:155], v[238:241], v[4:7]
	v_mfma_f32_16x16x32_bf16 v[68:71], v[148:151], v[202:205], v[68:71]
	v_mfma_f32_16x16x32_bf16 v[52:55], v[166:169], v[202:205], v[52:55]
	v_mfma_f32_16x16x32_bf16 v[44:47], v[148:151], v[210:213], v[44:47]
	v_mfma_f32_16x16x32_bf16 v[36:39], v[166:169], v[210:213], v[36:39]
	v_mfma_f32_16x16x32_bf16 v[28:31], v[148:151], v[234:237], v[28:31]
	v_mfma_f32_16x16x32_bf16 v[20:23], v[166:169], v[234:237], v[20:23]
	v_mfma_f32_16x16x32_bf16 v[12:15], v[148:151], v[242:245], v[12:15]
	v_mfma_f32_16x16x32_bf16 v[4:7], v[166:169], v[242:245], v[4:7]
	s_setprio 0
	s_setprio 1
	v_mfma_f32_16x16x32_bf16 v[60:63], v[170:173], v[198:201], v[60:63]
	v_mfma_f32_16x16x32_bf16 v[48:51], v[190:193], v[198:201], v[48:51]
	v_mfma_f32_16x16x32_bf16 v[40:43], v[170:173], v[206:209], v[40:43]
	v_mfma_f32_16x16x32_bf16 v[32:35], v[190:193], v[206:209], v[32:35]
	v_mfma_f32_16x16x32_bf16 v[24:27], v[170:173], v[214:217], v[24:27]
	v_mfma_f32_16x16x32_bf16 v[16:19], v[190:193], v[214:217], v[16:19]
	v_mfma_f32_16x16x32_bf16 v[8:11], v[170:173], v[238:241], v[8:11]
	v_mfma_f32_16x16x32_bf16 v[0:3], v[190:193], v[238:241], v[0:3]
	v_mfma_f32_16x16x32_bf16 v[64:67], v[186:189], v[202:205], v[60:63]
	v_mfma_f32_16x16x32_bf16 v[48:51], v[194:197], v[202:205], v[48:51]
	v_mfma_f32_16x16x32_bf16 v[40:43], v[186:189], v[210:213], v[40:43]
	v_mfma_f32_16x16x32_bf16 v[32:35], v[194:197], v[210:213], v[32:35]
	v_mfma_f32_16x16x32_bf16 v[24:27], v[186:189], v[234:237], v[24:27]
	v_mfma_f32_16x16x32_bf16 v[16:19], v[194:197], v[234:237], v[16:19]
	v_mfma_f32_16x16x32_bf16 v[8:11], v[186:189], v[242:245], v[8:11]
	s_setprio 0
	v_mfma_f32_16x16x32_bf16 v[0:3], v[194:197], v[242:245], v[0:3]
	s_barrier
	s_add_i32 s63, s63, 2
	s_add_u32 s50, s50, 0x100
	s_addc_u32 s51, s51, 0
	s_cmp_gt_u32 s63, 13
; #define PG8_STAGE(bufoff, gbase, voff) do { _Pragma("unroll") for (int _i = 0; _i < 2; ++_i) \
;         __builtin_amdgcn_global_load_lds((const unsigned*)((const char*)(gbase) + (voff)[_i]), (PG8_LAS unsigned*)(lds + (bufoff) + ldsw + _i * 8192), 16, 0, 0); } while (0)
; #define PG8_LDA(dst, b, h) do { _Pragma("unroll") for (int m = 0; m < 4; ++m) _Pragma("unroll") for (int k = 0; k < 2; ++k) dst[m][k] = *(const PG8_LAS bf16x8*)(lds + PG8_SA(b, h) + aoff + m * 2048 + k * 1024); } while (0)
; #define PG8_LDB(dst, b, h) do { _Pragma("unroll") for (int n = 0; n < 2; ++n) _Pragma("unroll") for (int k = 0; k < 2; ++k) dst[n][k] = *(const PG8_LAS bf16x8*)(lds + PG8_SB(b, h) + boff + n * 2048 + k * 1024); } while (0)
; #define PG8_WAIT_L(n) asm volatile("s_waitcnt lgkmcnt(" #n ")" ::: "memory")
; template <class Epi, class Sched, bool ALIGN_EPI = false, bool SP2 = false>
; __device__ __forceinline__ void gemm_phase(PG8_LAS unsigned char* lds, const Gemm g, const Sched& S, const Epi& E) {
;     ...
;         for (int t = 0; t < nt; t += 2) {
;             const bool last = (t == nt - 2);
;             const char* a1 = cA + (size_t)(t + 1) * kstep;
;             const char* a2 = last ? nA : cA + (size_t)(t + 2) * kstep; const char* b2 = last ? nB : cB + (size_t)(t + 2) * kstep;
;             const char* a3 = a2 + kstep; const char* b3 = b2 + kstep;
;             if (last && has_next) S.a_ready(nxt);
;             if constexpr (SP2) {
;             const int relax = __builtin_amdgcn_readfirstlane((t == 0 && ui > 0) ? 1 : 0);
;             PG8_LDB(B0, 0, 0); PG8_LDB(B1, 0, 1); PG8_SCHED; PG8_LDA(At, 0, 0); PG8_STAGE(PG8_SA(1, 1), a1 + hstep, voffA);
;             asm volatile("s_cmp_lg_u32 %0, 0\n\ts_cbranch_scc1 .Lrelax%=\n\ts_waitcnt vmcnt(8)\n.Lrelax%=:\n\ts_waitcnt vmcnt(%1)" :: "s"(relax), "n"(8 + Epi::NST) : "memory", "scc");
;             PG8_WAIT_L(0); PG8_BAR; PG8_MMA(0, 0, At, B0); PG8_MMA(0, 1, At, B1); PG8_BAR; PG8_SCHED;
;             PG8_LDA(At, 0, 1); PG8_STAGE(PG8_SB(0, 0), b2, voffB); PG8_STAGE(PG8_SB(0, 1), b2 + hstep, voffB); PG8_STAGE(PG8_SA(0, 0), a2, voffA);
;             asm volatile("s_cmp_lg_u32 %0, 0\n\ts_cbranch_scc1 .Lrelax%=\n\ts_waitcnt vmcnt(8)\n.Lrelax%=:\n\ts_waitcnt vmcnt(%1)" :: "s"(relax), "n"(8 + Epi::NST) : "memory", "scc");
;             PG8_WAIT_L(0); PG8_BAR; PG8_MMA(1, 0, At, B0); PG8_MMA(1, 1, At, B1); PG8_BAR; PG8_SCHED;
.LBB0_236:
	s_add_u32 s4, s40, s50
	s_addc_u32 s5, s41, s51
	s_add_u32 s64, s4, 0x40080
	s_addc_u32 s65, s5, 0
	s_add_u32 s34, s4, 0x100
	s_addc_u32 s35, s5, 0
	s_add_u32 s4, s61, s50
	s_addc_u32 s5, s62, s51
	s_cmpk_eq_i32 s50, 0x700
	s_cselect_b32 s35, s27, s35
	s_cselect_b32 s34, s59, s34
	s_cselect_b32 s5, s25, s5
	s_cselect_b32 s4, s60, s4
	ds_read_b128 v[60:63], v156
	ds_read_b128 v[148:151], v156 offset:1024
	ds_read_b128 v[152:155], v156 offset:2048
	ds_read_b128 v[166:169], v156 offset:3072
	ds_read_b128 v[170:173], v156 offset:16384
	ds_read_b128 v[186:189], v156 offset:17408
	ds_read_b128 v[190:193], v156 offset:18432
	ds_read_b128 v[194:197], v156 offset:19456
	s_add_i32 m0, s31, 0xc000
	ds_read_b128 v[198:201], v165
	ds_read_b128 v[202:205], v165 offset:1024
	ds_read_b128 v[206:209], v165 offset:2048
	ds_read_b128 v[210:213], v165 offset:3072
	ds_read_b128 v[214:217], v165 offset:4096
	ds_read_b128 v[234:237], v165 offset:5120
	ds_read_b128 v[238:241], v165 offset:6144
	ds_read_b128 v[242:245], v165 offset:7168
	global_load_lds_dwordx4 v144, s[64:65]
	s_add_i32 m0, s31, 0xe000
	s_nop 0
	global_load_lds_dwordx4 v146, s[64:65]
	s_waitcnt vmcnt(8)
	s_waitcnt lgkmcnt(0)
	s_setprio 1
	s_barrier
	v_mfma_f32_16x16x32_bf16 v[132:135], v[60:63], v[198:201], v[132:135]
	v_mfma_f32_16x16x32_bf16 v[124:127], v[152:155], v[198:201], v[124:127]
	v_mfma_f32_16x16x32_bf16 v[116:119], v[60:63], v[206:209], v[116:119]
	v_mfma_f32_16x16x32_bf16 v[108:111], v[152:155], v[206:209], v[108:111]
	v_mfma_f32_16x16x32_bf16 v[100:103], v[60:63], v[214:217], v[100:103]
	v_mfma_f32_16x16x32_bf16 v[92:95], v[152:155], v[214:217], v[92:95]
	v_mfma_f32_16x16x32_bf16 v[84:87], v[60:63], v[238:241], v[84:87]
	v_mfma_f32_16x16x32_bf16 v[76:79], v[152:155], v[238:241], v[76:79]
	v_mfma_f32_16x16x32_bf16 v[132:135], v[148:151], v[202:205], v[132:135]
	v_mfma_f32_16x16x32_bf16 v[124:127], v[166:169], v[202:205], v[124:127]
	v_mfma_f32_16x16x32_bf16 v[116:119], v[148:151], v[210:213], v[116:119]
	v_mfma_f32_16x16x32_bf16 v[108:111], v[166:169], v[210:213], v[108:111]
	v_mfma_f32_16x16x32_bf16 v[100:103], v[148:151], v[234:237], v[100:103]
	v_mfma_f32_16x16x32_bf16 v[92:95], v[166:169], v[234:237], v[92:95]
	v_mfma_f32_16x16x32_bf16 v[84:87], v[148:151], v[242:245], v[84:87]
	v_mfma_f32_16x16x32_bf16 v[76:79], v[166:169], v[242:245], v[76:79]
	s_setprio 0
	s_setprio 1
	v_mfma_f32_16x16x32_bf16 v[128:131], v[170:173], v[198:201], v[128:131]
	v_mfma_f32_16x16x32_bf16 v[120:123], v[190:193], v[198:201], v[120:123]
	v_mfma_f32_16x16x32_bf16 v[112:115], v[170:173], v[206:209], v[112:115]
	v_mfma_f32_16x16x32_bf16 v[104:107], v[190:193], v[206:209], v[104:107]
	v_mfma_f32_16x16x32_bf16 v[96:99], v[170:173], v[214:217], v[96:99]
	v_mfma_f32_16x16x32_bf16 v[88:91], v[190:193], v[214:217], v[88:91]
	v_mfma_f32_16x16x32_bf16 v[80:83], v[170:173], v[238:241], v[80:83]
	v_mfma_f32_16x16x32_bf16 v[72:75], v[190:193], v[238:241], v[72:75]
	v_mfma_f32_16x16x32_bf16 v[128:131], v[186:189], v[202:205], v[128:131]
	v_mfma_f32_16x16x32_bf16 v[120:123], v[194:197], v[202:205], v[120:123]
	v_mfma_f32_16x16x32_bf16 v[112:115], v[186:189], v[210:213], v[112:115]
	v_mfma_f32_16x16x32_bf16 v[104:107], v[194:197], v[210:213], v[104:107]
	v_mfma_f32_16x16x32_bf16 v[96:99], v[186:189], v[234:237], v[96:99]
	v_mfma_f32_16x16x32_bf16 v[88:91], v[194:197], v[234:237], v[88:91]
	v_mfma_f32_16x16x32_bf16 v[80:83], v[186:189], v[242:245], v[80:83]
	s_setprio 0
	v_mfma_f32_16x16x32_bf16 v[72:75], v[194:197], v[242:245], v[72:75]
	s_barrier
	s_add_i32 m0, s29, 0x10000
	ds_read_b128 v[198:201], v165 offset:16384
	ds_read_b128 v[202:205], v165 offset:17408
	ds_read_b128 v[206:209], v165 offset:18432
	ds_read_b128 v[210:213], v165 offset:19456
	ds_read_b128 v[214:217], v165 offset:20480
	ds_read_b128 v[234:237], v165 offset:21504
	ds_read_b128 v[238:241], v165 offset:22528
	ds_read_b128 v[242:245], v165 offset:23552
	global_load_lds_dwordx4 v176, s[4:5]
	s_add_i32 m0, s29, 0x12000
	s_add_u32 s64, s4, 0x40000
	s_addc_u32 s65, s5, 0
	global_load_lds_dwordx4 v140, s[4:5]
	s_add_i32 m0, s29, 0x14000
	s_nop 0
	global_load_lds_dwordx4 v176, s[64:65]
	s_add_i32 m0, s29, 0x16000
	s_nop 0
	global_load_lds_dwordx4 v140, s[64:65]
	s_mov_b32 m0, s31
	s_nop 0
	global_load_lds_dwordx4 v136, s[34:35]
	s_mov_b32 m0, s52
	s_nop 0
	global_load_lds_dwordx4 v138, s[34:35]
	s_waitcnt vmcnt(8)
	s_waitcnt lgkmcnt(0)
	s_setprio 1
	s_barrier
	v_mfma_f32_16x16x32_bf16 v[68:71], v[60:63], v[198:201], v[68:71]
	v_mfma_f32_16x16x32_bf16 v[52:55], v[152:155], v[198:201], v[52:55]
	v_mfma_f32_16x16x32_bf16 v[44:47], v[60:63], v[206:209], v[44:47]
	v_mfma_f32_16x16x32_bf16 v[36:39], v[152:155], v[206:209], v[36:39]
	v_mfma_f32_16x16x32_bf16 v[28:31], v[60:63], v[214:217], v[28:31]
	v_mfma_f32_16x16x32_bf16 v[20:23], v[152:155], v[214:217], v[20:23]
	v_mfma_f32_16x16x32_bf16 v[12:15], v[60:63], v[238:241], v[12:15]
	v_mfma_f32_16x16x32_bf16 v[4:7], v[152:155], v[238:241], v[4:7]
	v_mfma_f32_16x16x32_bf16 v[68:71], v[148:151], v[202:205], v[68:71]
	v_mfma_f32_16x16x32_bf16 v[52:55], v[166:169], v[202:205], v[52:55]
	v_mfma_f32_16x16x32_bf16 v[44:47], v[148:151], v[210:213], v[44:47]
	v_mfma_f32_16x16x32_bf16 v[36:39], v[166:169], v[210:213], v[36:39]
	v_mfma_f32_16x16x32_bf16 v[28:31], v[148:151], v[234:237], v[28:31]
	v_mfma_f32_16x16x32_bf16 v[20:23], v[166:169], v[234:237], v[20:23]
	v_mfma_f32_16x16x32_bf16 v[12:15], v[148:151], v[242:245], v[12:15]
	v_mfma_f32_16x16x32_bf16 v[4:7], v[166:169], v[242:245], v[4:7]
	s_setprio 0
	s_setprio 1
	v_mfma_f32_16x16x32_bf16 v[48:51], v[190:193], v[198:201], v[48:51]
	v_mfma_f32_16x16x32_bf16 v[40:43], v[170:173], v[206:209], v[40:43]
	v_mfma_f32_16x16x32_bf16 v[32:35], v[190:193], v[206:209], v[32:35]
	v_mfma_f32_16x16x32_bf16 v[24:27], v[170:173], v[214:217], v[24:27]
	v_mfma_f32_16x16x32_bf16 v[16:19], v[190:193], v[214:217], v[16:19]
	v_mfma_f32_16x16x32_bf16 v[8:11], v[170:173], v[238:241], v[8:11]
	v_mfma_f32_16x16x32_bf16 v[0:3], v[190:193], v[238:241], v[0:3]
	v_mfma_f32_16x16x32_bf16 v[60:63], v[170:173], v[198:201], v[64:67]
	v_mfma_f32_16x16x32_bf16 v[48:51], v[194:197], v[202:205], v[48:51]
	v_mfma_f32_16x16x32_bf16 v[40:43], v[186:189], v[210:213], v[40:43]
	v_mfma_f32_16x16x32_bf16 v[32:35], v[194:197], v[210:213], v[32:35]
	v_mfma_f32_16x16x32_bf16 v[24:27], v[186:189], v[234:237], v[24:27]
	v_mfma_f32_16x16x32_bf16 v[16:19], v[194:197], v[234:237], v[16:19]
	v_mfma_f32_16x16x32_bf16 v[8:11], v[186:189], v[242:245], v[8:11]
	v_mfma_f32_16x16x32_bf16 v[0:3], v[194:197], v[242:245], v[0:3]
	s_setprio 0
	v_mfma_f32_16x16x32_bf16 v[60:63], v[186:189], v[202:205], v[60:63]
	s_barrier
; #define PG8_STAGE(bufoff, gbase, voff) do { _Pragma("unroll") for (int _i = 0; _i < 2; ++_i) \
;         __builtin_amdgcn_global_load_lds((const unsigned*)((const char*)(gbase) + (voff)[_i]), (PG8_LAS unsigned*)(lds + (bufoff) + ldsw + _i * 8192), 16, 0, 0); } while (0)
; #define PG8_LDA(dst, b, h) do { _Pragma("unroll") for (int m = 0; m < 4; ++m) _Pragma("unroll") for (int k = 0; k < 2; ++k) dst[m][k] = *(const PG8_LAS bf16x8*)(lds + PG8_SA(b, h) + aoff + m * 2048 + k * 1024); } while (0)
; #define PG8_LDB(dst, b, h) do { _Pragma("unroll") for (int n = 0; n < 2; ++n) _Pragma("unroll") for (int k = 0; k < 2; ++k) dst[n][k] = *(const PG8_LAS bf16x8*)(lds + PG8_SB(b, h) + boff + n * 2048 + k * 1024); } while (0)
; #define PG8_MMA(ai, bj, At, Bt) do { __builtin_amdgcn_s_setprio(1); _Pragma("unroll") for (int m = 0; m < 4; ++m) _Pragma("unroll") for (int n = 0; n < 2; ++n) _Pragma("unroll") for (int k = 0; k < 2; ++k) \
;         acc[ai][bj][m][n] = __builtin_amdgcn_mfma_f32_16x16x32_bf16(Bt[n][k], At[m][k], acc[ai][bj][m][n], 0, 0, 0); __builtin_amdgcn_s_setprio(0); } while (0)
; #define PG8_WAIT_V(n) asm volatile("s_waitcnt vmcnt(" #n ")" ::: "memory")
; #define PG8_WAIT_L(n) asm volatile("s_waitcnt lgkmcnt(" #n ")" ::: "memory")
; #define PG8_BAR __builtin_amdgcn_s_barrier()
; #define PG8_SCHED __builtin_amdgcn_sched_barrier(0)
; template <class Epi, class Sched, bool ALIGN_EPI = false, bool SP2 = false>
; __device__ __forceinline__ void gemm_phase(PG8_LAS unsigned char* lds, const Gemm g, const Sched& S, const Epi& E) {
;     ...
;         for (int t = 0; t < nt; t += 2) {
;     ...
;             PG8_LDB(B0, 1, 0); PG8_LDB(B1, 1, 1); PG8_SCHED; PG8_LDA(At, 1, 0); PG8_STAGE(PG8_SA(0, 1), a2 + hstep, voffA);
;             PG8_WAIT_V(8); PG8_WAIT_L(0); PG8_BAR; PG8_MMA(0, 0, At, B0); PG8_MMA(0, 1, At, B1); PG8_BAR; PG8_SCHED;
;             PG8_LDA(At, 1, 1); PG8_STAGE(PG8_SB(1, 0), b3, voffB); PG8_STAGE(PG8_SB(1, 1), b3 + hstep, voffB); PG8_STAGE(PG8_SA(1, 0), a3, voffA);
;             PG8_WAIT_V(8); PG8_WAIT_L(0); PG8_BAR; PG8_MMA(1, 0, At, B0); PG8_MMA(1, 1, At, B1); PG8_BAR; PG8_SCHED;
	ds_read_b128 v[64:67], v156 offset:32768
	ds_read_b128 v[148:151], v156 offset:33792
	ds_read_b128 v[152:155], v156 offset:34816
	ds_read_b128 v[166:169], v156 offset:35840
	ds_read_b128 v[170:173], v156 offset:49152
	ds_read_b128 v[186:189], v156 offset:50176
	ds_read_b128 v[190:193], v156 offset:51200
	ds_read_b128 v[194:197], v156 offset:52224
	s_add_u32 s34, s34, 0x40000
	s_addc_u32 s35, s35, 0
	s_mov_b32 m0, s53
	ds_read_b128 v[198:201], v165 offset:32768
	ds_read_b128 v[202:205], v165 offset:33792
	ds_read_b128 v[206:209], v165 offset:34816
	ds_read_b128 v[210:213], v165 offset:35840
	ds_read_b128 v[214:217], v165 offset:36864
	ds_read_b128 v[234:237], v165 offset:37888
	ds_read_b128 v[238:241], v165 offset:38912
	ds_read_b128 v[242:245], v165 offset:39936
	global_load_lds_dwordx4 v136, s[34:35]
	s_mov_b32 m0, s54
	s_nop 0
	global_load_lds_dwordx4 v138, s[34:35]
	s_waitcnt vmcnt(8)
	s_waitcnt lgkmcnt(0)
	s_setprio 1
	s_barrier
	v_mfma_f32_16x16x32_bf16 v[132:135], v[64:67], v[198:201], v[132:135]
	v_mfma_f32_16x16x32_bf16 v[124:127], v[152:155], v[198:201], v[124:127]
	v_mfma_f32_16x16x32_bf16 v[116:119], v[64:67], v[206:209], v[116:119]
	v_mfma_f32_16x16x32_bf16 v[108:111], v[152:155], v[206:209], v[108:111]
	v_mfma_f32_16x16x32_bf16 v[100:103], v[64:67], v[214:217], v[100:103]
	v_mfma_f32_16x16x32_bf16 v[92:95], v[152:155], v[214:217], v[92:95]
	v_mfma_f32_16x16x32_bf16 v[84:87], v[64:67], v[238:241], v[84:87]
	v_mfma_f32_16x16x32_bf16 v[76:79], v[152:155], v[238:241], v[76:79]
	v_mfma_f32_16x16x32_bf16 v[132:135], v[148:151], v[202:205], v[132:135]
	v_mfma_f32_16x16x32_bf16 v[124:127], v[166:169], v[202:205], v[124:127]
	v_mfma_f32_16x16x32_bf16 v[116:119], v[148:151], v[210:213], v[116:119]
	v_mfma_f32_16x16x32_bf16 v[108:111], v[166:169], v[210:213], v[108:111]
	v_mfma_f32_16x16x32_bf16 v[100:103], v[148:151], v[234:237], v[100:103]
	v_mfma_f32_16x16x32_bf16 v[92:95], v[166:169], v[234:237], v[92:95]
	v_mfma_f32_16x16x32_bf16 v[84:87], v[148:151], v[242:245], v[84:87]
	v_mfma_f32_16x16x32_bf16 v[76:79], v[166:169], v[242:245], v[76:79]
	s_setprio 0
	s_setprio 1
	v_mfma_f32_16x16x32_bf16 v[128:131], v[170:173], v[198:201], v[128:131]
	v_mfma_f32_16x16x32_bf16 v[120:123], v[190:193], v[198:201], v[120:123]
	v_mfma_f32_16x16x32_bf16 v[112:115], v[170:173], v[206:209], v[112:115]
	v_mfma_f32_16x16x32_bf16 v[104:107], v[190:193], v[206:209], v[104:107]
	v_mfma_f32_16x16x32_bf16 v[96:99], v[170:173], v[214:217], v[96:99]
	v_mfma_f32_16x16x32_bf16 v[88:91], v[190:193], v[214:217], v[88:91]
	v_mfma_f32_16x16x32_bf16 v[80:83], v[170:173], v[238:241], v[80:83]
	v_mfma_f32_16x16x32_bf16 v[72:75], v[190:193], v[238:241], v[72:75]
	v_mfma_f32_16x16x32_bf16 v[128:131], v[186:189], v[202:205], v[128:131]
	v_mfma_f32_16x16x32_bf16 v[120:123], v[194:197], v[202:205], v[120:123]
	v_mfma_f32_16x16x32_bf16 v[112:115], v[186:189], v[210:213], v[112:115]
	v_mfma_f32_16x16x32_bf16 v[104:107], v[194:197], v[210:213], v[104:107]
	v_mfma_f32_16x16x32_bf16 v[96:99], v[186:189], v[234:237], v[96:99]
	v_mfma_f32_16x16x32_bf16 v[88:91], v[194:197], v[234:237], v[88:91]
	v_mfma_f32_16x16x32_bf16 v[80:83], v[186:189], v[242:245], v[80:83]
	s_setprio 0
	v_mfma_f32_16x16x32_bf16 v[72:75], v[194:197], v[242:245], v[72:75]
	s_barrier
	s_add_i32 m0, s29, 0x18000
	s_add_u32 s4, s4, 0x80
	s_addc_u32 s5, s5, 0
	ds_read_b128 v[198:201], v165 offset:49152
	ds_read_b128 v[202:205], v165 offset:50176
	ds_read_b128 v[206:209], v165 offset:51200
	ds_read_b128 v[210:213], v165 offset:52224
	ds_read_b128 v[214:217], v165 offset:53248
	ds_read_b128 v[234:237], v165 offset:54272
	ds_read_b128 v[238:241], v165 offset:55296
	ds_read_b128 v[242:245], v165 offset:56320
	global_load_lds_dwordx4 v176, s[4:5]
	s_add_i32 m0, s29, 0x1a000
	s_add_u32 s64, s4, 0x40000
	s_addc_u32 s65, s5, 0
	global_load_lds_dwordx4 v140, s[4:5]
	s_add_i32 m0, s29, 0x1c000
	s_add_u32 s34, s34, 0xfffc0080
	s_addc_u32 s35, s35, -1
	global_load_lds_dwordx4 v176, s[64:65]
	s_add_i32 m0, s29, 0x1e000
	s_nop 0
	global_load_lds_dwordx4 v140, s[64:65]
	s_mov_b32 m0, s55
	s_nop 0
	global_load_lds_dwordx4 v136, s[34:35]
	s_mov_b32 m0, s56
	s_nop 0
	global_load_lds_dwordx4 v138, s[34:35]
	s_waitcnt vmcnt(8)
	s_waitcnt lgkmcnt(0)
	s_setprio 1
	s_barrier
	v_mfma_f32_16x16x32_bf16 v[68:71], v[64:67], v[198:201], v[68:71]
	v_mfma_f32_16x16x32_bf16 v[52:55], v[152:155], v[198:201], v[52:55]
	v_mfma_f32_16x16x32_bf16 v[44:47], v[64:67], v[206:209], v[44:47]
	v_mfma_f32_16x16x32_bf16 v[36:39], v[152:155], v[206:209], v[36:39]
	v_mfma_f32_16x16x32_bf16 v[28:31], v[64:67], v[214:217], v[28:31]
	v_mfma_f32_16x16x32_bf16 v[20:23], v[152:155], v[214:217], v[20:23]
	v_mfma_f32_16x16x32_bf16 v[12:15], v[64:67], v[238:241], v[12:15]
	v_mfma_f32_16x16x32_bf16 v[4:7], v[152:155], v[238:241], v[4:7]
	v_mfma_f32_16x16x32_bf16 v[68:71], v[148:151], v[202:205], v[68:71]
	v_mfma_f32_16x16x32_bf16 v[52:55], v[166:169], v[202:205], v[52:55]
	v_mfma_f32_16x16x32_bf16 v[44:47], v[148:151], v[210:213], v[44:47]
	v_mfma_f32_16x16x32_bf16 v[36:39], v[166:169], v[210:213], v[36:39]
	v_mfma_f32_16x16x32_bf16 v[28:31], v[148:151], v[234:237], v[28:31]
	v_mfma_f32_16x16x32_bf16 v[20:23], v[166:169], v[234:237], v[20:23]
	v_mfma_f32_16x16x32_bf16 v[12:15], v[148:151], v[242:245], v[12:15]
	v_mfma_f32_16x16x32_bf16 v[4:7], v[166:169], v[242:245], v[4:7]
	s_setprio 0
	s_setprio 1
	v_mfma_f32_16x16x32_bf16 v[60:63], v[170:173], v[198:201], v[60:63]
	v_mfma_f32_16x16x32_bf16 v[48:51], v[190:193], v[198:201], v[48:51]
	v_mfma_f32_16x16x32_bf16 v[40:43], v[170:173], v[206:209], v[40:43]
	v_mfma_f32_16x16x32_bf16 v[32:35], v[190:193], v[206:209], v[32:35]
	v_mfma_f32_16x16x32_bf16 v[24:27], v[170:173], v[214:217], v[24:27]
	v_mfma_f32_16x16x32_bf16 v[16:19], v[190:193], v[214:217], v[16:19]
	v_mfma_f32_16x16x32_bf16 v[8:11], v[170:173], v[238:241], v[8:11]
	v_mfma_f32_16x16x32_bf16 v[0:3], v[190:193], v[238:241], v[0:3]
	v_mfma_f32_16x16x32_bf16 v[64:67], v[186:189], v[202:205], v[60:63]
	v_mfma_f32_16x16x32_bf16 v[48:51], v[194:197], v[202:205], v[48:51]
	v_mfma_f32_16x16x32_bf16 v[40:43], v[186:189], v[210:213], v[40:43]
	v_mfma_f32_16x16x32_bf16 v[32:35], v[194:197], v[210:213], v[32:35]
	v_mfma_f32_16x16x32_bf16 v[24:27], v[186:189], v[234:237], v[24:27]
	v_mfma_f32_16x16x32_bf16 v[16:19], v[194:197], v[234:237], v[16:19]
	v_mfma_f32_16x16x32_bf16 v[8:11], v[186:189], v[242:245], v[8:11]
	s_setprio 0
	v_mfma_f32_16x16x32_bf16 v[0:3], v[194:197], v[242:245], v[0:3]
	s_barrier
	s_add_i32 s63, s63, 2
	s_add_u32 s50, s50, 0x100
	s_addc_u32 s51, s51, 0
	s_cmp_gt_u32 s63, 13
	s_cbranch_scc0 .LBB0_236
